# EpiRes epilogues: store/atomic-ack vmcnt waits removed from shared path (x0 path waits moved into its own blocks)
# speedup vs baseline: 1.0067x; 1.0067x over previous
;     __device__ __forceinline__ void operator()(const f32x4 (&acc)[2][2][4][2], const Unit& u, int wr, int wc, int fr, int fq) const {
;     ...
;             for (int m = 0; m < 4; ++m) {
;                 const int row = row0 + ai * HALF + m * 16; const size_t off = (size_t)row * 1024 + col0;
;                 float s1 = 0.f, s2 = 0.f;
; #pragma unroll
;                 for (int bj = 0; bj < 2; ++bj) {
;                     f32x4 yp[2];
;                     if (st) { const f16x8 h = hv[m][bj]; yp[0] = (f32x4){(float)h[0], (float)h[1], (float)h[2], (float)h[3]}; yp[1] = (f32x4){(float)h[4], (float)h[5], (float)h[6], (float)h[7]}; }
;                     else { yp[0] = *(const f32x4*)(x0 + off + bj * 32); yp[1] = *(const f32x4*)(x0 + off + bj * 32 + 4); }
;                     f32x4 y[2];
; #pragma unroll
;                     for (int n = 0; n < 2; ++n) { const f32x4 x = (yp[n] - rmu[m]) * ra[m] * gv[bj][n] + bv[bj][n];
;                         y[n] = x * alpha + acc[ai][bj][m][n] * s;
;                         s1 += (y[n][0] + y[n][1]) + (y[n][2] + y[n][3]); s2 += (y[n][0] * y[n][0] + y[n][1] * y[n][1]) + (y[n][2] * y[n][2] + y[n][3] * y[n][3]); }
;                     u32x4 w; w.x = cvtpk_h(y[0][0], y[0][1]); w.y = cvtpk_h(y[0][2], y[0][3]); w.z = cvtpk_h(y[1][0], y[1][1]); w.w = cvtpk_h(y[1][2], y[1][3]);
;                     *(u32x4*)(yh + off + bj * 32) = w;
;                 }
;                 s1 += __shfl_xor(s1, 16); s1 += __shfl_xor(s1, 32); s2 += __shfl_xor(s2, 16); s2 += __shfl_xor(s2, 32);
;                 if (fq == 0) { atomicAdd(st_new + 2 * (size_t)row, s1); atomicAdd(st_new + 2 * (size_t)row + 1, s2); }
.LBB0_440:
	v_lshlrev_b64 v[208:209], 10, v[228:229]
	v_lshl_add_u64 v[250:251], v[208:209], 0, v[224:225]
	s_andn2_b64 vcc, exec, s[36:37]
	v_lshl_add_u64 v[246:247], v[250:251], 2, s[68:69]
	s_cbranch_vccnz .LBB0_442
	global_load_dwordx4 v[202:205], v[246:247], off
	global_load_dwordx4 v[198:201], v[246:247], off offset:16
	s_waitcnt vmcnt(0)
.LBB0_442:
	v_mov_b32_e32 v243, v244
	s_nop 0
	v_sub_f32_e32 v205, v205, v178
	v_sub_f32_e32 v204, v204, v178
	v_sub_f32_e32 v203, v203, v178
	v_sub_f32_e32 v202, v202, v178
	v_pk_mul_f32 v[202:203], v[242:243], v[202:203] op_sel_hi:[0,1]
	v_pk_mul_f32 v[204:205], v[242:243], v[204:205] op_sel_hi:[0,1]
	v_pk_fma_f32 v[204:205], v[76:77], v[204:205], v[80:81]
	v_pk_fma_f32 v[202:203], v[74:75], v[202:203], v[78:79]
	v_mov_b32_e32 v238, v237
	v_pk_mul_f32 v[208:209], v[202:203], s[66:67] op_sel_hi:[1,0]
	v_pk_mul_f32 v[202:203], v[204:205], s[66:67] op_sel_hi:[1,0]
	v_pk_fma_f32 v[204:205], v[194:195], 0.5, v[208:209] op_sel_hi:[1,0,1]
	v_pk_fma_f32 v[202:203], v[196:197], 0.5, v[202:203] op_sel_hi:[1,0,1]
	v_sub_f32_e32 v195, v201, v178
	v_sub_f32_e32 v194, v200, v178
	v_sub_f32_e32 v197, v199, v178
	v_sub_f32_e32 v196, v198, v178
	v_pk_mul_f32 v[196:197], v[242:243], v[196:197] op_sel_hi:[0,1]
	v_pk_mul_f32 v[194:195], v[242:243], v[194:195] op_sel_hi:[0,1]
	v_pk_fma_f32 v[194:195], v[68:69], v[194:195], v[72:73]
	v_pk_fma_f32 v[196:197], v[66:67], v[196:197], v[70:71]
	v_pk_mul_f32 v[194:195], v[194:195], s[66:67] op_sel_hi:[1,0]
	v_pk_mul_f32 v[196:197], v[196:197], s[66:67] op_sel_hi:[1,0]
	v_pk_fma_f32 v[200:201], v[192:193], 0.5, v[194:195] op_sel_hi:[1,0,1]
	v_pk_fma_f32 v[248:249], v[190:191], 0.5, v[196:197] op_sel_hi:[1,0,1]
	v_cvt_pk_f16_f32 v190, v204, v205
	v_cvt_pk_f16_f32 v191, v202, v203
	v_cvt_pk_f16_f32 v192, v248, v249
	v_cvt_pk_f16_f32 v193, v200, v201
	v_lshl_add_u64 v[198:199], v[250:251], 1, s[92:93]
	s_and_b64 vcc, exec, s[38:39]
	s_mov_b64 s[36:37], -1
	global_store_dwordx4 v[198:199], v[190:193], off
	s_cbranch_vccnz .LBB0_444
	v_cvt_f32_f16_sdwa v195, v146 dst_sel:DWORD dst_unused:UNUSED_PAD src0_sel:WORD_1
	v_cvt_f32_f16_e32 v194, v146
	v_cvt_f32_f16_sdwa v197, v147 dst_sel:DWORD dst_unused:UNUSED_PAD src0_sel:WORD_1
	v_cvt_f32_f16_e32 v196, v147
	v_cvt_f32_f16_sdwa v191, v148 dst_sel:DWORD dst_unused:UNUSED_PAD src0_sel:WORD_1
	v_cvt_f32_f16_e32 v190, v148
	v_cvt_f32_f16_sdwa v193, v149 dst_sel:DWORD dst_unused:UNUSED_PAD src0_sel:WORD_1
	v_cvt_f32_f16_e32 v192, v149
	s_mov_b64 s[36:37], 0
.LBB0_444:
	s_andn2_b64 vcc, exec, s[36:37]
	s_cbranch_vccnz .LBB0_446
	global_load_dwordx4 v[194:197], v[246:247], off offset:128
	global_load_dwordx4 v[190:193], v[246:247], off offset:144
	s_waitcnt vmcnt(0)
.LBB0_446:
	v_add_f32_e32 v207, v204, v205
	v_add_f32_e32 v208, v202, v203
	v_mul_f32_e32 v205, v205, v205
	v_mul_f32_e32 v203, v203, v203
	v_fmac_f32_e32 v205, v204, v204
	v_fmac_f32_e32 v203, v202, v202
	v_add_f32_e32 v202, v205, v203
	v_add_f32_e32 v203, v248, v249
	v_add_f32_e32 v204, v200, v201
	v_add_f32_e32 v203, v203, v204
	v_mul_f32_e32 v204, v249, v249
	v_mul_f32_e32 v201, v201, v201
	v_fmac_f32_e32 v204, v248, v248
	v_fmac_f32_e32 v201, v200, v200
	v_add_f32_e32 v200, v204, v201
	v_and_b32_e32 v201, 64, v252
	v_add_f32_e32 v202, v202, v200
	v_xor_b32_e32 v200, 16, v252
	v_add_u32_e32 v209, 64, v201
	v_add_f32_e32 v207, v207, v208
	v_cmp_lt_i32_e32 vcc, v200, v209
	v_add_f32_e32 v207, 0, v207
	v_add_f32_e32 v203, v203, v207
	v_cndmask_b32_e32 v200, v252, v200, vcc
	v_lshlrev_b32_e32 v207, 2, v200
	v_xor_b32_e32 v200, 32, v252
	v_cmp_lt_i32_e32 vcc, v200, v209
	v_mov_b32_e32 v246, v242
	v_mov_b32_e32 v247, v242
	v_cndmask_b32_e32 v204, v252, v200, vcc
	s_nop 0
	v_sub_f32_e32 v197, v197, v178
	v_sub_f32_e32 v196, v196, v178
	v_sub_f32_e32 v195, v195, v178
	v_sub_f32_e32 v194, v194, v178
	v_mov_b32_e32 v200, v242
	v_mov_b32_e32 v201, v242
	v_pk_mul_f32 v[194:195], v[246:247], v[194:195]
	v_pk_mul_f32 v[196:197], v[200:201], v[196:197]
	s_nop 0
	v_sub_f32_e32 v193, v193, v178
	v_sub_f32_e32 v192, v192, v178
	v_sub_f32_e32 v191, v191, v178
	v_sub_f32_e32 v190, v190, v178
	v_pk_fma_f32 v[196:197], v[56:57], v[196:197], v[60:61]
	v_pk_fma_f32 v[194:195], v[54:55], v[194:195], v[58:59]
	v_pk_mul_f32 v[190:191], v[246:247], v[190:191]
	v_pk_mul_f32 v[192:193], v[200:201], v[192:193]
	v_pk_mul_f32 v[194:195], v[194:195], s[66:67] op_sel_hi:[1,0]
	v_pk_mul_f32 v[196:197], v[196:197], s[66:67] op_sel_hi:[1,0]
	v_pk_fma_f32 v[192:193], v[44:45], v[192:193], v[48:49]
	v_pk_fma_f32 v[190:191], v[42:43], v[190:191], v[46:47]
	v_pk_fma_f32 v[188:189], v[188:189], 0.5, v[196:197] op_sel_hi:[1,0,1]
	v_pk_fma_f32 v[186:187], v[186:187], 0.5, v[194:195] op_sel_hi:[1,0,1]
	v_pk_mul_f32 v[190:191], v[190:191], s[66:67] op_sel_hi:[1,0]
	v_pk_mul_f32 v[192:193], v[192:193], s[66:67] op_sel_hi:[1,0]
	v_add_f32_e32 v194, v186, v187
	v_add_f32_e32 v195, v188, v189
	v_pk_fma_f32 v[192:193], v[184:185], 0.5, v[192:193] op_sel_hi:[1,0,1]
	v_pk_fma_f32 v[190:191], v[182:183], 0.5, v[190:191] op_sel_hi:[1,0,1]
	v_add_f32_e32 v194, v194, v195
	v_mul_f32_e32 v195, v187, v187
	v_mul_f32_e32 v196, v189, v189
	v_add_f32_e32 v178, v190, v191
	v_add_f32_e32 v182, v192, v193
	v_fmac_f32_e32 v195, v186, v186
	v_fmac_f32_e32 v196, v188, v188
	v_add_f32_e32 v178, v178, v182
	v_mul_f32_e32 v182, v191, v191
	v_mul_f32_e32 v183, v193, v193
	v_add_f32_e32 v195, v195, v196
	v_fmac_f32_e32 v182, v190, v190
	v_fmac_f32_e32 v183, v192, v192
	v_add_f32_e32 v194, v203, v194
	v_add_f32_e32 v195, v202, v195
	v_add_f32_e32 v182, v182, v183
	v_add_f32_e32 v178, v178, v194
	v_add_f32_e32 v184, v182, v195
	ds_bpermute_b32 v183, v207, v178
	ds_bpermute_b32 v185, v207, v184
	v_lshlrev_b32_e32 v208, 2, v204
	v_cvt_pk_f16_f32 v186, v186, v187
	v_cvt_pk_f16_f32 v187, v188, v189
	s_waitcnt lgkmcnt(1)
	v_add_f32_e32 v178, v178, v183
	s_waitcnt lgkmcnt(0)
	v_add_f32_e32 v183, v184, v185
	ds_bpermute_b32 v182, v208, v178
	ds_bpermute_b32 v184, v208, v183
	v_cvt_pk_f16_f32 v188, v190, v191
	v_cvt_pk_f16_f32 v189, v192, v193
	global_store_dwordx4 v[198:199], v[186:189], off offset:64
	s_and_saveexec_b64 s[36:37], s[40:41]
	s_cbranch_execz .LBB0_448
	v_lshl_add_u64 v[186:187], v[228:229], 3, s[80:81]
	s_waitcnt lgkmcnt(1)
	v_add_f32_e32 v178, v178, v182
	s_waitcnt lgkmcnt(0)
	v_add_f32_e32 v182, v183, v184
	global_atomic_add_f32 v[186:187], v178, off
	global_atomic_add_f32 v[186:187], v182, off offset:4

;     __device__ __forceinline__ void operator()(const f32x4 (&acc)[2][2][4][2], const Unit& u, int wr, int wc, int fr, int fq) const {
;     ...
;             for (int m = 0; m < 4; ++m) {
;                 const int row = row0 + ai * HALF + m * 16; const size_t off = (size_t)row * 1024 + col0;
;                 float s1 = 0.f, s2 = 0.f;
; #pragma unroll
;                 for (int bj = 0; bj < 2; ++bj) {
;                     f32x4 yp[2];
;                     if (st) { const f16x8 h = hv[m][bj]; yp[0] = (f32x4){(float)h[0], (float)h[1], (float)h[2], (float)h[3]}; yp[1] = (f32x4){(float)h[4], (float)h[5], (float)h[6], (float)h[7]}; }
;                     else { yp[0] = *(const f32x4*)(x0 + off + bj * 32); yp[1] = *(const f32x4*)(x0 + off + bj * 32 + 4); }
;                     f32x4 y[2];
; #pragma unroll
;                     for (int n = 0; n < 2; ++n) { const f32x4 x = (yp[n] - rmu[m]) * ra[m] * gv[bj][n] + bv[bj][n];
;                         y[n] = x * alpha + acc[ai][bj][m][n] * s;
;                         s1 += (y[n][0] + y[n][1]) + (y[n][2] + y[n][3]); s2 += (y[n][0] * y[n][0] + y[n][1] * y[n][1]) + (y[n][2] * y[n][2] + y[n][3] * y[n][3]); }
;                     u32x4 w; w.x = cvtpk_h(y[0][0], y[0][1]); w.y = cvtpk_h(y[0][2], y[0][3]); w.z = cvtpk_h(y[1][0], y[1][1]); w.w = cvtpk_h(y[1][2], y[1][3]);
;                     *(u32x4*)(yh + off + bj * 32) = w;
;                 }
;                 s1 += __shfl_xor(s1, 16); s1 += __shfl_xor(s1, 32); s2 += __shfl_xor(s2, 16); s2 += __shfl_xor(s2, 32);
;                 if (fq == 0) { atomicAdd(st_new + 2 * (size_t)row, s1); atomicAdd(st_new + 2 * (size_t)row + 1, s2); }
.LBB0_450:
	v_lshlrev_b64 v[190:191], 10, v[240:241]
	v_lshl_add_u64 v[194:195], v[190:191], 0, v[224:225]
	s_andn2_b64 vcc, exec, s[36:37]
	v_lshl_add_u64 v[190:191], v[194:195], 2, s[68:69]
	s_cbranch_vccnz .LBB0_452
	global_load_dwordx4 v[186:189], v[190:191], off
	s_waitcnt lgkmcnt(0)
	global_load_dwordx4 v[182:185], v[190:191], off offset:16
	s_waitcnt vmcnt(0)
.LBB0_452:
	s_nop 0
	v_sub_f32_e32 v189, v189, v179
	v_sub_f32_e32 v188, v188, v179
	v_sub_f32_e32 v187, v187, v179
	v_sub_f32_e32 v186, v186, v179
	v_pk_mul_f32 v[186:187], v[242:243], v[186:187] op_sel:[1,0]
	v_pk_mul_f32 v[188:189], v[242:243], v[188:189] op_sel:[1,0]
	v_pk_fma_f32 v[186:187], v[74:75], v[186:187], v[78:79]
	v_pk_fma_f32 v[188:189], v[76:77], v[188:189], v[80:81]
	v_pk_mul_f32 v[192:193], v[186:187], s[66:67] op_sel_hi:[1,0]
	v_pk_mul_f32 v[186:187], v[188:189], s[66:67] op_sel_hi:[1,0]
	v_pk_fma_f32 v[188:189], v[174:175], 0.5, v[192:193] op_sel_hi:[1,0,1]
	v_pk_fma_f32 v[186:187], v[176:177], 0.5, v[186:187] op_sel_hi:[1,0,1]
	s_nop 0
	v_sub_f32_e32 v175, v185, v179
	s_waitcnt lgkmcnt(0)
	v_sub_f32_e32 v174, v184, v179
	v_sub_f32_e32 v177, v183, v179
	v_sub_f32_e32 v176, v182, v179
	v_pk_mul_f32 v[176:177], v[242:243], v[176:177] op_sel:[1,0]
	v_pk_mul_f32 v[174:175], v[242:243], v[174:175] op_sel:[1,0]
	v_pk_fma_f32 v[176:177], v[66:67], v[176:177], v[70:71]
	v_pk_fma_f32 v[174:175], v[68:69], v[174:175], v[72:73]
	v_pk_mul_f32 v[176:177], v[176:177], s[66:67] op_sel_hi:[1,0]
	v_pk_mul_f32 v[174:175], v[174:175], s[66:67] op_sel_hi:[1,0]
	v_pk_fma_f32 v[192:193], v[170:171], 0.5, v[176:177] op_sel_hi:[1,0,1]
	v_pk_fma_f32 v[184:185], v[172:173], 0.5, v[174:175] op_sel_hi:[1,0,1]
	v_cvt_pk_f16_f32 v170, v188, v189
	v_cvt_pk_f16_f32 v171, v186, v187
	v_cvt_pk_f16_f32 v172, v192, v193
	v_cvt_pk_f16_f32 v173, v184, v185
	v_lshl_add_u64 v[182:183], v[194:195], 1, s[92:93]
	s_and_b64 vcc, exec, s[38:39]
	s_mov_b64 s[36:37], -1
	global_store_dwordx4 v[182:183], v[170:173], off
	s_cbranch_vccnz .LBB0_454
	v_cvt_f32_f16_sdwa v175, v130 dst_sel:DWORD dst_unused:UNUSED_PAD src0_sel:WORD_1
	v_cvt_f32_f16_e32 v174, v130
	v_cvt_f32_f16_sdwa v177, v131 dst_sel:DWORD dst_unused:UNUSED_PAD src0_sel:WORD_1
	v_cvt_f32_f16_e32 v176, v131
	v_cvt_f32_f16_sdwa v171, v132 dst_sel:DWORD dst_unused:UNUSED_PAD src0_sel:WORD_1
	v_cvt_f32_f16_e32 v170, v132
	v_cvt_f32_f16_sdwa v173, v133 dst_sel:DWORD dst_unused:UNUSED_PAD src0_sel:WORD_1
	v_cvt_f32_f16_e32 v172, v133
	s_mov_b64 s[36:37], 0
.LBB0_454:
	s_andn2_b64 vcc, exec, s[36:37]
	s_cbranch_vccnz .LBB0_456
	global_load_dwordx4 v[174:177], v[190:191], off offset:128
	global_load_dwordx4 v[170:173], v[190:191], off offset:144
	s_waitcnt vmcnt(0)
.LBB0_456:
	v_mov_b32_e32 v245, v243
	s_nop 0
	v_sub_f32_e32 v177, v177, v179
	v_sub_f32_e32 v176, v176, v179
	v_sub_f32_e32 v175, v175, v179
	v_sub_f32_e32 v174, v174, v179
	v_mov_b32_e32 v242, v244
	v_add_f32_e32 v178, v188, v189
	v_add_f32_e32 v190, v186, v187
	v_mul_f32_e32 v189, v189, v189
	v_mul_f32_e32 v187, v187, v187
	v_pk_mul_f32 v[174:175], v[244:245], v[174:175]
	v_pk_mul_f32 v[176:177], v[242:243], v[176:177]
	s_nop 0
	v_sub_f32_e32 v173, v173, v179
	v_sub_f32_e32 v172, v172, v179
	v_sub_f32_e32 v171, v171, v179
	v_sub_f32_e32 v170, v170, v179
	v_fmac_f32_e32 v189, v188, v188
	v_fmac_f32_e32 v187, v186, v186
	v_pk_fma_f32 v[176:177], v[56:57], v[176:177], v[60:61]
	v_pk_fma_f32 v[174:175], v[54:55], v[174:175], v[58:59]
	v_pk_mul_f32 v[170:171], v[244:245], v[170:171]
	v_pk_mul_f32 v[172:173], v[242:243], v[172:173]
	v_add_f32_e32 v178, v178, v190
	v_add_f32_e32 v186, v189, v187
	v_add_f32_e32 v187, v192, v193
	v_add_f32_e32 v188, v184, v185
	v_pk_mul_f32 v[174:175], v[174:175], s[66:67] op_sel_hi:[1,0]
	v_pk_mul_f32 v[176:177], v[176:177], s[66:67] op_sel_hi:[1,0]
	v_pk_fma_f32 v[172:173], v[44:45], v[172:173], v[48:49]
	v_pk_fma_f32 v[170:171], v[42:43], v[170:171], v[46:47]
	v_add_f32_e32 v178, 0, v178
	v_add_f32_e32 v187, v187, v188
	v_pk_fma_f32 v[168:169], v[168:169], 0.5, v[176:177] op_sel_hi:[1,0,1]
	v_pk_fma_f32 v[166:167], v[166:167], 0.5, v[174:175] op_sel_hi:[1,0,1]
	v_pk_mul_f32 v[170:171], v[170:171], s[66:67] op_sel_hi:[1,0]
	v_pk_mul_f32 v[172:173], v[172:173], s[66:67] op_sel_hi:[1,0]
	v_add_f32_e32 v178, v187, v178
	v_mul_f32_e32 v187, v193, v193
	v_mul_f32_e32 v185, v185, v185
	v_add_f32_e32 v174, v166, v167
	v_add_f32_e32 v175, v168, v169
	v_pk_fma_f32 v[172:173], v[164:165], 0.5, v[172:173] op_sel_hi:[1,0,1]
	v_pk_fma_f32 v[170:171], v[162:163], 0.5, v[170:171] op_sel_hi:[1,0,1]
	v_fmac_f32_e32 v187, v192, v192
	v_fmac_f32_e32 v185, v184, v184
	v_add_f32_e32 v174, v174, v175
	v_mul_f32_e32 v175, v167, v167
	v_mul_f32_e32 v176, v169, v169
	v_add_f32_e32 v162, v170, v171
	v_add_f32_e32 v163, v172, v173
	v_add_f32_e32 v184, v187, v185
	v_fmac_f32_e32 v175, v166, v166
	v_fmac_f32_e32 v176, v168, v168
	v_add_f32_e32 v162, v162, v163
	v_mul_f32_e32 v163, v171, v171
	v_mul_f32_e32 v164, v173, v173
	v_add_f32_e32 v184, v186, v184
	v_add_f32_e32 v175, v175, v176
	v_fmac_f32_e32 v163, v170, v170
	v_fmac_f32_e32 v164, v172, v172
	v_add_f32_e32 v174, v178, v174
	v_add_f32_e32 v175, v184, v175
	v_add_f32_e32 v163, v163, v164
	v_add_f32_e32 v162, v162, v174
	v_add_f32_e32 v165, v163, v175
	ds_bpermute_b32 v164, v207, v162
	ds_bpermute_b32 v174, v207, v165
	v_cvt_pk_f16_f32 v166, v166, v167
	v_cvt_pk_f16_f32 v167, v168, v169
	v_cvt_pk_f16_f32 v168, v170, v171
	s_waitcnt lgkmcnt(1)
	v_add_f32_e32 v162, v162, v164
	s_waitcnt lgkmcnt(0)
	v_add_f32_e32 v164, v165, v174
	ds_bpermute_b32 v163, v208, v162
	ds_bpermute_b32 v165, v208, v164
	v_cvt_pk_f16_f32 v169, v172, v173
	global_store_dwordx4 v[182:183], v[166:169], off offset:64
	s_and_saveexec_b64 s[36:37], s[40:41]
	s_cbranch_execz .LBB0_458
	v_lshl_add_u64 v[166:167], v[240:241], 3, s[80:81]
	s_waitcnt lgkmcnt(1)
	v_add_f32_e32 v162, v162, v163
	s_waitcnt lgkmcnt(0)
	v_add_f32_e32 v163, v164, v165
	global_atomic_add_f32 v[166:167], v162, off
	global_atomic_add_f32 v[166:167], v163, off offset:4

;     __device__ __forceinline__ void operator()(const f32x4 (&acc)[2][2][4][2], const Unit& u, int wr, int wc, int fr, int fq) const {
;     ...
;             for (int m = 0; m < 4; ++m) {
;                 const int row = row0 + ai * HALF + m * 16; const size_t off = (size_t)row * 1024 + col0;
;                 float s1 = 0.f, s2 = 0.f;
; #pragma unroll
;                 for (int bj = 0; bj < 2; ++bj) {
;                     f32x4 yp[2];
;                     if (st) { const f16x8 h = hv[m][bj]; yp[0] = (f32x4){(float)h[0], (float)h[1], (float)h[2], (float)h[3]}; yp[1] = (f32x4){(float)h[4], (float)h[5], (float)h[6], (float)h[7]}; }
;                     else { yp[0] = *(const f32x4*)(x0 + off + bj * 32); yp[1] = *(const f32x4*)(x0 + off + bj * 32 + 4); }
;                     f32x4 y[2];
; #pragma unroll
;                     for (int n = 0; n < 2; ++n) { const f32x4 x = (yp[n] - rmu[m]) * ra[m] * gv[bj][n] + bv[bj][n];
;                         y[n] = x * alpha + acc[ai][bj][m][n] * s;
;                         s1 += (y[n][0] + y[n][1]) + (y[n][2] + y[n][3]); s2 += (y[n][0] * y[n][0] + y[n][1] * y[n][1]) + (y[n][2] * y[n][2] + y[n][3] * y[n][3]); }
;                     u32x4 w; w.x = cvtpk_h(y[0][0], y[0][1]); w.y = cvtpk_h(y[0][2], y[0][3]); w.z = cvtpk_h(y[1][0], y[1][1]); w.w = cvtpk_h(y[1][2], y[1][3]);
;                     *(u32x4*)(yh + off + bj * 32) = w;
;                 }
;                 s1 += __shfl_xor(s1, 16); s1 += __shfl_xor(s1, 32); s2 += __shfl_xor(s2, 16); s2 += __shfl_xor(s2, 32);
;                 if (fq == 0) { atomicAdd(st_new + 2 * (size_t)row, s1); atomicAdd(st_new + 2 * (size_t)row + 1, s2); }
.LBB0_460:
	v_lshlrev_b64 v[170:171], 10, v[234:235]
	v_lshl_add_u64 v[174:175], v[170:171], 0, v[224:225]
	s_andn2_b64 vcc, exec, s[36:37]
	v_lshl_add_u64 v[170:171], v[174:175], 2, s[68:69]
	s_cbranch_vccnz .LBB0_462
	global_load_dwordx4 v[166:169], v[170:171], off
	s_waitcnt lgkmcnt(0)
	global_load_dwordx4 v[162:165], v[170:171], off offset:16
	s_waitcnt vmcnt(0)
.LBB0_462:
	s_nop 0
	v_sub_f32_e32 v169, v169, v180
	v_sub_f32_e32 v168, v168, v180
	v_sub_f32_e32 v167, v167, v180
	v_sub_f32_e32 v166, v166, v180
	v_pk_mul_f32 v[166:167], v[238:239], v[166:167] op_sel_hi:[0,1]
	v_pk_mul_f32 v[168:169], v[238:239], v[168:169] op_sel_hi:[0,1]
	v_pk_fma_f32 v[168:169], v[76:77], v[168:169], v[80:81]
	v_pk_fma_f32 v[166:167], v[74:75], v[166:167], v[78:79]
	s_and_b64 vcc, exec, s[38:39]
	v_pk_mul_f32 v[172:173], v[166:167], s[66:67] op_sel_hi:[1,0]
	v_pk_mul_f32 v[166:167], v[168:169], s[66:67] op_sel_hi:[1,0]
	v_pk_fma_f32 v[168:169], v[154:155], 0.5, v[172:173] op_sel_hi:[1,0,1]
	v_pk_fma_f32 v[166:167], v[156:157], 0.5, v[166:167] op_sel_hi:[1,0,1]
	s_waitcnt lgkmcnt(0)
	v_sub_f32_e32 v155, v165, v180
	v_sub_f32_e32 v154, v164, v180
	v_sub_f32_e32 v157, v163, v180
	v_sub_f32_e32 v156, v162, v180
	v_pk_mul_f32 v[156:157], v[238:239], v[156:157] op_sel_hi:[0,1]
	v_pk_mul_f32 v[154:155], v[238:239], v[154:155] op_sel_hi:[0,1]
	v_pk_fma_f32 v[154:155], v[68:69], v[154:155], v[72:73]
	v_pk_fma_f32 v[156:157], v[66:67], v[156:157], v[70:71]
	v_pk_mul_f32 v[154:155], v[154:155], s[66:67] op_sel_hi:[1,0]
	v_pk_mul_f32 v[156:157], v[156:157], s[66:67] op_sel_hi:[1,0]
	v_pk_fma_f32 v[164:165], v[152:153], 0.5, v[154:155] op_sel_hi:[1,0,1]
	v_pk_fma_f32 v[172:173], v[150:151], 0.5, v[156:157] op_sel_hi:[1,0,1]
	v_cvt_pk_f16_f32 v150, v168, v169
	v_cvt_pk_f16_f32 v151, v166, v167
	v_cvt_pk_f16_f32 v152, v172, v173
	v_cvt_pk_f16_f32 v153, v164, v165
	v_lshl_add_u64 v[162:163], v[174:175], 1, s[92:93]
	s_mov_b64 s[36:37], -1
	global_store_dwordx4 v[162:163], v[150:153], off
	s_cbranch_vccnz .LBB0_464
	v_cvt_f32_f16_sdwa v155, v106 dst_sel:DWORD dst_unused:UNUSED_PAD src0_sel:WORD_1
	v_cvt_f32_f16_e32 v154, v106
	v_cvt_f32_f16_sdwa v157, v107 dst_sel:DWORD dst_unused:UNUSED_PAD src0_sel:WORD_1
	v_cvt_f32_f16_e32 v156, v107
	v_cvt_f32_f16_sdwa v151, v108 dst_sel:DWORD dst_unused:UNUSED_PAD src0_sel:WORD_1
	v_cvt_f32_f16_e32 v150, v108
	v_cvt_f32_f16_sdwa v153, v109 dst_sel:DWORD dst_unused:UNUSED_PAD src0_sel:WORD_1
	v_cvt_f32_f16_e32 v152, v109
	s_mov_b64 s[36:37], 0
.LBB0_464:
	s_andn2_b64 vcc, exec, s[36:37]
	s_cbranch_vccnz .LBB0_466
	global_load_dwordx4 v[154:157], v[170:171], off offset:128
	global_load_dwordx4 v[150:153], v[170:171], off offset:144
	s_waitcnt vmcnt(0)
.LBB0_466:
	v_mov_b32_e32 v236, v238
	s_nop 0
	v_sub_f32_e32 v157, v157, v180
	v_sub_f32_e32 v156, v156, v180
	v_sub_f32_e32 v155, v155, v180
	v_sub_f32_e32 v154, v154, v180
	v_mov_b32_e32 v239, v237
	v_pk_mul_f32 v[154:155], v[236:237], v[154:155]
	v_pk_mul_f32 v[156:157], v[238:239], v[156:157]
	s_nop 0
	v_sub_f32_e32 v153, v153, v180
	v_sub_f32_e32 v152, v152, v180
	v_sub_f32_e32 v151, v151, v180
	v_sub_f32_e32 v150, v150, v180
	v_add_f32_e32 v170, v168, v169
	v_add_f32_e32 v171, v166, v167
	v_mul_f32_e32 v169, v169, v169
	v_mul_f32_e32 v167, v167, v167
	v_pk_fma_f32 v[156:157], v[56:57], v[156:157], v[60:61]
	v_pk_fma_f32 v[154:155], v[54:55], v[154:155], v[58:59]
	v_pk_mul_f32 v[150:151], v[236:237], v[150:151]
	v_pk_mul_f32 v[152:153], v[238:239], v[152:153]
	v_fmac_f32_e32 v169, v168, v168
	v_fmac_f32_e32 v167, v166, v166
	v_pk_mul_f32 v[154:155], v[154:155], s[66:67] op_sel_hi:[1,0]
	v_pk_mul_f32 v[156:157], v[156:157], s[66:67] op_sel_hi:[1,0]
	v_pk_fma_f32 v[152:153], v[44:45], v[152:153], v[48:49]
	v_pk_fma_f32 v[150:151], v[42:43], v[150:151], v[46:47]
	v_add_f32_e32 v166, v169, v167
	v_add_f32_e32 v167, v172, v173
	v_add_f32_e32 v168, v164, v165
	v_pk_fma_f32 v[144:145], v[144:145], 0.5, v[156:157] op_sel_hi:[1,0,1]
	v_pk_fma_f32 v[142:143], v[142:143], 0.5, v[154:155] op_sel_hi:[1,0,1]
	v_pk_mul_f32 v[150:151], v[150:151], s[66:67] op_sel_hi:[1,0]
	v_pk_mul_f32 v[152:153], v[152:153], s[66:67] op_sel_hi:[1,0]
	v_add_f32_e32 v167, v167, v168
	v_mul_f32_e32 v168, v173, v173
	v_mul_f32_e32 v165, v165, v165
	v_add_f32_e32 v154, v142, v143
	v_add_f32_e32 v155, v144, v145
	v_pk_fma_f32 v[152:153], v[136:137], 0.5, v[152:153] op_sel_hi:[1,0,1]
	v_pk_fma_f32 v[150:151], v[134:135], 0.5, v[150:151] op_sel_hi:[1,0,1]
	v_add_f32_e32 v170, v170, v171
	v_fmac_f32_e32 v168, v172, v172
	v_fmac_f32_e32 v165, v164, v164
	v_add_f32_e32 v154, v154, v155
	v_mul_f32_e32 v155, v143, v143
	v_mul_f32_e32 v156, v145, v145
	v_add_f32_e32 v134, v150, v151
	v_add_f32_e32 v135, v152, v153
	v_add_f32_e32 v170, 0, v170
	v_add_f32_e32 v164, v168, v165
	v_fmac_f32_e32 v155, v142, v142
	v_fmac_f32_e32 v156, v144, v144
	v_add_f32_e32 v134, v134, v135
	v_mul_f32_e32 v135, v151, v151
	v_mul_f32_e32 v136, v153, v153
	v_add_f32_e32 v167, v167, v170
	v_add_f32_e32 v164, v166, v164
	v_add_f32_e32 v155, v155, v156
	v_fmac_f32_e32 v135, v150, v150
	v_fmac_f32_e32 v136, v152, v152
	v_add_f32_e32 v154, v167, v154
	v_add_f32_e32 v155, v164, v155
	v_add_f32_e32 v135, v135, v136
	v_add_f32_e32 v134, v134, v154
	v_add_f32_e32 v137, v135, v155
	ds_bpermute_b32 v136, v207, v134
	ds_bpermute_b32 v154, v207, v137
	v_cvt_pk_f16_f32 v142, v142, v143
	v_cvt_pk_f16_f32 v143, v144, v145
	v_cvt_pk_f16_f32 v144, v150, v151
	s_waitcnt lgkmcnt(1)
	v_add_f32_e32 v134, v134, v136
	s_waitcnt lgkmcnt(0)
	v_add_f32_e32 v136, v137, v154
	ds_bpermute_b32 v135, v208, v134
	ds_bpermute_b32 v137, v208, v136
	v_cvt_pk_f16_f32 v145, v152, v153
	global_store_dwordx4 v[162:163], v[142:145], off offset:64
	s_and_saveexec_b64 s[36:37], s[40:41]
	s_cbranch_execz .LBB0_468
	v_lshl_add_u64 v[142:143], v[234:235], 3, s[80:81]
	s_waitcnt lgkmcnt(1)
	v_add_f32_e32 v134, v134, v135
	s_waitcnt lgkmcnt(0)
	v_add_f32_e32 v135, v136, v137
	global_atomic_add_f32 v[142:143], v134, off
	global_atomic_add_f32 v[142:143], v135, off offset:4

;     __device__ __forceinline__ void operator()(const f32x4 (&acc)[2][2][4][2], const Unit& u, int wr, int wc, int fr, int fq) const {
;     ...
;             for (int m = 0; m < 4; ++m) {
;                 const int row = row0 + ai * HALF + m * 16; const size_t off = (size_t)row * 1024 + col0;
;                 float s1 = 0.f, s2 = 0.f;
; #pragma unroll
;                 for (int bj = 0; bj < 2; ++bj) {
;                     f32x4 yp[2];
;                     if (st) { const f16x8 h = hv[m][bj]; yp[0] = (f32x4){(float)h[0], (float)h[1], (float)h[2], (float)h[3]}; yp[1] = (f32x4){(float)h[4], (float)h[5], (float)h[6], (float)h[7]}; }
;                     else { yp[0] = *(const f32x4*)(x0 + off + bj * 32); yp[1] = *(const f32x4*)(x0 + off + bj * 32 + 4); }
;                     f32x4 y[2];
; #pragma unroll
;                     for (int n = 0; n < 2; ++n) { const f32x4 x = (yp[n] - rmu[m]) * ra[m] * gv[bj][n] + bv[bj][n];
;                         y[n] = x * alpha + acc[ai][bj][m][n] * s;
;                         s1 += (y[n][0] + y[n][1]) + (y[n][2] + y[n][3]); s2 += (y[n][0] * y[n][0] + y[n][1] * y[n][1]) + (y[n][2] * y[n][2] + y[n][3] * y[n][3]); }
;                     u32x4 w; w.x = cvtpk_h(y[0][0], y[0][1]); w.y = cvtpk_h(y[0][2], y[0][3]); w.z = cvtpk_h(y[1][0], y[1][1]); w.w = cvtpk_h(y[1][2], y[1][3]);
;                     *(u32x4*)(yh + off + bj * 32) = w;
;                 }
;                 s1 += __shfl_xor(s1, 16); s1 += __shfl_xor(s1, 32); s2 += __shfl_xor(s2, 16); s2 += __shfl_xor(s2, 32);
;                 if (fq == 0) { atomicAdd(st_new + 2 * (size_t)row, s1); atomicAdd(st_new + 2 * (size_t)row + 1, s2); }
.LBB0_470:
	v_lshlrev_b64 v[150:151], 10, v[230:231]
	v_lshl_add_u64 v[154:155], v[150:151], 0, v[224:225]
	s_andn2_b64 vcc, exec, s[36:37]
	v_lshl_add_u64 v[150:151], v[154:155], 2, s[68:69]
	s_cbranch_vccnz .LBB0_472
	global_load_dwordx4 v[142:145], v[150:151], off
	s_waitcnt lgkmcnt(0)
	global_load_dwordx4 v[134:137], v[150:151], off offset:16
	s_waitcnt vmcnt(0)
.LBB0_472:
	s_nop 0
	v_sub_f32_e32 v145, v145, v181
	v_sub_f32_e32 v144, v144, v181
	v_sub_f32_e32 v143, v143, v181
	v_sub_f32_e32 v142, v142, v181
	v_pk_mul_f32 v[142:143], v[232:233], v[142:143] op_sel_hi:[0,1]
	v_pk_mul_f32 v[144:145], v[232:233], v[144:145] op_sel_hi:[0,1]
	v_pk_fma_f32 v[144:145], v[76:77], v[144:145], v[80:81]
	v_pk_fma_f32 v[142:143], v[74:75], v[142:143], v[78:79]
	s_and_b64 vcc, exec, s[38:39]
	v_pk_mul_f32 v[152:153], v[142:143], s[66:67] op_sel_hi:[1,0]
	v_pk_mul_f32 v[142:143], v[144:145], s[66:67] op_sel_hi:[1,0]
	v_pk_fma_f32 v[144:145], v[126:127], 0.5, v[152:153] op_sel_hi:[1,0,1]
	v_pk_fma_f32 v[142:143], v[128:129], 0.5, v[142:143] op_sel_hi:[1,0,1]
	s_waitcnt lgkmcnt(0)
	v_sub_f32_e32 v127, v137, v181
	v_sub_f32_e32 v126, v136, v181
	v_sub_f32_e32 v129, v135, v181
	v_sub_f32_e32 v128, v134, v181
	v_pk_mul_f32 v[128:129], v[232:233], v[128:129] op_sel_hi:[0,1]
	v_pk_mul_f32 v[126:127], v[232:233], v[126:127] op_sel_hi:[0,1]
	v_pk_fma_f32 v[126:127], v[68:69], v[126:127], v[72:73]
	v_pk_fma_f32 v[128:129], v[66:67], v[128:129], v[70:71]
	v_pk_mul_f32 v[126:127], v[126:127], s[66:67] op_sel_hi:[1,0]
	v_pk_mul_f32 v[128:129], v[128:129], s[66:67] op_sel_hi:[1,0]
	v_pk_fma_f32 v[136:137], v[124:125], 0.5, v[126:127] op_sel_hi:[1,0,1]
	v_pk_fma_f32 v[152:153], v[122:123], 0.5, v[128:129] op_sel_hi:[1,0,1]
	v_cvt_pk_f16_f32 v122, v144, v145
	v_cvt_pk_f16_f32 v123, v142, v143
	v_cvt_pk_f16_f32 v124, v152, v153
	v_cvt_pk_f16_f32 v125, v136, v137
	v_lshl_add_u64 v[134:135], v[154:155], 1, s[92:93]
	s_mov_b64 s[36:37], -1
	global_store_dwordx4 v[134:135], v[122:125], off
	s_cbranch_vccnz .LBB0_474
	v_cvt_f32_f16_sdwa v127, v98 dst_sel:DWORD dst_unused:UNUSED_PAD src0_sel:WORD_1
	v_cvt_f32_f16_e32 v126, v98
	v_cvt_f32_f16_sdwa v129, v99 dst_sel:DWORD dst_unused:UNUSED_PAD src0_sel:WORD_1
	v_cvt_f32_f16_e32 v128, v99
	v_cvt_f32_f16_sdwa v123, v100 dst_sel:DWORD dst_unused:UNUSED_PAD src0_sel:WORD_1
	v_cvt_f32_f16_e32 v122, v100
	v_cvt_f32_f16_sdwa v125, v101 dst_sel:DWORD dst_unused:UNUSED_PAD src0_sel:WORD_1
	v_cvt_f32_f16_e32 v124, v101
	s_mov_b64 s[36:37], 0
.LBB0_474:
	s_andn2_b64 vcc, exec, s[36:37]
	s_cbranch_vccnz .LBB0_476
	global_load_dwordx4 v[126:129], v[150:151], off offset:128
	global_load_dwordx4 v[122:125], v[150:151], off offset:144
	s_waitcnt vmcnt(0)
.LBB0_476:
	v_add_f32_e32 v150, v144, v145
	v_add_f32_e32 v151, v142, v143
	v_mul_f32_e32 v145, v145, v145
	v_mul_f32_e32 v143, v143, v143
	v_fmac_f32_e32 v145, v144, v144
	v_fmac_f32_e32 v143, v142, v142
	v_add_f32_e32 v142, v145, v143
	v_add_f32_e32 v143, v152, v153
	v_add_f32_e32 v144, v136, v137
	v_add_f32_e32 v143, v143, v144
	v_mul_f32_e32 v144, v153, v153
	v_mul_f32_e32 v137, v137, v137
	v_fmac_f32_e32 v144, v152, v152
	v_fmac_f32_e32 v137, v136, v136
	v_add_f32_e32 v136, v144, v137
	v_mov_b32_e32 v233, v232
	v_add_f32_e32 v142, v142, v136
	s_nop 0
	v_sub_f32_e32 v129, v129, v181
	v_sub_f32_e32 v128, v128, v181
	v_sub_f32_e32 v127, v127, v181
	v_sub_f32_e32 v126, v126, v181
	v_mov_b32_e32 v136, v232
	v_mov_b32_e32 v137, v232
	v_pk_mul_f32 v[126:127], v[232:233], v[126:127]
	v_pk_mul_f32 v[128:129], v[136:137], v[128:129]
	s_nop 0
	v_sub_f32_e32 v125, v125, v181
	v_sub_f32_e32 v124, v124, v181
	v_sub_f32_e32 v123, v123, v181
	v_sub_f32_e32 v122, v122, v181
	v_pk_fma_f32 v[128:129], v[56:57], v[128:129], v[60:61]
	v_pk_fma_f32 v[126:127], v[54:55], v[126:127], v[58:59]
	v_pk_mul_f32 v[122:123], v[232:233], v[122:123]
	v_pk_mul_f32 v[124:125], v[136:137], v[124:125]
	v_pk_mul_f32 v[126:127], v[126:127], s[66:67] op_sel_hi:[1,0]
	v_pk_mul_f32 v[128:129], v[128:129], s[66:67] op_sel_hi:[1,0]
	v_pk_fma_f32 v[124:125], v[44:45], v[124:125], v[48:49]
	v_pk_fma_f32 v[122:123], v[42:43], v[122:123], v[46:47]
	v_pk_fma_f32 v[116:117], v[116:117], 0.5, v[128:129] op_sel_hi:[1,0,1]
	v_pk_fma_f32 v[114:115], v[114:115], 0.5, v[126:127] op_sel_hi:[1,0,1]
	v_pk_mul_f32 v[122:123], v[122:123], s[66:67] op_sel_hi:[1,0]
	v_pk_mul_f32 v[124:125], v[124:125], s[66:67] op_sel_hi:[1,0]
	v_add_f32_e32 v126, v114, v115
	v_add_f32_e32 v127, v116, v117
	v_pk_fma_f32 v[124:125], v[112:113], 0.5, v[124:125] op_sel_hi:[1,0,1]
	v_pk_fma_f32 v[122:123], v[110:111], 0.5, v[122:123] op_sel_hi:[1,0,1]
	v_add_f32_e32 v150, v150, v151
	v_add_f32_e32 v126, v126, v127
	v_mul_f32_e32 v127, v115, v115
	v_mul_f32_e32 v128, v117, v117
	v_add_f32_e32 v110, v122, v123
	v_add_f32_e32 v111, v124, v125
	v_add_f32_e32 v150, 0, v150
	v_fmac_f32_e32 v127, v114, v114
	v_fmac_f32_e32 v128, v116, v116
	v_add_f32_e32 v110, v110, v111
	v_mul_f32_e32 v111, v123, v123
	v_mul_f32_e32 v112, v125, v125
	v_add_f32_e32 v143, v143, v150
	v_add_f32_e32 v127, v127, v128
	v_fmac_f32_e32 v111, v122, v122
	v_fmac_f32_e32 v112, v124, v124
	v_add_f32_e32 v126, v143, v126
	v_add_f32_e32 v127, v142, v127
	v_add_f32_e32 v111, v111, v112
	v_add_f32_e32 v110, v110, v126
	v_add_f32_e32 v113, v111, v127
	ds_bpermute_b32 v112, v207, v110
	ds_bpermute_b32 v126, v207, v113
	v_cvt_pk_f16_f32 v114, v114, v115
	v_cvt_pk_f16_f32 v115, v116, v117
	v_cvt_pk_f16_f32 v116, v122, v123
	s_waitcnt lgkmcnt(1)
	v_add_f32_e32 v110, v110, v112
	s_waitcnt lgkmcnt(0)
	v_add_f32_e32 v112, v113, v126
	ds_bpermute_b32 v111, v208, v110
	ds_bpermute_b32 v113, v208, v112
	v_cvt_pk_f16_f32 v117, v124, v125
	global_store_dwordx4 v[134:135], v[114:117], off offset:64
	s_and_saveexec_b64 s[36:37], s[40:41]
	s_cbranch_execz .LBB0_478
	v_lshl_add_u64 v[114:115], v[230:231], 3, s[80:81]
	s_waitcnt lgkmcnt(1)
	v_add_f32_e32 v110, v110, v111
	s_waitcnt lgkmcnt(0)
	v_add_f32_e32 v111, v112, v113
	global_atomic_add_f32 v[114:115], v110, off
	global_atomic_add_f32 v[114:115], v111, off offset:4

;     __device__ __forceinline__ void operator()(const f32x4 (&acc)[2][2][4][2], const Unit& u, int wr, int wc, int fr, int fq) const {
;     ...
;                 if (st) {
;                     const f32x2v sv = *(const f32x2v*)(st + 2 * (size_t)row); rmu[m] = sv.x * (1.0f / 1024.0f); ra[m] = rsqrtf(sv.y * (1.0f / 1024.0f) - rmu[m] * rmu[m] + 1e-5f);
;                     hv[m][0] = *(const f16x8*)(yh + off); hv[m][1] = *(const f16x8*)(yh + off + 32);
;                 }
;             }
;             asm volatile("" ::: "memory");
; #pragma unroll
;             for (int m = 0; m < 4; ++m) {
;                 const int row = row0 + ai * HALF + m * 16; const size_t off = (size_t)row * 1024 + col0;
;                 float s1 = 0.f, s2 = 0.f;
; #pragma unroll
;                 for (int bj = 0; bj < 2; ++bj) {
;                     f32x4 yp[2];
;                     if (st) { const f16x8 h = hv[m][bj]; yp[0] = (f32x4){(float)h[0], (float)h[1], (float)h[2], (float)h[3]}; yp[1] = (f32x4){(float)h[4], (float)h[5], (float)h[6], (float)h[7]}; }
;                     else { yp[0] = *(const f32x4*)(x0 + off + bj * 32); yp[1] = *(const f32x4*)(x0 + off + bj * 32 + 4); }
;                     f32x4 y[2];
; #pragma unroll
;                     for (int n = 0; n < 2; ++n) { const f32x4 x = (yp[n] - rmu[m]) * ra[m] * gv[bj][n] + bv[bj][n];
;                         y[n] = x * alpha + acc[ai][bj][m][n] * s;
;                         s1 += (y[n][0] + y[n][1]) + (y[n][2] + y[n][3]); s2 += (y[n][0] * y[n][0] + y[n][1] * y[n][1]) + (y[n][2] * y[n][2] + y[n][3] * y[n][3]); }
;                     u32x4 w; w.x = cvtpk_h(y[0][0], y[0][1]); w.y = cvtpk_h(y[0][2], y[0][3]); w.z = cvtpk_h(y[1][0], y[1][1]); w.w = cvtpk_h(y[1][2], y[1][3]);
;                     *(u32x4*)(yh + off + bj * 32) = w;
.LBB0_487:
	v_lshl_add_u64 v[98:99], v[116:117], 3, s[50:51]
	s_waitcnt lgkmcnt(1)
	global_load_dwordx2 v[110:111], v[98:99], off
	v_lshlrev_b64 v[98:99], 11, v[116:117]
	v_lshl_add_u64 v[98:99], v[226:227], 0, v[98:99]
	global_load_dwordx4 v[102:105], v[98:99], off
	s_nop 0
	global_load_dwordx4 v[98:101], v[98:99], off offset:64
	s_waitcnt vmcnt(0)
	v_pk_mul_f32 v[110:111], v[110:111], s[64:65] op_sel_hi:[1,0]
	s_nop 0
	v_fma_f32 v111, -v110, v110, v111
	v_add_f32_e32 v111, 0x3727c5ac, v111
	v_mul_f32_e32 v112, 0x4b800000, v111
	v_cmp_gt_f32_e32 vcc, s29, v111
	s_nop 1
	v_cndmask_b32_e32 v111, v111, v112, vcc
	v_rsq_f32_e32 v111, v111
	s_nop 0
	v_mul_f32_e32 v112, 0x45800000, v111
	v_cndmask_b32_e32 v127, v111, v112, vcc
.LBB0_488:
	s_and_b64 vcc, exec, s[38:39]
	s_mov_b64 s[36:37], -1
	s_cbranch_vccnz .LBB0_490
	s_nop 0
	v_cvt_f32_f16_sdwa v123, v158 dst_sel:DWORD dst_unused:UNUSED_PAD src0_sel:WORD_1
	v_cvt_f32_f16_e32 v122, v158
	v_cvt_f32_f16_sdwa v125, v159 dst_sel:DWORD dst_unused:UNUSED_PAD src0_sel:WORD_1
	v_cvt_f32_f16_e32 v124, v159
	s_waitcnt lgkmcnt(0)
	v_cvt_f32_f16_sdwa v113, v160 dst_sel:DWORD dst_unused:UNUSED_PAD src0_sel:WORD_1
	v_cvt_f32_f16_e32 v112, v160
	v_cvt_f32_f16_sdwa v115, v161 dst_sel:DWORD dst_unused:UNUSED_PAD src0_sel:WORD_1
	v_cvt_f32_f16_e32 v114, v161
	s_mov_b64 s[36:37], 0
.LBB0_490:
	v_lshlrev_b64 v[154:155], 10, v[150:151]
	s_nop 0
	v_lshl_add_u64 v[158:159], v[154:155], 0, v[224:225]
	s_andn2_b64 vcc, exec, s[36:37]
	v_lshl_add_u64 v[154:155], v[158:159], 2, s[68:69]
	s_cbranch_vccnz .LBB0_492
	global_load_dwordx4 v[122:125], v[154:155], off
	s_waitcnt lgkmcnt(0)
	global_load_dwordx4 v[112:115], v[154:155], off offset:16
	s_waitcnt vmcnt(0)
.LBB0_492:
	s_nop 0
	v_sub_f32_e32 v125, v125, v152
	v_sub_f32_e32 v124, v124, v152
	v_sub_f32_e32 v123, v123, v152
	v_sub_f32_e32 v122, v122, v152
	v_pk_mul_f32 v[122:123], v[144:145], v[122:123] op_sel_hi:[0,1]
	v_pk_mul_f32 v[124:125], v[144:145], v[124:125] op_sel_hi:[0,1]
	v_pk_fma_f32 v[124:125], v[76:77], v[124:125], v[80:81]
	v_pk_fma_f32 v[122:123], v[74:75], v[122:123], v[78:79]
	s_waitcnt lgkmcnt(1)
	v_mov_b32_e32 v111, v142
	v_pk_mul_f32 v[156:157], v[122:123], s[66:67] op_sel_hi:[1,0]
	v_pk_mul_f32 v[122:123], v[124:125], s[66:67] op_sel_hi:[1,0]
	v_pk_fma_f32 v[124:125], v[94:95], 0.5, v[156:157] op_sel_hi:[1,0,1]
	v_pk_fma_f32 v[122:123], v[96:97], 0.5, v[122:123] op_sel_hi:[1,0,1]
	s_nop 0
	v_sub_f32_e32 v95, v115, v152
	v_sub_f32_e32 v94, v114, v152
	s_waitcnt lgkmcnt(0)
	v_sub_f32_e32 v97, v113, v152
	v_sub_f32_e32 v96, v112, v152
	v_pk_mul_f32 v[96:97], v[144:145], v[96:97] op_sel_hi:[0,1]
	v_pk_mul_f32 v[94:95], v[144:145], v[94:95] op_sel_hi:[0,1]
	v_pk_fma_f32 v[94:95], v[68:69], v[94:95], v[72:73]
	v_pk_fma_f32 v[96:97], v[66:67], v[96:97], v[70:71]
	v_pk_mul_f32 v[94:95], v[94:95], s[66:67] op_sel_hi:[1,0]
	v_pk_mul_f32 v[96:97], v[96:97], s[66:67] op_sel_hi:[1,0]
	v_pk_fma_f32 v[114:115], v[92:93], 0.5, v[94:95] op_sel_hi:[1,0,1]
	v_pk_fma_f32 v[156:157], v[90:91], 0.5, v[96:97] op_sel_hi:[1,0,1]
	v_cvt_pk_f16_f32 v90, v124, v125
	v_cvt_pk_f16_f32 v91, v122, v123
	v_cvt_pk_f16_f32 v92, v156, v157
	v_cvt_pk_f16_f32 v93, v114, v115
	v_lshl_add_u64 v[112:113], v[158:159], 1, s[92:93]
	s_and_b64 vcc, exec, s[38:39]
	s_mov_b64 s[36:37], -1
	global_store_dwordx4 v[112:113], v[90:93], off
	s_cbranch_vccnz .LBB0_494
	v_cvt_f32_f16_sdwa v95, v146 dst_sel:DWORD dst_unused:UNUSED_PAD src0_sel:WORD_1
	v_cvt_f32_f16_e32 v94, v146
	v_cvt_f32_f16_sdwa v97, v147 dst_sel:DWORD dst_unused:UNUSED_PAD src0_sel:WORD_1
	v_cvt_f32_f16_e32 v96, v147
	v_cvt_f32_f16_sdwa v91, v148 dst_sel:DWORD dst_unused:UNUSED_PAD src0_sel:WORD_1
	v_cvt_f32_f16_e32 v90, v148
	v_cvt_f32_f16_sdwa v93, v149 dst_sel:DWORD dst_unused:UNUSED_PAD src0_sel:WORD_1
	v_cvt_f32_f16_e32 v92, v149
	s_mov_b64 s[36:37], 0
;     __device__ __forceinline__ void operator()(const f32x4 (&acc)[2][2][4][2], const Unit& u, int wr, int wc, int fr, int fq) const {
;     ...
;                 for (int bj = 0; bj < 2; ++bj) {
;                     f32x4 yp[2];
;                     if (st) { const f16x8 h = hv[m][bj]; yp[0] = (f32x4){(float)h[0], (float)h[1], (float)h[2], (float)h[3]}; yp[1] = (f32x4){(float)h[4], (float)h[5], (float)h[6], (float)h[7]}; }
;                     else { yp[0] = *(const f32x4*)(x0 + off + bj * 32); yp[1] = *(const f32x4*)(x0 + off + bj * 32 + 4); }
;                     f32x4 y[2];
; #pragma unroll
;                     for (int n = 0; n < 2; ++n) { const f32x4 x = (yp[n] - rmu[m]) * ra[m] * gv[bj][n] + bv[bj][n];
;                         y[n] = x * alpha + acc[ai][bj][m][n] * s;
;                         s1 += (y[n][0] + y[n][1]) + (y[n][2] + y[n][3]); s2 += (y[n][0] * y[n][0] + y[n][1] * y[n][1]) + (y[n][2] * y[n][2] + y[n][3] * y[n][3]); }
;                     u32x4 w; w.x = cvtpk_h(y[0][0], y[0][1]); w.y = cvtpk_h(y[0][2], y[0][3]); w.z = cvtpk_h(y[1][0], y[1][1]); w.w = cvtpk_h(y[1][2], y[1][3]);
;                     *(u32x4*)(yh + off + bj * 32) = w;
;                 }
;                 s1 += __shfl_xor(s1, 16); s1 += __shfl_xor(s1, 32); s2 += __shfl_xor(s2, 16); s2 += __shfl_xor(s2, 32);
;                 if (fq == 0) { atomicAdd(st_new + 2 * (size_t)row, s1); atomicAdd(st_new + 2 * (size_t)row + 1, s2); }
.LBB0_494:
	s_andn2_b64 vcc, exec, s[36:37]
	s_cbranch_vccnz .LBB0_496
	global_load_dwordx4 v[94:97], v[154:155], off offset:128
	global_load_dwordx4 v[90:93], v[154:155], off offset:144
	s_waitcnt vmcnt(0)
.LBB0_496:
	v_add_f32_e32 v135, v124, v125
	v_add_f32_e32 v143, v122, v123
	v_mul_f32_e32 v125, v125, v125
	v_mul_f32_e32 v123, v123, v123
	v_fmac_f32_e32 v125, v124, v124
	v_fmac_f32_e32 v123, v122, v122
	v_add_f32_e32 v122, v125, v123
	v_add_f32_e32 v123, v156, v157
	v_add_f32_e32 v124, v114, v115
	v_add_f32_e32 v123, v123, v124
	v_mul_f32_e32 v124, v157, v157
	v_mul_f32_e32 v115, v115, v115
	v_fmac_f32_e32 v124, v156, v156
	v_fmac_f32_e32 v115, v114, v114
	v_add_f32_e32 v114, v124, v115
	v_mov_b32_e32 v146, v144
	v_mov_b32_e32 v147, v144
	v_add_f32_e32 v122, v122, v114
	s_nop 0
	v_sub_f32_e32 v97, v97, v152
	v_sub_f32_e32 v96, v96, v152
	v_sub_f32_e32 v95, v95, v152
	v_sub_f32_e32 v94, v94, v152
	v_mov_b32_e32 v114, v144
	v_mov_b32_e32 v115, v144
	v_pk_mul_f32 v[94:95], v[146:147], v[94:95]
	v_pk_mul_f32 v[96:97], v[114:115], v[96:97]
	s_nop 0
	v_sub_f32_e32 v93, v93, v152
	v_sub_f32_e32 v92, v92, v152
	v_sub_f32_e32 v91, v91, v152
	v_sub_f32_e32 v90, v90, v152
	v_pk_fma_f32 v[96:97], v[56:57], v[96:97], v[60:61]
	v_pk_fma_f32 v[94:95], v[54:55], v[94:95], v[58:59]
	v_pk_mul_f32 v[90:91], v[146:147], v[90:91]
	v_pk_mul_f32 v[92:93], v[114:115], v[92:93]
	v_pk_mul_f32 v[94:95], v[94:95], s[66:67] op_sel_hi:[1,0]
	v_pk_mul_f32 v[96:97], v[96:97], s[66:67] op_sel_hi:[1,0]
	v_pk_fma_f32 v[92:93], v[44:45], v[92:93], v[48:49]
	v_pk_fma_f32 v[90:91], v[42:43], v[90:91], v[46:47]
	v_pk_fma_f32 v[88:89], v[88:89], 0.5, v[96:97] op_sel_hi:[1,0,1]
	v_pk_fma_f32 v[86:87], v[86:87], 0.5, v[94:95] op_sel_hi:[1,0,1]
	v_pk_mul_f32 v[90:91], v[90:91], s[66:67] op_sel_hi:[1,0]
	v_pk_mul_f32 v[92:93], v[92:93], s[66:67] op_sel_hi:[1,0]
	v_add_f32_e32 v94, v86, v87
	v_add_f32_e32 v95, v88, v89
	v_pk_fma_f32 v[92:93], v[84:85], 0.5, v[92:93] op_sel_hi:[1,0,1]
	v_pk_fma_f32 v[90:91], v[82:83], 0.5, v[90:91] op_sel_hi:[1,0,1]
	v_add_f32_e32 v135, v135, v143
	v_add_f32_e32 v94, v94, v95
	v_mul_f32_e32 v95, v87, v87
	v_mul_f32_e32 v96, v89, v89
	v_add_f32_e32 v82, v90, v91
	v_add_f32_e32 v83, v92, v93
	v_add_f32_e32 v135, 0, v135
	v_fmac_f32_e32 v95, v86, v86
	v_fmac_f32_e32 v96, v88, v88
	v_add_f32_e32 v82, v82, v83
	v_mul_f32_e32 v83, v91, v91
	v_mul_f32_e32 v84, v93, v93
	v_add_f32_e32 v123, v123, v135
	v_add_f32_e32 v95, v95, v96
	v_fmac_f32_e32 v83, v90, v90
	v_fmac_f32_e32 v84, v92, v92
	v_add_f32_e32 v94, v123, v94
	v_add_f32_e32 v95, v122, v95
	v_add_f32_e32 v83, v83, v84
	v_add_f32_e32 v82, v82, v94
	v_add_f32_e32 v85, v83, v95
	ds_bpermute_b32 v84, v207, v82
	ds_bpermute_b32 v94, v207, v85
	v_cvt_pk_f16_f32 v86, v86, v87
	v_cvt_pk_f16_f32 v87, v88, v89
	v_cvt_pk_f16_f32 v88, v90, v91
	s_waitcnt lgkmcnt(1)
	v_add_f32_e32 v82, v82, v84
	s_waitcnt lgkmcnt(0)
	v_add_f32_e32 v84, v85, v94
	ds_bpermute_b32 v83, v208, v82
	ds_bpermute_b32 v85, v208, v84
	v_cvt_pk_f16_f32 v89, v92, v93
	global_store_dwordx4 v[112:113], v[86:89], off offset:64
	s_and_saveexec_b64 s[36:37], s[40:41]
	s_cbranch_execz .LBB0_498
	v_lshl_add_u64 v[86:87], v[150:151], 3, s[80:81]
	s_waitcnt lgkmcnt(1)
	v_add_f32_e32 v82, v82, v83
	s_waitcnt lgkmcnt(0)
	v_add_f32_e32 v83, v84, v85
	global_atomic_add_f32 v[86:87], v82, off
	global_atomic_add_f32 v[86:87], v83, off offset:4

;     __device__ __forceinline__ void operator()(const f32x4 (&acc)[2][2][4][2], const Unit& u, int wr, int wc, int fr, int fq) const {
;     ...
;             for (int m = 0; m < 4; ++m) {
;                 const int row = row0 + ai * HALF + m * 16; const size_t off = (size_t)row * 1024 + col0;
;                 float s1 = 0.f, s2 = 0.f;
; #pragma unroll
;                 for (int bj = 0; bj < 2; ++bj) {
;                     f32x4 yp[2];
;                     if (st) { const f16x8 h = hv[m][bj]; yp[0] = (f32x4){(float)h[0], (float)h[1], (float)h[2], (float)h[3]}; yp[1] = (f32x4){(float)h[4], (float)h[5], (float)h[6], (float)h[7]}; }
;                     else { yp[0] = *(const f32x4*)(x0 + off + bj * 32); yp[1] = *(const f32x4*)(x0 + off + bj * 32 + 4); }
;                     f32x4 y[2];
; #pragma unroll
;                     for (int n = 0; n < 2; ++n) { const f32x4 x = (yp[n] - rmu[m]) * ra[m] * gv[bj][n] + bv[bj][n];
;                         y[n] = x * alpha + acc[ai][bj][m][n] * s;
;                         s1 += (y[n][0] + y[n][1]) + (y[n][2] + y[n][3]); s2 += (y[n][0] * y[n][0] + y[n][1] * y[n][1]) + (y[n][2] * y[n][2] + y[n][3] * y[n][3]); }
;                     u32x4 w; w.x = cvtpk_h(y[0][0], y[0][1]); w.y = cvtpk_h(y[0][2], y[0][3]); w.z = cvtpk_h(y[1][0], y[1][1]); w.w = cvtpk_h(y[1][2], y[1][3]);
;                     *(u32x4*)(yh + off + bj * 32) = w;
;                 }
;                 s1 += __shfl_xor(s1, 16); s1 += __shfl_xor(s1, 32); s2 += __shfl_xor(s2, 16); s2 += __shfl_xor(s2, 32);
;                 if (fq == 0) { atomicAdd(st_new + 2 * (size_t)row, s1); atomicAdd(st_new + 2 * (size_t)row + 1, s2); }
.LBB0_500:
	v_lshlrev_b64 v[90:91], 10, v[136:137]
	v_lshl_add_u64 v[94:95], v[90:91], 0, v[224:225]
	s_andn2_b64 vcc, exec, s[36:37]
	v_lshl_add_u64 v[90:91], v[94:95], 2, s[68:69]
	s_cbranch_vccnz .LBB0_502
	global_load_dwordx4 v[86:89], v[90:91], off
	s_waitcnt lgkmcnt(0)
	global_load_dwordx4 v[82:85], v[90:91], off offset:16
	s_waitcnt vmcnt(0)
.LBB0_502:
	s_nop 0
	v_sub_f32_e32 v89, v89, v111
	v_sub_f32_e32 v88, v88, v111
	v_sub_f32_e32 v87, v87, v111
	v_sub_f32_e32 v86, v86, v111
	v_pk_mul_f32 v[86:87], v[144:145], v[86:87] op_sel:[1,0]
	v_pk_mul_f32 v[88:89], v[144:145], v[88:89] op_sel:[1,0]
	v_pk_fma_f32 v[86:87], v[74:75], v[86:87], v[78:79]
	v_pk_fma_f32 v[88:89], v[76:77], v[88:89], v[80:81]
	v_pk_mul_f32 v[92:93], v[86:87], s[66:67] op_sel_hi:[1,0]
	v_pk_mul_f32 v[86:87], v[88:89], s[66:67] op_sel_hi:[1,0]
	v_pk_fma_f32 v[88:89], v[62:63], 0.5, v[92:93] op_sel_hi:[1,0,1]
	v_pk_fma_f32 v[86:87], v[64:65], 0.5, v[86:87] op_sel_hi:[1,0,1]
	s_waitcnt lgkmcnt(0)
	v_sub_f32_e32 v63, v85, v111
	v_sub_f32_e32 v62, v84, v111
	v_sub_f32_e32 v65, v83, v111
	v_sub_f32_e32 v64, v82, v111
	v_pk_mul_f32 v[64:65], v[144:145], v[64:65] op_sel:[1,0]
	v_pk_mul_f32 v[62:63], v[144:145], v[62:63] op_sel:[1,0]
	v_pk_fma_f32 v[64:65], v[66:67], v[64:65], v[70:71]
	v_pk_fma_f32 v[62:63], v[68:69], v[62:63], v[72:73]
	v_pk_mul_f32 v[64:65], v[64:65], s[66:67] op_sel_hi:[1,0]
	v_pk_mul_f32 v[62:63], v[62:63], s[66:67] op_sel_hi:[1,0]
	v_pk_fma_f32 v[92:93], v[50:51], 0.5, v[64:65] op_sel_hi:[1,0,1]
	v_pk_fma_f32 v[84:85], v[52:53], 0.5, v[62:63] op_sel_hi:[1,0,1]
	v_cvt_pk_f16_f32 v50, v88, v89
	v_cvt_pk_f16_f32 v51, v86, v87
	v_cvt_pk_f16_f32 v52, v92, v93
	v_cvt_pk_f16_f32 v53, v84, v85
	v_lshl_add_u64 v[82:83], v[94:95], 1, s[92:93]
	s_and_b64 vcc, exec, s[38:39]
	s_mov_b64 s[36:37], -1
	global_store_dwordx4 v[82:83], v[50:53], off
	s_cbranch_vccnz .LBB0_504
	v_cvt_f32_f16_sdwa v63, v130 dst_sel:DWORD dst_unused:UNUSED_PAD src0_sel:WORD_1
	v_cvt_f32_f16_e32 v62, v130
	v_cvt_f32_f16_sdwa v65, v131 dst_sel:DWORD dst_unused:UNUSED_PAD src0_sel:WORD_1
	v_cvt_f32_f16_e32 v64, v131
	v_cvt_f32_f16_sdwa v51, v132 dst_sel:DWORD dst_unused:UNUSED_PAD src0_sel:WORD_1
	v_cvt_f32_f16_e32 v50, v132
	v_cvt_f32_f16_sdwa v53, v133 dst_sel:DWORD dst_unused:UNUSED_PAD src0_sel:WORD_1
	v_cvt_f32_f16_e32 v52, v133
	s_mov_b64 s[36:37], 0
.LBB0_504:
	s_andn2_b64 vcc, exec, s[36:37]
	s_cbranch_vccnz .LBB0_506
	global_load_dwordx4 v[62:65], v[90:91], off offset:128
	global_load_dwordx4 v[50:53], v[90:91], off offset:144
	s_waitcnt vmcnt(0)
.LBB0_506:
	v_add_f32_e32 v90, v88, v89
	v_add_f32_e32 v91, v86, v87
	v_mul_f32_e32 v89, v89, v89
	v_mul_f32_e32 v87, v87, v87
	v_fmac_f32_e32 v89, v88, v88
	v_fmac_f32_e32 v87, v86, v86
	v_add_f32_e32 v86, v89, v87
	v_add_f32_e32 v87, v92, v93
	v_add_f32_e32 v88, v84, v85
	v_add_f32_e32 v87, v87, v88
	v_mul_f32_e32 v88, v93, v93
	v_mul_f32_e32 v85, v85, v85
	v_fmac_f32_e32 v88, v92, v92
	v_fmac_f32_e32 v85, v84, v84
	v_add_f32_e32 v84, v88, v85
	v_mov_b32_e32 v144, v145
	v_add_f32_e32 v86, v86, v84
	s_nop 0
	v_sub_f32_e32 v65, v65, v111
	v_sub_f32_e32 v64, v64, v142
	v_sub_f32_e32 v63, v63, v111
	v_sub_f32_e32 v62, v62, v142
	v_mov_b32_e32 v84, v145
	v_mov_b32_e32 v85, v145
	v_pk_mul_f32 v[62:63], v[144:145], v[62:63]
	v_pk_mul_f32 v[64:65], v[84:85], v[64:65]
	s_nop 0
	v_sub_f32_e32 v53, v53, v111
	v_sub_f32_e32 v52, v52, v142
	v_sub_f32_e32 v51, v51, v111
	v_sub_f32_e32 v50, v50, v142
	v_pk_fma_f32 v[64:65], v[56:57], v[64:65], v[60:61]
	v_pk_fma_f32 v[62:63], v[54:55], v[62:63], v[58:59]
	v_pk_mul_f32 v[50:51], v[144:145], v[50:51]
	v_pk_mul_f32 v[52:53], v[84:85], v[52:53]
	v_pk_mul_f32 v[62:63], v[62:63], s[66:67] op_sel_hi:[1,0]
	v_pk_mul_f32 v[64:65], v[64:65], s[66:67] op_sel_hi:[1,0]
	v_pk_fma_f32 v[52:53], v[44:45], v[52:53], v[48:49]
	v_pk_fma_f32 v[50:51], v[42:43], v[50:51], v[46:47]
	v_pk_fma_f32 v[40:41], v[40:41], 0.5, v[64:65] op_sel_hi:[1,0,1]
	v_pk_fma_f32 v[38:39], v[38:39], 0.5, v[62:63] op_sel_hi:[1,0,1]
	v_pk_mul_f32 v[50:51], v[50:51], s[66:67] op_sel_hi:[1,0]
	v_pk_mul_f32 v[52:53], v[52:53], s[66:67] op_sel_hi:[1,0]
	v_add_f32_e32 v62, v38, v39
	v_add_f32_e32 v63, v40, v41
	v_pk_fma_f32 v[52:53], v[36:37], 0.5, v[52:53] op_sel_hi:[1,0,1]
	v_pk_fma_f32 v[50:51], v[34:35], 0.5, v[50:51] op_sel_hi:[1,0,1]
	v_add_f32_e32 v90, v90, v91
	v_add_f32_e32 v62, v62, v63
	v_mul_f32_e32 v63, v39, v39
	v_mul_f32_e32 v64, v41, v41
	v_add_f32_e32 v34, v50, v51
	v_add_f32_e32 v35, v52, v53
	v_add_f32_e32 v90, 0, v90
	v_fmac_f32_e32 v63, v38, v38
	v_fmac_f32_e32 v64, v40, v40
	v_add_f32_e32 v34, v34, v35
	v_mul_f32_e32 v35, v51, v51
	v_mul_f32_e32 v36, v53, v53
	v_add_f32_e32 v87, v87, v90
	v_add_f32_e32 v63, v63, v64
	v_fmac_f32_e32 v35, v50, v50
	v_fmac_f32_e32 v36, v52, v52
	v_add_f32_e32 v62, v87, v62
	v_add_f32_e32 v63, v86, v63
	v_add_f32_e32 v35, v35, v36
	v_add_f32_e32 v34, v34, v62
	v_add_f32_e32 v37, v35, v63
	ds_bpermute_b32 v36, v207, v34
	ds_bpermute_b32 v62, v207, v37
	v_cvt_pk_f16_f32 v38, v38, v39
	v_cvt_pk_f16_f32 v39, v40, v41
	v_cvt_pk_f16_f32 v40, v50, v51
	s_waitcnt lgkmcnt(1)
	v_add_f32_e32 v34, v34, v36
	s_waitcnt lgkmcnt(0)
	v_add_f32_e32 v36, v37, v62
	ds_bpermute_b32 v35, v208, v34
	ds_bpermute_b32 v37, v208, v36
	v_cvt_pk_f16_f32 v41, v52, v53
	global_store_dwordx4 v[82:83], v[38:41], off offset:64
	s_and_saveexec_b64 s[36:37], s[40:41]
	s_cbranch_execz .LBB0_508
	v_lshl_add_u64 v[38:39], v[136:137], 3, s[80:81]
	s_waitcnt lgkmcnt(1)
	v_add_f32_e32 v34, v34, v35
	s_waitcnt lgkmcnt(0)
	v_add_f32_e32 v35, v36, v37
	global_atomic_add_f32 v[38:39], v34, off
	global_atomic_add_f32 v[38:39], v35, off offset:4

;     __device__ __forceinline__ void operator()(const f32x4 (&acc)[2][2][4][2], const Unit& u, int wr, int wc, int fr, int fq) const {
;     ...
;             for (int m = 0; m < 4; ++m) {
;                 const int row = row0 + ai * HALF + m * 16; const size_t off = (size_t)row * 1024 + col0;
;                 float s1 = 0.f, s2 = 0.f;
; #pragma unroll
;                 for (int bj = 0; bj < 2; ++bj) {
;                     f32x4 yp[2];
;                     if (st) { const f16x8 h = hv[m][bj]; yp[0] = (f32x4){(float)h[0], (float)h[1], (float)h[2], (float)h[3]}; yp[1] = (f32x4){(float)h[4], (float)h[5], (float)h[6], (float)h[7]}; }
;                     else { yp[0] = *(const f32x4*)(x0 + off + bj * 32); yp[1] = *(const f32x4*)(x0 + off + bj * 32 + 4); }
;                     f32x4 y[2];
; #pragma unroll
;                     for (int n = 0; n < 2; ++n) { const f32x4 x = (yp[n] - rmu[m]) * ra[m] * gv[bj][n] + bv[bj][n];
;                         y[n] = x * alpha + acc[ai][bj][m][n] * s;
;                         s1 += (y[n][0] + y[n][1]) + (y[n][2] + y[n][3]); s2 += (y[n][0] * y[n][0] + y[n][1] * y[n][1]) + (y[n][2] * y[n][2] + y[n][3] * y[n][3]); }
;                     u32x4 w; w.x = cvtpk_h(y[0][0], y[0][1]); w.y = cvtpk_h(y[0][2], y[0][3]); w.z = cvtpk_h(y[1][0], y[1][1]); w.w = cvtpk_h(y[1][2], y[1][3]);
;                     *(u32x4*)(yh + off + bj * 32) = w;
;                 }
;                 s1 += __shfl_xor(s1, 16); s1 += __shfl_xor(s1, 32); s2 += __shfl_xor(s2, 16); s2 += __shfl_xor(s2, 32);
;                 if (fq == 0) { atomicAdd(st_new + 2 * (size_t)row, s1); atomicAdd(st_new + 2 * (size_t)row + 1, s2); }
.LBB0_510:
	v_lshlrev_b64 v[50:51], 10, v[128:129]
	v_lshl_add_u64 v[62:63], v[50:51], 0, v[224:225]
	s_andn2_b64 vcc, exec, s[36:37]
	v_lshl_add_u64 v[50:51], v[62:63], 2, s[68:69]
	s_cbranch_vccnz .LBB0_512
	global_load_dwordx4 v[38:41], v[50:51], off
	s_waitcnt lgkmcnt(0)
	global_load_dwordx4 v[34:37], v[50:51], off offset:16
	s_waitcnt vmcnt(0)
.LBB0_512:
	s_nop 0
	v_sub_f32_e32 v41, v41, v134
	v_sub_f32_e32 v40, v40, v134
	v_sub_f32_e32 v39, v39, v134
	v_sub_f32_e32 v38, v38, v134
	v_pk_mul_f32 v[38:39], v[126:127], v[38:39] op_sel_hi:[0,1]
	v_pk_mul_f32 v[40:41], v[126:127], v[40:41] op_sel_hi:[0,1]
	v_pk_fma_f32 v[40:41], v[76:77], v[40:41], v[80:81]
	v_pk_fma_f32 v[38:39], v[74:75], v[38:39], v[78:79]
	s_and_b64 vcc, exec, s[38:39]
	v_pk_mul_f32 v[52:53], v[38:39], s[66:67] op_sel_hi:[1,0]
	v_pk_mul_f32 v[38:39], v[40:41], s[66:67] op_sel_hi:[1,0]
	v_pk_fma_f32 v[40:41], v[30:31], 0.5, v[52:53] op_sel_hi:[1,0,1]
	v_pk_fma_f32 v[38:39], v[32:33], 0.5, v[38:39] op_sel_hi:[1,0,1]
	s_waitcnt lgkmcnt(0)
	v_sub_f32_e32 v31, v37, v134
	v_sub_f32_e32 v30, v36, v134
	v_sub_f32_e32 v33, v35, v134
	v_sub_f32_e32 v32, v34, v134
	v_pk_mul_f32 v[32:33], v[126:127], v[32:33] op_sel_hi:[0,1]
	v_pk_mul_f32 v[30:31], v[126:127], v[30:31] op_sel_hi:[0,1]
	v_pk_fma_f32 v[30:31], v[68:69], v[30:31], v[72:73]
	v_pk_fma_f32 v[32:33], v[66:67], v[32:33], v[70:71]
	v_pk_mul_f32 v[30:31], v[30:31], s[66:67] op_sel_hi:[1,0]
	v_pk_mul_f32 v[32:33], v[32:33], s[66:67] op_sel_hi:[1,0]
	v_pk_fma_f32 v[36:37], v[28:29], 0.5, v[30:31] op_sel_hi:[1,0,1]
	v_pk_fma_f32 v[52:53], v[26:27], 0.5, v[32:33] op_sel_hi:[1,0,1]
	v_cvt_pk_f16_f32 v26, v40, v41
	v_cvt_pk_f16_f32 v27, v38, v39
	v_cvt_pk_f16_f32 v28, v52, v53
	v_cvt_pk_f16_f32 v29, v36, v37
	v_lshl_add_u64 v[34:35], v[62:63], 1, s[92:93]
	s_mov_b64 s[36:37], -1
	global_store_dwordx4 v[34:35], v[26:29], off
	s_cbranch_vccnz .LBB0_514
	v_cvt_f32_f16_sdwa v31, v106 dst_sel:DWORD dst_unused:UNUSED_PAD src0_sel:WORD_1
	v_cvt_f32_f16_e32 v30, v106
	v_cvt_f32_f16_sdwa v33, v107 dst_sel:DWORD dst_unused:UNUSED_PAD src0_sel:WORD_1
	v_cvt_f32_f16_e32 v32, v107
	v_cvt_f32_f16_sdwa v27, v108 dst_sel:DWORD dst_unused:UNUSED_PAD src0_sel:WORD_1
	v_cvt_f32_f16_e32 v26, v108
	v_cvt_f32_f16_sdwa v29, v109 dst_sel:DWORD dst_unused:UNUSED_PAD src0_sel:WORD_1
	v_cvt_f32_f16_e32 v28, v109
	s_mov_b64 s[36:37], 0
.LBB0_514:
	s_andn2_b64 vcc, exec, s[36:37]
	s_cbranch_vccnz .LBB0_516
	global_load_dwordx4 v[30:33], v[50:51], off offset:128
	global_load_dwordx4 v[26:29], v[50:51], off offset:144
	s_waitcnt vmcnt(0)
.LBB0_516:
	v_add_f32_e32 v62, v40, v41
	v_add_f32_e32 v63, v38, v39
	v_mul_f32_e32 v41, v41, v41
	v_mul_f32_e32 v39, v39, v39
	v_fmac_f32_e32 v41, v40, v40
	v_fmac_f32_e32 v39, v38, v38
	v_add_f32_e32 v38, v41, v39
	v_add_f32_e32 v39, v52, v53
	v_add_f32_e32 v40, v36, v37
	v_add_f32_e32 v39, v39, v40
	v_mul_f32_e32 v40, v53, v53
	v_mul_f32_e32 v37, v37, v37
	v_fmac_f32_e32 v40, v52, v52
	v_fmac_f32_e32 v37, v36, v36
	v_add_f32_e32 v36, v40, v37
	v_mov_b32_e32 v50, v126
	v_mov_b32_e32 v51, v126
	v_add_f32_e32 v38, v38, v36
	s_nop 0
	v_sub_f32_e32 v33, v33, v134
	v_sub_f32_e32 v32, v32, v134
	v_sub_f32_e32 v31, v31, v134
	v_sub_f32_e32 v30, v30, v134
	v_mov_b32_e32 v36, v126
	v_mov_b32_e32 v37, v126
	v_pk_mul_f32 v[30:31], v[50:51], v[30:31]
	v_pk_mul_f32 v[32:33], v[36:37], v[32:33]
	s_nop 0
	v_sub_f32_e32 v29, v29, v134
	v_sub_f32_e32 v28, v28, v134
	v_sub_f32_e32 v27, v27, v134
	v_sub_f32_e32 v26, v26, v134
	v_pk_fma_f32 v[32:33], v[56:57], v[32:33], v[60:61]
	v_pk_fma_f32 v[30:31], v[54:55], v[30:31], v[58:59]
	v_pk_mul_f32 v[26:27], v[50:51], v[26:27]
	v_pk_mul_f32 v[28:29], v[36:37], v[28:29]
	v_pk_mul_f32 v[30:31], v[30:31], s[66:67] op_sel_hi:[1,0]
	v_pk_mul_f32 v[32:33], v[32:33], s[66:67] op_sel_hi:[1,0]
	v_pk_fma_f32 v[28:29], v[44:45], v[28:29], v[48:49]
	v_pk_fma_f32 v[26:27], v[42:43], v[26:27], v[46:47]
	v_pk_fma_f32 v[24:25], v[24:25], 0.5, v[32:33] op_sel_hi:[1,0,1]
	v_pk_fma_f32 v[22:23], v[22:23], 0.5, v[30:31] op_sel_hi:[1,0,1]
	v_pk_mul_f32 v[26:27], v[26:27], s[66:67] op_sel_hi:[1,0]
	v_pk_mul_f32 v[28:29], v[28:29], s[66:67] op_sel_hi:[1,0]
	v_add_f32_e32 v30, v22, v23
	v_add_f32_e32 v31, v24, v25
	v_pk_fma_f32 v[28:29], v[20:21], 0.5, v[28:29] op_sel_hi:[1,0,1]
	v_pk_fma_f32 v[26:27], v[18:19], 0.5, v[26:27] op_sel_hi:[1,0,1]
	v_add_f32_e32 v62, v62, v63
	v_add_f32_e32 v30, v30, v31
	v_mul_f32_e32 v31, v23, v23
	v_mul_f32_e32 v32, v25, v25
	v_add_f32_e32 v18, v26, v27
	v_add_f32_e32 v19, v28, v29
	v_add_f32_e32 v62, 0, v62
	v_fmac_f32_e32 v31, v22, v22
	v_fmac_f32_e32 v32, v24, v24
	v_add_f32_e32 v18, v18, v19
	v_mul_f32_e32 v19, v27, v27
	v_mul_f32_e32 v20, v29, v29
	v_add_f32_e32 v39, v39, v62
	v_add_f32_e32 v31, v31, v32
	v_fmac_f32_e32 v19, v26, v26
	v_fmac_f32_e32 v20, v28, v28
	v_add_f32_e32 v30, v39, v30
	v_add_f32_e32 v31, v38, v31
	v_add_f32_e32 v19, v19, v20
	v_add_f32_e32 v18, v18, v30
	v_add_f32_e32 v21, v19, v31
	ds_bpermute_b32 v20, v207, v18
	ds_bpermute_b32 v30, v207, v21
	v_cvt_pk_f16_f32 v22, v22, v23
	v_cvt_pk_f16_f32 v23, v24, v25
	v_cvt_pk_f16_f32 v24, v26, v27
	s_waitcnt lgkmcnt(1)
	v_add_f32_e32 v18, v18, v20
	s_waitcnt lgkmcnt(0)
	v_add_f32_e32 v20, v21, v30
	ds_bpermute_b32 v19, v208, v18
	ds_bpermute_b32 v21, v208, v20
	v_cvt_pk_f16_f32 v25, v28, v29
	global_store_dwordx4 v[34:35], v[22:25], off offset:64
	s_and_saveexec_b64 s[36:37], s[40:41]
	s_cbranch_execz .LBB0_518
	v_lshl_add_u64 v[22:23], v[128:129], 3, s[80:81]
	s_waitcnt lgkmcnt(1)
	v_add_f32_e32 v18, v18, v19
	s_waitcnt lgkmcnt(0)
	v_add_f32_e32 v19, v20, v21
	global_atomic_add_f32 v[22:23], v18, off
	global_atomic_add_f32 v[22:23], v19, off offset:4

;     __device__ __forceinline__ void operator()(const f32x4 (&acc)[2][2][4][2], const Unit& u, int wr, int wc, int fr, int fq) const {
;     ...
;             for (int m = 0; m < 4; ++m) {
;                 const int row = row0 + ai * HALF + m * 16; const size_t off = (size_t)row * 1024 + col0;
;                 float s1 = 0.f, s2 = 0.f;
; #pragma unroll
;                 for (int bj = 0; bj < 2; ++bj) {
;                     f32x4 yp[2];
;                     if (st) { const f16x8 h = hv[m][bj]; yp[0] = (f32x4){(float)h[0], (float)h[1], (float)h[2], (float)h[3]}; yp[1] = (f32x4){(float)h[4], (float)h[5], (float)h[6], (float)h[7]}; }
;                     else { yp[0] = *(const f32x4*)(x0 + off + bj * 32); yp[1] = *(const f32x4*)(x0 + off + bj * 32 + 4); }
;                     f32x4 y[2];
; #pragma unroll
;                     for (int n = 0; n < 2; ++n) { const f32x4 x = (yp[n] - rmu[m]) * ra[m] * gv[bj][n] + bv[bj][n];
;                         y[n] = x * alpha + acc[ai][bj][m][n] * s;
;                         s1 += (y[n][0] + y[n][1]) + (y[n][2] + y[n][3]); s2 += (y[n][0] * y[n][0] + y[n][1] * y[n][1]) + (y[n][2] * y[n][2] + y[n][3] * y[n][3]); }
;                     u32x4 w; w.x = cvtpk_h(y[0][0], y[0][1]); w.y = cvtpk_h(y[0][2], y[0][3]); w.z = cvtpk_h(y[1][0], y[1][1]); w.w = cvtpk_h(y[1][2], y[1][3]);
;                     *(u32x4*)(yh + off + bj * 32) = w;
;                 }
;                 s1 += __shfl_xor(s1, 16); s1 += __shfl_xor(s1, 32); s2 += __shfl_xor(s2, 16); s2 += __shfl_xor(s2, 32);
;                 if (fq == 0) { atomicAdd(st_new + 2 * (size_t)row, s1); atomicAdd(st_new + 2 * (size_t)row + 1, s2); }
.LBB0_520:
	v_lshlrev_b64 v[26:27], 10, v[116:117]
	v_lshl_add_u64 v[30:31], v[26:27], 0, v[224:225]
	s_andn2_b64 vcc, exec, s[36:37]
	v_lshl_add_u64 v[26:27], v[30:31], 2, s[68:69]
	s_cbranch_vccnz .LBB0_522
	global_load_dwordx4 v[22:25], v[26:27], off
	s_waitcnt lgkmcnt(0)
	global_load_dwordx4 v[18:21], v[26:27], off offset:16
	s_waitcnt vmcnt(0)
.LBB0_522:
	s_nop 0
	v_sub_f32_e32 v25, v25, v110
	v_sub_f32_e32 v24, v24, v110
	v_sub_f32_e32 v23, v23, v110
	v_sub_f32_e32 v22, v22, v110
	v_mov_b32_e32 v28, v127
	v_pk_mul_f32 v[22:23], v[28:29], v[22:23] op_sel_hi:[0,1]
	v_pk_mul_f32 v[24:25], v[28:29], v[24:25] op_sel_hi:[0,1]
	v_pk_fma_f32 v[24:25], v[76:77], v[24:25], v[80:81]
	v_pk_fma_f32 v[22:23], v[74:75], v[22:23], v[78:79]
	s_and_b64 vcc, exec, s[38:39]
	v_pk_mul_f32 v[32:33], v[22:23], s[66:67] op_sel_hi:[1,0]
	v_pk_mul_f32 v[22:23], v[24:25], s[66:67] op_sel_hi:[1,0]
	v_pk_fma_f32 v[24:25], v[14:15], 0.5, v[32:33] op_sel_hi:[1,0,1]
	v_pk_fma_f32 v[22:23], v[16:17], 0.5, v[22:23] op_sel_hi:[1,0,1]
	s_waitcnt lgkmcnt(0)
	v_sub_f32_e32 v15, v21, v110
	v_sub_f32_e32 v14, v20, v110
	v_sub_f32_e32 v17, v19, v110
	v_sub_f32_e32 v16, v18, v110
	v_pk_mul_f32 v[16:17], v[28:29], v[16:17] op_sel_hi:[0,1]
	v_pk_mul_f32 v[14:15], v[28:29], v[14:15] op_sel_hi:[0,1]
	v_pk_fma_f32 v[14:15], v[68:69], v[14:15], v[72:73]
	v_pk_fma_f32 v[16:17], v[66:67], v[16:17], v[70:71]
	v_pk_mul_f32 v[14:15], v[14:15], s[66:67] op_sel_hi:[1,0]
	v_pk_mul_f32 v[16:17], v[16:17], s[66:67] op_sel_hi:[1,0]
	v_pk_fma_f32 v[20:21], v[12:13], 0.5, v[14:15] op_sel_hi:[1,0,1]
	v_pk_fma_f32 v[28:29], v[10:11], 0.5, v[16:17] op_sel_hi:[1,0,1]
	v_cvt_pk_f16_f32 v10, v24, v25
	v_cvt_pk_f16_f32 v11, v22, v23
	v_cvt_pk_f16_f32 v12, v28, v29
	v_cvt_pk_f16_f32 v13, v20, v21
	v_lshl_add_u64 v[18:19], v[30:31], 1, s[92:93]
	s_mov_b64 s[36:37], -1
	global_store_dwordx4 v[18:19], v[10:13], off
	s_cbranch_vccnz .LBB0_524
	v_cvt_f32_f16_sdwa v15, v98 dst_sel:DWORD dst_unused:UNUSED_PAD src0_sel:WORD_1
	v_cvt_f32_f16_e32 v14, v98
	v_cvt_f32_f16_sdwa v17, v99 dst_sel:DWORD dst_unused:UNUSED_PAD src0_sel:WORD_1
	v_cvt_f32_f16_e32 v16, v99
	v_cvt_f32_f16_sdwa v11, v100 dst_sel:DWORD dst_unused:UNUSED_PAD src0_sel:WORD_1
	v_cvt_f32_f16_e32 v10, v100
	v_cvt_f32_f16_sdwa v13, v101 dst_sel:DWORD dst_unused:UNUSED_PAD src0_sel:WORD_1
	v_cvt_f32_f16_e32 v12, v101
	s_mov_b64 s[36:37], 0
.LBB0_524:
	s_andn2_b64 vcc, exec, s[36:37]
	s_cbranch_vccnz .LBB0_526
	global_load_dwordx4 v[14:17], v[26:27], off offset:128
	global_load_dwordx4 v[10:13], v[26:27], off offset:144
	s_waitcnt vmcnt(0)
.LBB0_526:
	v_mov_b32_e32 v26, v127
	v_mov_b32_e32 v27, v127
	s_nop 0
	v_sub_f32_e32 v17, v17, v110
	v_sub_f32_e32 v16, v16, v110
	v_sub_f32_e32 v15, v15, v110
	v_sub_f32_e32 v14, v14, v110
	v_mov_b32_e32 v126, v127
	v_pk_mul_f32 v[14:15], v[26:27], v[14:15]
	v_pk_mul_f32 v[16:17], v[126:127], v[16:17]
	s_nop 0
	v_sub_f32_e32 v13, v13, v110
	v_sub_f32_e32 v12, v12, v110
	v_sub_f32_e32 v11, v11, v110
	v_sub_f32_e32 v10, v10, v110
	v_add_f32_e32 v30, v24, v25
	v_add_f32_e32 v31, v22, v23
	v_mul_f32_e32 v25, v25, v25
	v_mul_f32_e32 v23, v23, v23
	v_pk_fma_f32 v[16:17], v[56:57], v[16:17], v[60:61]
	v_pk_fma_f32 v[14:15], v[54:55], v[14:15], v[58:59]
	v_pk_mul_f32 v[10:11], v[26:27], v[10:11]
	v_pk_mul_f32 v[12:13], v[126:127], v[12:13]
	v_fmac_f32_e32 v25, v24, v24
	v_fmac_f32_e32 v23, v22, v22
	v_pk_mul_f32 v[14:15], v[14:15], s[66:67] op_sel_hi:[1,0]
	v_pk_mul_f32 v[16:17], v[16:17], s[66:67] op_sel_hi:[1,0]
	v_pk_fma_f32 v[12:13], v[44:45], v[12:13], v[48:49]
	v_pk_fma_f32 v[10:11], v[42:43], v[10:11], v[46:47]
	v_add_f32_e32 v22, v25, v23
	v_add_f32_e32 v23, v28, v29
	v_add_f32_e32 v24, v20, v21
	v_pk_fma_f32 v[8:9], v[8:9], 0.5, v[16:17] op_sel_hi:[1,0,1]
	v_pk_fma_f32 v[6:7], v[6:7], 0.5, v[14:15] op_sel_hi:[1,0,1]
	v_pk_mul_f32 v[10:11], v[10:11], s[66:67] op_sel_hi:[1,0]
	v_pk_mul_f32 v[12:13], v[12:13], s[66:67] op_sel_hi:[1,0]
	v_add_f32_e32 v23, v23, v24
	v_mul_f32_e32 v24, v29, v29
	v_mul_f32_e32 v21, v21, v21
	v_add_f32_e32 v14, v6, v7
	v_add_f32_e32 v15, v8, v9
	v_pk_fma_f32 v[12:13], v[4:5], 0.5, v[12:13] op_sel_hi:[1,0,1]
	v_pk_fma_f32 v[10:11], v[2:3], 0.5, v[10:11] op_sel_hi:[1,0,1]
	v_add_f32_e32 v30, v30, v31
	v_fmac_f32_e32 v24, v28, v28
	v_fmac_f32_e32 v21, v20, v20
	v_add_f32_e32 v14, v14, v15
	v_mul_f32_e32 v15, v7, v7
	v_mul_f32_e32 v16, v9, v9
	v_add_f32_e32 v2, v10, v11
	v_add_f32_e32 v3, v12, v13
	v_add_f32_e32 v30, 0, v30
	v_add_f32_e32 v20, v24, v21
	v_fmac_f32_e32 v15, v6, v6
	v_fmac_f32_e32 v16, v8, v8
	v_add_f32_e32 v2, v2, v3
	v_mul_f32_e32 v3, v11, v11
	v_mul_f32_e32 v4, v13, v13
	v_add_f32_e32 v23, v23, v30
	v_add_f32_e32 v20, v22, v20
	v_add_f32_e32 v15, v15, v16
	v_fmac_f32_e32 v3, v10, v10
	v_fmac_f32_e32 v4, v12, v12
	v_add_f32_e32 v14, v23, v14
	v_add_f32_e32 v15, v20, v15
	v_add_f32_e32 v3, v3, v4
	v_add_f32_e32 v2, v2, v14
	v_add_f32_e32 v5, v3, v15
	ds_bpermute_b32 v4, v207, v2
	ds_bpermute_b32 v14, v207, v5
	v_cvt_pk_f16_f32 v6, v6, v7
	v_cvt_pk_f16_f32 v7, v8, v9
	v_cvt_pk_f16_f32 v8, v10, v11
	s_waitcnt lgkmcnt(1)
	v_add_f32_e32 v2, v2, v4
	s_waitcnt lgkmcnt(0)
	v_add_f32_e32 v4, v5, v14
	ds_bpermute_b32 v3, v208, v2
	ds_bpermute_b32 v5, v208, v4
	v_cvt_pk_f16_f32 v9, v12, v13
	global_store_dwordx4 v[18:19], v[6:9], off offset:64
	s_and_saveexec_b64 s[36:37], s[40:41]
	s_cbranch_execz .LBB0_528
	v_lshl_add_u64 v[6:7], v[116:117], 3, s[80:81]
	s_waitcnt lgkmcnt(1)
	v_add_f32_e32 v2, v2, v3
	s_waitcnt lgkmcnt(0)
	v_add_f32_e32 v3, v4, v5
	global_atomic_add_f32 v[6:7], v2, off
	global_atomic_add_f32 v[6:7], v3, off offset:4

;     __device__ __forceinline__ void operator()(const f32x4 (&acc)[2][2][4][2], const Unit& u, int wr, int wc, int fr, int fq) const {
;     ...
;                     f32x4 yp[2];
;                     if (st) { const f16x8 h = hv[m][bj]; yp[0] = (f32x4){(float)h[0], (float)h[1], (float)h[2], (float)h[3]}; yp[1] = (f32x4){(float)h[4], (float)h[5], (float)h[6], (float)h[7]}; }
;                     else { yp[0] = *(const f32x4*)(x0 + off + bj * 32); yp[1] = *(const f32x4*)(x0 + off + bj * 32 + 4); }
;                     f32x4 y[2];
; #pragma unroll
;                     for (int n = 0; n < 2; ++n) { const f32x4 x = (yp[n] - rmu[m]) * ra[m] * gv[bj][n] + bv[bj][n];
;                         y[n] = x * alpha + acc[ai][bj][m][n] * s;
;                         s1 += (y[n][0] + y[n][1]) + (y[n][2] + y[n][3]); s2 += (y[n][0] * y[n][0] + y[n][1] * y[n][1]) + (y[n][2] * y[n][2] + y[n][3] * y[n][3]); }
;                     u32x4 w; w.x = cvtpk_h(y[0][0], y[0][1]); w.y = cvtpk_h(y[0][2], y[0][3]); w.z = cvtpk_h(y[1][0], y[1][1]); w.w = cvtpk_h(y[1][2], y[1][3]);
;                     *(u32x4*)(yh + off + bj * 32) = w;
.LBB0_881:
	v_lshlrev_b64 v[238:239], 10, v[228:229]
	v_lshl_add_u64 v[250:251], v[238:239], 0, v[224:225]
	s_andn2_b64 vcc, exec, s[36:37]
	v_lshl_add_u64 v[246:247], v[250:251], 2, s[68:69]
	s_cbranch_vccnz .LBB0_883
	global_load_dwordx4 v[202:205], v[246:247], off
	global_load_dwordx4 v[198:201], v[246:247], off offset:16
	s_waitcnt vmcnt(0)
.LBB0_883:
	v_mov_b32_e32 v245, v242
	s_nop 0
	v_sub_f32_e32 v203, v203, v178
	v_sub_f32_e32 v202, v202, v178
	v_sub_f32_e32 v205, v205, v178
	v_sub_f32_e32 v204, v204, v178
	v_pk_mul_f32 v[204:205], v[244:245], v[204:205] op_sel_hi:[0,1]
	v_pk_mul_f32 v[202:203], v[244:245], v[202:203] op_sel_hi:[0,1]
	v_pk_fma_f32 v[248:249], v[74:75], v[202:203], v[78:79]
	v_pk_fma_f32 v[202:203], v[76:77], v[204:205], v[80:81]
	v_pk_fma_f32 v[204:205], v[248:249], s[66:67], v[194:195] op_sel_hi:[1,0,1]
	v_pk_fma_f32 v[202:203], v[202:203], s[66:67], v[196:197] op_sel_hi:[1,0,1]
	v_sub_f32_e32 v195, v199, v178
	v_sub_f32_e32 v194, v198, v178
	v_sub_f32_e32 v197, v201, v178
	v_sub_f32_e32 v196, v200, v178
	v_pk_mul_f32 v[196:197], v[244:245], v[196:197] op_sel_hi:[0,1]
	v_pk_mul_f32 v[194:195], v[244:245], v[194:195] op_sel_hi:[0,1]
	v_pk_fma_f32 v[194:195], v[66:67], v[194:195], v[70:71]
	v_pk_fma_f32 v[196:197], v[68:69], v[196:197], v[72:73]
	v_pk_fma_f32 v[248:249], v[194:195], s[66:67], v[190:191] op_sel_hi:[1,0,1]
	v_pk_fma_f32 v[200:201], v[196:197], s[66:67], v[192:193] op_sel_hi:[1,0,1]
	v_mov_b32_e32 v238, v237
	v_cvt_pk_f16_f32 v190, v204, v205
	v_cvt_pk_f16_f32 v191, v202, v203
	v_cvt_pk_f16_f32 v192, v248, v249
	v_cvt_pk_f16_f32 v193, v200, v201
	v_lshl_add_u64 v[198:199], v[250:251], 1, s[92:93]
	s_and_b64 vcc, exec, s[38:39]
	s_mov_b64 s[36:37], -1
	global_store_dwordx4 v[198:199], v[190:193], off
	s_cbranch_vccnz .LBB0_885
	v_cvt_f32_f16_sdwa v195, v146 dst_sel:DWORD dst_unused:UNUSED_PAD src0_sel:WORD_1
	v_cvt_f32_f16_e32 v194, v146
	v_cvt_f32_f16_sdwa v197, v147 dst_sel:DWORD dst_unused:UNUSED_PAD src0_sel:WORD_1
	v_cvt_f32_f16_e32 v196, v147
	v_cvt_f32_f16_sdwa v191, v148 dst_sel:DWORD dst_unused:UNUSED_PAD src0_sel:WORD_1
	v_cvt_f32_f16_e32 v190, v148
	v_cvt_f32_f16_sdwa v193, v149 dst_sel:DWORD dst_unused:UNUSED_PAD src0_sel:WORD_1
	v_cvt_f32_f16_e32 v192, v149
	s_mov_b64 s[36:37], 0

;     __device__ __forceinline__ void operator()(const f32x4 (&acc)[2][2][4][2], const Unit& u, int wr, int wc, int fr, int fq) const {
;     ...
;                     if (st) { const f16x8 h = hv[m][bj]; yp[0] = (f32x4){(float)h[0], (float)h[1], (float)h[2], (float)h[3]}; yp[1] = (f32x4){(float)h[4], (float)h[5], (float)h[6], (float)h[7]}; }
;                     else { yp[0] = *(const f32x4*)(x0 + off + bj * 32); yp[1] = *(const f32x4*)(x0 + off + bj * 32 + 4); }
;                     f32x4 y[2];
; #pragma unroll
;                     for (int n = 0; n < 2; ++n) { const f32x4 x = (yp[n] - rmu[m]) * ra[m] * gv[bj][n] + bv[bj][n];
;                         y[n] = x * alpha + acc[ai][bj][m][n] * s;
;                         s1 += (y[n][0] + y[n][1]) + (y[n][2] + y[n][3]); s2 += (y[n][0] * y[n][0] + y[n][1] * y[n][1]) + (y[n][2] * y[n][2] + y[n][3] * y[n][3]); }
;                     u32x4 w; w.x = cvtpk_h(y[0][0], y[0][1]); w.y = cvtpk_h(y[0][2], y[0][3]); w.z = cvtpk_h(y[1][0], y[1][1]); w.w = cvtpk_h(y[1][2], y[1][3]);
;                     *(u32x4*)(yh + off + bj * 32) = w;
;                 }
;                 s1 += __shfl_xor(s1, 16); s1 += __shfl_xor(s1, 32); s2 += __shfl_xor(s2, 16); s2 += __shfl_xor(s2, 32);
;                 if (fq == 0) { atomicAdd(st_new + 2 * (size_t)row, s1); atomicAdd(st_new + 2 * (size_t)row + 1, s2); }
.LBB0_887:
	v_add_f32_e32 v233, v204, v205
	v_add_f32_e32 v236, v202, v203
	v_mul_f32_e32 v205, v205, v205
	v_mul_f32_e32 v203, v203, v203
	v_fmac_f32_e32 v205, v204, v204
	v_fmac_f32_e32 v203, v202, v202
	v_add_f32_e32 v202, v205, v203
	v_add_f32_e32 v203, v248, v249
	v_add_f32_e32 v204, v200, v201
	v_add_f32_e32 v203, v203, v204
	v_mul_f32_e32 v204, v249, v249
	v_mul_f32_e32 v201, v201, v201
	v_fmac_f32_e32 v204, v248, v248
	v_fmac_f32_e32 v201, v200, v200
	v_add_f32_e32 v200, v204, v201
	v_mov_b32_e32 v246, v244
	v_mov_b32_e32 v247, v244
	v_add_f32_e32 v202, v202, v200
	s_nop 0
	v_sub_f32_e32 v195, v195, v178
	v_sub_f32_e32 v194, v194, v178
	v_sub_f32_e32 v197, v197, v178
	v_sub_f32_e32 v196, v196, v178
	v_mov_b32_e32 v200, v244
	v_mov_b32_e32 v201, v244
	v_pk_mul_f32 v[196:197], v[200:201], v[196:197]
	v_pk_mul_f32 v[194:195], v[246:247], v[194:195]
	s_nop 0
	v_sub_f32_e32 v191, v191, v178
	v_sub_f32_e32 v190, v190, v178
	v_sub_f32_e32 v193, v193, v178
	v_sub_f32_e32 v192, v192, v178
	v_pk_fma_f32 v[194:195], v[54:55], v[194:195], v[62:63]
	v_pk_fma_f32 v[196:197], v[56:57], v[196:197], v[64:65]
	v_pk_mul_f32 v[192:193], v[200:201], v[192:193]
	v_pk_mul_f32 v[190:191], v[246:247], v[190:191]
	v_pk_fma_f32 v[188:189], v[196:197], s[66:67], v[188:189] op_sel_hi:[1,0,1]
	v_pk_fma_f32 v[186:187], v[194:195], s[66:67], v[186:187] op_sel_hi:[1,0,1]
	v_pk_fma_f32 v[190:191], v[42:43], v[190:191], v[46:47]
	v_pk_fma_f32 v[192:193], v[44:45], v[192:193], v[48:49]
	v_add_f32_e32 v194, v186, v187
	v_add_f32_e32 v195, v188, v189
	v_pk_fma_f32 v[192:193], v[192:193], s[66:67], v[184:185] op_sel_hi:[1,0,1]
	v_pk_fma_f32 v[190:191], v[190:191], s[66:67], v[182:183] op_sel_hi:[1,0,1]
	v_add_f32_e32 v233, v233, v236
	v_add_f32_e32 v194, v194, v195
	v_mul_f32_e32 v195, v187, v187
	v_mul_f32_e32 v196, v189, v189
	v_add_f32_e32 v178, v190, v191
	v_add_f32_e32 v182, v192, v193
	v_add_f32_e32 v233, 0, v233
	v_fmac_f32_e32 v195, v186, v186
	v_fmac_f32_e32 v196, v188, v188
	v_add_f32_e32 v178, v178, v182
	v_mul_f32_e32 v182, v191, v191
	v_mul_f32_e32 v183, v193, v193
	v_add_f32_e32 v203, v203, v233
	v_add_f32_e32 v195, v195, v196
	v_fmac_f32_e32 v182, v190, v190
	v_fmac_f32_e32 v183, v192, v192
	v_add_f32_e32 v194, v203, v194
	v_add_f32_e32 v195, v202, v195
	v_add_f32_e32 v182, v182, v183
	v_add_f32_e32 v178, v178, v194
	v_add_f32_e32 v184, v182, v195
	ds_bpermute_b32 v183, v207, v178
	ds_bpermute_b32 v185, v207, v184
	v_cvt_pk_f16_f32 v186, v186, v187
	v_cvt_pk_f16_f32 v187, v188, v189
	v_cvt_pk_f16_f32 v188, v190, v191
	s_waitcnt lgkmcnt(1)
	v_add_f32_e32 v178, v178, v183
	s_waitcnt lgkmcnt(0)
	v_add_f32_e32 v183, v184, v185
	ds_bpermute_b32 v182, v208, v178
	ds_bpermute_b32 v184, v208, v183
	v_cvt_pk_f16_f32 v189, v192, v193
	global_store_dwordx4 v[198:199], v[186:189], off offset:64
	s_and_saveexec_b64 s[36:37], s[40:41]
	s_cbranch_execz .LBB0_889
	v_lshl_add_u64 v[186:187], v[228:229], 3, s[86:87]
	s_waitcnt lgkmcnt(1)
	v_add_f32_e32 v178, v178, v182
	s_waitcnt lgkmcnt(0)
	v_add_f32_e32 v182, v183, v184
	global_atomic_add_f32 v[186:187], v178, off
	global_atomic_add_f32 v[186:187], v182, off offset:4

;     __device__ __forceinline__ void operator()(const f32x4 (&acc)[2][2][4][2], const Unit& u, int wr, int wc, int fr, int fq) const {
;     ...
;                     if (st) { const f16x8 h = hv[m][bj]; yp[0] = (f32x4){(float)h[0], (float)h[1], (float)h[2], (float)h[3]}; yp[1] = (f32x4){(float)h[4], (float)h[5], (float)h[6], (float)h[7]}; }
;                     else { yp[0] = *(const f32x4*)(x0 + off + bj * 32); yp[1] = *(const f32x4*)(x0 + off + bj * 32 + 4); }
;                     f32x4 y[2];
; #pragma unroll
;                     for (int n = 0; n < 2; ++n) { const f32x4 x = (yp[n] - rmu[m]) * ra[m] * gv[bj][n] + bv[bj][n];
;                         y[n] = x * alpha + acc[ai][bj][m][n] * s;
;                         s1 += (y[n][0] + y[n][1]) + (y[n][2] + y[n][3]); s2 += (y[n][0] * y[n][0] + y[n][1] * y[n][1]) + (y[n][2] * y[n][2] + y[n][3] * y[n][3]); }
;                     u32x4 w; w.x = cvtpk_h(y[0][0], y[0][1]); w.y = cvtpk_h(y[0][2], y[0][3]); w.z = cvtpk_h(y[1][0], y[1][1]); w.w = cvtpk_h(y[1][2], y[1][3]);
;                     *(u32x4*)(yh + off + bj * 32) = w;
.LBB0_893:
	s_nop 0
	v_sub_f32_e32 v187, v187, v179
	v_sub_f32_e32 v186, v186, v179
	v_sub_f32_e32 v189, v189, v179
	v_sub_f32_e32 v188, v188, v179
	v_pk_mul_f32 v[188:189], v[244:245], v[188:189] op_sel:[1,0]
	v_pk_mul_f32 v[186:187], v[244:245], v[186:187] op_sel:[1,0]
	s_and_b64 vcc, exec, s[38:39]
	v_pk_fma_f32 v[192:193], v[74:75], v[186:187], v[78:79]
	v_pk_fma_f32 v[186:187], v[76:77], v[188:189], v[80:81]
	v_pk_fma_f32 v[188:189], v[192:193], s[66:67], v[174:175] op_sel_hi:[1,0,1]
	v_pk_fma_f32 v[186:187], v[186:187], s[66:67], v[176:177] op_sel_hi:[1,0,1]
	s_nop 0
	v_sub_f32_e32 v175, v183, v179
	s_waitcnt lgkmcnt(1)
	v_sub_f32_e32 v174, v182, v179
	v_sub_f32_e32 v177, v185, v179
	s_waitcnt lgkmcnt(0)
	v_sub_f32_e32 v176, v184, v179
	v_pk_mul_f32 v[176:177], v[244:245], v[176:177] op_sel:[1,0]
	v_pk_mul_f32 v[174:175], v[244:245], v[174:175] op_sel:[1,0]
	v_pk_fma_f32 v[176:177], v[68:69], v[176:177], v[72:73]
	v_pk_fma_f32 v[174:175], v[66:67], v[174:175], v[70:71]
	v_pk_fma_f32 v[184:185], v[176:177], s[66:67], v[172:173] op_sel_hi:[1,0,1]
	v_pk_fma_f32 v[192:193], v[174:175], s[66:67], v[170:171] op_sel_hi:[1,0,1]
	v_cvt_pk_f16_f32 v170, v188, v189
	v_cvt_pk_f16_f32 v171, v186, v187
	v_cvt_pk_f16_f32 v172, v192, v193
	v_cvt_pk_f16_f32 v173, v184, v185
	v_lshl_add_u64 v[182:183], v[194:195], 1, s[92:93]
	s_mov_b64 s[36:37], -1
	global_store_dwordx4 v[182:183], v[170:173], off
	s_cbranch_vccnz .LBB0_895
	v_cvt_f32_f16_sdwa v175, v130 dst_sel:DWORD dst_unused:UNUSED_PAD src0_sel:WORD_1
	v_cvt_f32_f16_e32 v174, v130
	v_cvt_f32_f16_sdwa v177, v131 dst_sel:DWORD dst_unused:UNUSED_PAD src0_sel:WORD_1
	v_cvt_f32_f16_e32 v176, v131
	v_cvt_f32_f16_sdwa v171, v132 dst_sel:DWORD dst_unused:UNUSED_PAD src0_sel:WORD_1
	v_cvt_f32_f16_e32 v170, v132
	v_cvt_f32_f16_sdwa v173, v133 dst_sel:DWORD dst_unused:UNUSED_PAD src0_sel:WORD_1
	v_cvt_f32_f16_e32 v172, v133
	s_mov_b64 s[36:37], 0

;     __device__ __forceinline__ void operator()(const f32x4 (&acc)[2][2][4][2], const Unit& u, int wr, int wc, int fr, int fq) const {
;     ...
;                     if (st) { const f16x8 h = hv[m][bj]; yp[0] = (f32x4){(float)h[0], (float)h[1], (float)h[2], (float)h[3]}; yp[1] = (f32x4){(float)h[4], (float)h[5], (float)h[6], (float)h[7]}; }
;                     else { yp[0] = *(const f32x4*)(x0 + off + bj * 32); yp[1] = *(const f32x4*)(x0 + off + bj * 32 + 4); }
;                     f32x4 y[2];
; #pragma unroll
;                     for (int n = 0; n < 2; ++n) { const f32x4 x = (yp[n] - rmu[m]) * ra[m] * gv[bj][n] + bv[bj][n];
;                         y[n] = x * alpha + acc[ai][bj][m][n] * s;
;                         s1 += (y[n][0] + y[n][1]) + (y[n][2] + y[n][3]); s2 += (y[n][0] * y[n][0] + y[n][1] * y[n][1]) + (y[n][2] * y[n][2] + y[n][3] * y[n][3]); }
;                     u32x4 w; w.x = cvtpk_h(y[0][0], y[0][1]); w.y = cvtpk_h(y[0][2], y[0][3]); w.z = cvtpk_h(y[1][0], y[1][1]); w.w = cvtpk_h(y[1][2], y[1][3]);
;                     *(u32x4*)(yh + off + bj * 32) = w;
;                 }
;                 s1 += __shfl_xor(s1, 16); s1 += __shfl_xor(s1, 32); s2 += __shfl_xor(s2, 16); s2 += __shfl_xor(s2, 32);
;                 if (fq == 0) { atomicAdd(st_new + 2 * (size_t)row, s1); atomicAdd(st_new + 2 * (size_t)row + 1, s2); }
.LBB0_897:
	v_mov_b32_e32 v243, v245
	v_add_f32_e32 v178, v188, v189
	v_add_f32_e32 v190, v186, v187
	v_mul_f32_e32 v189, v189, v189
	v_mul_f32_e32 v187, v187, v187
	s_nop 0
	v_sub_f32_e32 v175, v175, v179
	v_sub_f32_e32 v174, v174, v179
	v_sub_f32_e32 v177, v177, v179
	v_sub_f32_e32 v176, v176, v179
	v_mov_b32_e32 v244, v242
	v_fmac_f32_e32 v189, v188, v188
	v_fmac_f32_e32 v187, v186, v186
	v_pk_mul_f32 v[176:177], v[244:245], v[176:177]
	v_pk_mul_f32 v[174:175], v[242:243], v[174:175]
	s_nop 0
	v_sub_f32_e32 v171, v171, v179
	v_sub_f32_e32 v170, v170, v179
	v_sub_f32_e32 v173, v173, v179
	v_sub_f32_e32 v172, v172, v179
	v_add_f32_e32 v178, v178, v190
	v_add_f32_e32 v186, v189, v187
	v_add_f32_e32 v187, v192, v193
	v_add_f32_e32 v188, v184, v185
	v_pk_fma_f32 v[174:175], v[54:55], v[174:175], v[62:63]
	v_pk_fma_f32 v[176:177], v[56:57], v[176:177], v[64:65]
	v_pk_mul_f32 v[172:173], v[244:245], v[172:173]
	v_pk_mul_f32 v[170:171], v[242:243], v[170:171]
	v_add_f32_e32 v178, 0, v178
	v_add_f32_e32 v187, v187, v188
	v_pk_fma_f32 v[168:169], v[176:177], s[66:67], v[168:169] op_sel_hi:[1,0,1]
	v_pk_fma_f32 v[166:167], v[174:175], s[66:67], v[166:167] op_sel_hi:[1,0,1]
	v_pk_fma_f32 v[170:171], v[42:43], v[170:171], v[46:47]
	v_pk_fma_f32 v[172:173], v[44:45], v[172:173], v[48:49]
	v_add_f32_e32 v178, v187, v178
	v_mul_f32_e32 v187, v193, v193
	v_mul_f32_e32 v185, v185, v185
	v_add_f32_e32 v174, v166, v167
	v_add_f32_e32 v175, v168, v169
	v_pk_fma_f32 v[172:173], v[172:173], s[66:67], v[164:165] op_sel_hi:[1,0,1]
	v_pk_fma_f32 v[170:171], v[170:171], s[66:67], v[162:163] op_sel_hi:[1,0,1]
	v_fmac_f32_e32 v187, v192, v192
	v_fmac_f32_e32 v185, v184, v184
	v_add_f32_e32 v174, v174, v175
	v_mul_f32_e32 v175, v167, v167
	v_mul_f32_e32 v176, v169, v169
	v_add_f32_e32 v162, v170, v171
	v_add_f32_e32 v163, v172, v173
	v_add_f32_e32 v184, v187, v185
	v_fmac_f32_e32 v175, v166, v166
	v_fmac_f32_e32 v176, v168, v168
	v_add_f32_e32 v162, v162, v163
	v_mul_f32_e32 v163, v171, v171
	v_mul_f32_e32 v164, v173, v173
	v_add_f32_e32 v184, v186, v184
	v_add_f32_e32 v175, v175, v176
	v_fmac_f32_e32 v163, v170, v170
	v_fmac_f32_e32 v164, v172, v172
	v_add_f32_e32 v174, v178, v174
	v_add_f32_e32 v175, v184, v175
	v_add_f32_e32 v163, v163, v164
	v_add_f32_e32 v162, v162, v174
	v_add_f32_e32 v165, v163, v175
	ds_bpermute_b32 v164, v207, v162
	ds_bpermute_b32 v174, v207, v165
	v_cvt_pk_f16_f32 v166, v166, v167
	v_cvt_pk_f16_f32 v167, v168, v169
	v_cvt_pk_f16_f32 v168, v170, v171
	s_waitcnt lgkmcnt(1)
	v_add_f32_e32 v162, v162, v164
	s_waitcnt lgkmcnt(0)
	v_add_f32_e32 v164, v165, v174
	ds_bpermute_b32 v163, v208, v162
	ds_bpermute_b32 v165, v208, v164
	v_cvt_pk_f16_f32 v169, v172, v173
	global_store_dwordx4 v[182:183], v[166:169], off offset:64
	s_and_saveexec_b64 s[36:37], s[40:41]
	s_cbranch_execz .LBB0_899
	v_lshl_add_u64 v[166:167], v[240:241], 3, s[86:87]
	s_waitcnt lgkmcnt(1)
	v_add_f32_e32 v162, v162, v163
	s_waitcnt lgkmcnt(0)
	v_add_f32_e32 v163, v164, v165
	global_atomic_add_f32 v[166:167], v162, off
	global_atomic_add_f32 v[166:167], v163, off offset:4

;     __device__ __forceinline__ void operator()(const f32x4 (&acc)[2][2][4][2], const Unit& u, int wr, int wc, int fr, int fq) const {
;     ...
;                     if (st) { const f16x8 h = hv[m][bj]; yp[0] = (f32x4){(float)h[0], (float)h[1], (float)h[2], (float)h[3]}; yp[1] = (f32x4){(float)h[4], (float)h[5], (float)h[6], (float)h[7]}; }
;                     else { yp[0] = *(const f32x4*)(x0 + off + bj * 32); yp[1] = *(const f32x4*)(x0 + off + bj * 32 + 4); }
;                     f32x4 y[2];
; #pragma unroll
;                     for (int n = 0; n < 2; ++n) { const f32x4 x = (yp[n] - rmu[m]) * ra[m] * gv[bj][n] + bv[bj][n];
;                         y[n] = x * alpha + acc[ai][bj][m][n] * s;
;                         s1 += (y[n][0] + y[n][1]) + (y[n][2] + y[n][3]); s2 += (y[n][0] * y[n][0] + y[n][1] * y[n][1]) + (y[n][2] * y[n][2] + y[n][3] * y[n][3]); }
;                     u32x4 w; w.x = cvtpk_h(y[0][0], y[0][1]); w.y = cvtpk_h(y[0][2], y[0][3]); w.z = cvtpk_h(y[1][0], y[1][1]); w.w = cvtpk_h(y[1][2], y[1][3]);
;                     *(u32x4*)(yh + off + bj * 32) = w;
.LBB0_903:
	s_nop 0
	v_sub_f32_e32 v167, v167, v180
	v_sub_f32_e32 v166, v166, v180
	v_sub_f32_e32 v169, v169, v180
	v_sub_f32_e32 v168, v168, v180
	v_pk_mul_f32 v[168:169], v[238:239], v[168:169] op_sel_hi:[0,1]
	v_pk_mul_f32 v[166:167], v[238:239], v[166:167] op_sel_hi:[0,1]
	v_pk_fma_f32 v[172:173], v[74:75], v[166:167], v[78:79]
	v_pk_fma_f32 v[166:167], v[76:77], v[168:169], v[80:81]
	v_pk_fma_f32 v[168:169], v[172:173], s[66:67], v[154:155] op_sel_hi:[1,0,1]
	v_pk_fma_f32 v[166:167], v[166:167], s[66:67], v[156:157] op_sel_hi:[1,0,1]
	s_waitcnt lgkmcnt(1)
	v_sub_f32_e32 v155, v163, v180
	v_sub_f32_e32 v154, v162, v180
	s_waitcnt lgkmcnt(0)
	v_sub_f32_e32 v157, v165, v180
	v_sub_f32_e32 v156, v164, v180
	v_pk_mul_f32 v[156:157], v[238:239], v[156:157] op_sel_hi:[0,1]
	v_pk_mul_f32 v[154:155], v[238:239], v[154:155] op_sel_hi:[0,1]
	v_pk_fma_f32 v[154:155], v[66:67], v[154:155], v[70:71]
	v_pk_fma_f32 v[156:157], v[68:69], v[156:157], v[72:73]
	v_pk_fma_f32 v[172:173], v[154:155], s[66:67], v[150:151] op_sel_hi:[1,0,1]
	v_pk_fma_f32 v[164:165], v[156:157], s[66:67], v[152:153] op_sel_hi:[1,0,1]
	v_cvt_pk_f16_f32 v150, v168, v169
	v_cvt_pk_f16_f32 v151, v166, v167
	v_cvt_pk_f16_f32 v152, v172, v173
	v_cvt_pk_f16_f32 v153, v164, v165
	v_lshl_add_u64 v[162:163], v[174:175], 1, s[92:93]
	s_and_b64 vcc, exec, s[38:39]
	s_mov_b64 s[36:37], -1
	global_store_dwordx4 v[162:163], v[150:153], off
	s_cbranch_vccnz .LBB0_905
	v_cvt_f32_f16_sdwa v155, v106 dst_sel:DWORD dst_unused:UNUSED_PAD src0_sel:WORD_1
	v_cvt_f32_f16_e32 v154, v106
	v_cvt_f32_f16_sdwa v157, v107 dst_sel:DWORD dst_unused:UNUSED_PAD src0_sel:WORD_1
	v_cvt_f32_f16_e32 v156, v107
	v_cvt_f32_f16_sdwa v151, v108 dst_sel:DWORD dst_unused:UNUSED_PAD src0_sel:WORD_1
	v_cvt_f32_f16_e32 v150, v108
	v_cvt_f32_f16_sdwa v153, v109 dst_sel:DWORD dst_unused:UNUSED_PAD src0_sel:WORD_1
	v_cvt_f32_f16_e32 v152, v109
	s_mov_b64 s[36:37], 0

;     __device__ __forceinline__ void operator()(const f32x4 (&acc)[2][2][4][2], const Unit& u, int wr, int wc, int fr, int fq) const {
;     ...
;                     if (st) { const f16x8 h = hv[m][bj]; yp[0] = (f32x4){(float)h[0], (float)h[1], (float)h[2], (float)h[3]}; yp[1] = (f32x4){(float)h[4], (float)h[5], (float)h[6], (float)h[7]}; }
;                     else { yp[0] = *(const f32x4*)(x0 + off + bj * 32); yp[1] = *(const f32x4*)(x0 + off + bj * 32 + 4); }
;                     f32x4 y[2];
; #pragma unroll
;                     for (int n = 0; n < 2; ++n) { const f32x4 x = (yp[n] - rmu[m]) * ra[m] * gv[bj][n] + bv[bj][n];
;                         y[n] = x * alpha + acc[ai][bj][m][n] * s;
;                         s1 += (y[n][0] + y[n][1]) + (y[n][2] + y[n][3]); s2 += (y[n][0] * y[n][0] + y[n][1] * y[n][1]) + (y[n][2] * y[n][2] + y[n][3] * y[n][3]); }
;                     u32x4 w; w.x = cvtpk_h(y[0][0], y[0][1]); w.y = cvtpk_h(y[0][2], y[0][3]); w.z = cvtpk_h(y[1][0], y[1][1]); w.w = cvtpk_h(y[1][2], y[1][3]);
;                     *(u32x4*)(yh + off + bj * 32) = w;
;                 }
;                 s1 += __shfl_xor(s1, 16); s1 += __shfl_xor(s1, 32); s2 += __shfl_xor(s2, 16); s2 += __shfl_xor(s2, 32);
;                 if (fq == 0) { atomicAdd(st_new + 2 * (size_t)row, s1); atomicAdd(st_new + 2 * (size_t)row + 1, s2); }
.LBB0_907:
	v_mov_b32_e32 v236, v238
	s_nop 0
	v_sub_f32_e32 v155, v155, v180
	v_sub_f32_e32 v154, v154, v180
	v_sub_f32_e32 v157, v157, v180
	v_sub_f32_e32 v156, v156, v180
	v_mov_b32_e32 v239, v237
	v_add_f32_e32 v170, v168, v169
	v_add_f32_e32 v171, v166, v167
	v_mul_f32_e32 v169, v169, v169
	v_mul_f32_e32 v167, v167, v167
	v_pk_mul_f32 v[156:157], v[238:239], v[156:157]
	v_pk_mul_f32 v[154:155], v[236:237], v[154:155]
	s_nop 0
	v_sub_f32_e32 v151, v151, v180
	v_sub_f32_e32 v150, v150, v180
	v_sub_f32_e32 v153, v153, v180
	v_sub_f32_e32 v152, v152, v180
	v_fmac_f32_e32 v169, v168, v168
	v_fmac_f32_e32 v167, v166, v166
	v_pk_fma_f32 v[154:155], v[54:55], v[154:155], v[62:63]
	v_pk_fma_f32 v[156:157], v[56:57], v[156:157], v[64:65]
	v_pk_mul_f32 v[152:153], v[238:239], v[152:153]
	v_pk_mul_f32 v[150:151], v[236:237], v[150:151]
	v_add_f32_e32 v166, v169, v167
	v_add_f32_e32 v167, v172, v173
	v_add_f32_e32 v168, v164, v165
	v_pk_fma_f32 v[144:145], v[156:157], s[66:67], v[144:145] op_sel_hi:[1,0,1]
	v_pk_fma_f32 v[142:143], v[154:155], s[66:67], v[142:143] op_sel_hi:[1,0,1]
	v_pk_fma_f32 v[150:151], v[42:43], v[150:151], v[46:47]
	v_pk_fma_f32 v[152:153], v[44:45], v[152:153], v[48:49]
	v_add_f32_e32 v167, v167, v168
	v_mul_f32_e32 v168, v173, v173
	v_mul_f32_e32 v165, v165, v165
	v_add_f32_e32 v154, v142, v143
	v_add_f32_e32 v155, v144, v145
	v_pk_fma_f32 v[152:153], v[152:153], s[66:67], v[136:137] op_sel_hi:[1,0,1]
	v_pk_fma_f32 v[150:151], v[150:151], s[66:67], v[134:135] op_sel_hi:[1,0,1]
	v_add_f32_e32 v170, v170, v171
	v_fmac_f32_e32 v168, v172, v172
	v_fmac_f32_e32 v165, v164, v164
	v_add_f32_e32 v154, v154, v155
	v_mul_f32_e32 v155, v143, v143
	v_mul_f32_e32 v156, v145, v145
	v_add_f32_e32 v134, v150, v151
	v_add_f32_e32 v135, v152, v153
	v_add_f32_e32 v170, 0, v170
	v_add_f32_e32 v164, v168, v165
	v_fmac_f32_e32 v155, v142, v142
	v_fmac_f32_e32 v156, v144, v144
	v_add_f32_e32 v134, v134, v135
	v_mul_f32_e32 v135, v151, v151
	v_mul_f32_e32 v136, v153, v153
	v_add_f32_e32 v167, v167, v170
	v_add_f32_e32 v164, v166, v164
	v_add_f32_e32 v155, v155, v156
	v_fmac_f32_e32 v135, v150, v150
	v_fmac_f32_e32 v136, v152, v152
	v_add_f32_e32 v154, v167, v154
	v_add_f32_e32 v155, v164, v155
	v_add_f32_e32 v135, v135, v136
	v_add_f32_e32 v134, v134, v154
	v_add_f32_e32 v137, v135, v155
	ds_bpermute_b32 v136, v207, v134
	ds_bpermute_b32 v154, v207, v137
	v_cvt_pk_f16_f32 v142, v142, v143
	v_cvt_pk_f16_f32 v143, v144, v145
	v_cvt_pk_f16_f32 v144, v150, v151
	s_waitcnt lgkmcnt(1)
	v_add_f32_e32 v134, v134, v136
	s_waitcnt lgkmcnt(0)
	v_add_f32_e32 v136, v137, v154
	ds_bpermute_b32 v135, v208, v134
	ds_bpermute_b32 v137, v208, v136
	v_cvt_pk_f16_f32 v145, v152, v153
	global_store_dwordx4 v[162:163], v[142:145], off offset:64
	s_and_saveexec_b64 s[36:37], s[40:41]
	s_cbranch_execz .LBB0_909
	v_lshl_add_u64 v[142:143], v[234:235], 3, s[86:87]
	s_waitcnt lgkmcnt(1)
	v_add_f32_e32 v134, v134, v135
	s_waitcnt lgkmcnt(0)
	v_add_f32_e32 v135, v136, v137
	global_atomic_add_f32 v[142:143], v134, off
	global_atomic_add_f32 v[142:143], v135, off offset:4

;     __device__ __forceinline__ void operator()(const f32x4 (&acc)[2][2][4][2], const Unit& u, int wr, int wc, int fr, int fq) const {
;     ...
;                     if (st) { const f16x8 h = hv[m][bj]; yp[0] = (f32x4){(float)h[0], (float)h[1], (float)h[2], (float)h[3]}; yp[1] = (f32x4){(float)h[4], (float)h[5], (float)h[6], (float)h[7]}; }
;                     else { yp[0] = *(const f32x4*)(x0 + off + bj * 32); yp[1] = *(const f32x4*)(x0 + off + bj * 32 + 4); }
;                     f32x4 y[2];
; #pragma unroll
;                     for (int n = 0; n < 2; ++n) { const f32x4 x = (yp[n] - rmu[m]) * ra[m] * gv[bj][n] + bv[bj][n];
;                         y[n] = x * alpha + acc[ai][bj][m][n] * s;
;                         s1 += (y[n][0] + y[n][1]) + (y[n][2] + y[n][3]); s2 += (y[n][0] * y[n][0] + y[n][1] * y[n][1]) + (y[n][2] * y[n][2] + y[n][3] * y[n][3]); }
;                     u32x4 w; w.x = cvtpk_h(y[0][0], y[0][1]); w.y = cvtpk_h(y[0][2], y[0][3]); w.z = cvtpk_h(y[1][0], y[1][1]); w.w = cvtpk_h(y[1][2], y[1][3]);
;                     *(u32x4*)(yh + off + bj * 32) = w;
.LBB0_913:
	s_nop 0
	v_sub_f32_e32 v143, v143, v181
	v_sub_f32_e32 v142, v142, v181
	v_sub_f32_e32 v145, v145, v181
	v_sub_f32_e32 v144, v144, v181
	v_pk_mul_f32 v[144:145], v[232:233], v[144:145] op_sel_hi:[0,1]
	v_pk_mul_f32 v[142:143], v[232:233], v[142:143] op_sel_hi:[0,1]
	v_pk_fma_f32 v[152:153], v[74:75], v[142:143], v[78:79]
	v_pk_fma_f32 v[142:143], v[76:77], v[144:145], v[80:81]
	v_pk_fma_f32 v[144:145], v[152:153], s[66:67], v[126:127] op_sel_hi:[1,0,1]
	v_pk_fma_f32 v[142:143], v[142:143], s[66:67], v[128:129] op_sel_hi:[1,0,1]
	s_waitcnt lgkmcnt(1)
	v_sub_f32_e32 v127, v135, v181
	v_sub_f32_e32 v126, v134, v181
	s_waitcnt lgkmcnt(0)
	v_sub_f32_e32 v129, v137, v181
	v_sub_f32_e32 v128, v136, v181
	v_pk_mul_f32 v[128:129], v[232:233], v[128:129] op_sel_hi:[0,1]
	v_pk_mul_f32 v[126:127], v[232:233], v[126:127] op_sel_hi:[0,1]
	v_pk_fma_f32 v[126:127], v[66:67], v[126:127], v[70:71]
	v_pk_fma_f32 v[128:129], v[68:69], v[128:129], v[72:73]
	v_pk_fma_f32 v[152:153], v[126:127], s[66:67], v[122:123] op_sel_hi:[1,0,1]
	v_pk_fma_f32 v[136:137], v[128:129], s[66:67], v[124:125] op_sel_hi:[1,0,1]
	v_cvt_pk_f16_f32 v122, v144, v145
	v_cvt_pk_f16_f32 v123, v142, v143
	v_cvt_pk_f16_f32 v124, v152, v153
	v_cvt_pk_f16_f32 v125, v136, v137
	v_lshl_add_u64 v[134:135], v[154:155], 1, s[92:93]
	s_and_b64 vcc, exec, s[38:39]
	s_mov_b64 s[36:37], -1
	global_store_dwordx4 v[134:135], v[122:125], off
	s_cbranch_vccnz .LBB0_915
	v_cvt_f32_f16_sdwa v127, v98 dst_sel:DWORD dst_unused:UNUSED_PAD src0_sel:WORD_1
	v_cvt_f32_f16_e32 v126, v98
	v_cvt_f32_f16_sdwa v129, v99 dst_sel:DWORD dst_unused:UNUSED_PAD src0_sel:WORD_1
	v_cvt_f32_f16_e32 v128, v99
	v_cvt_f32_f16_sdwa v123, v100 dst_sel:DWORD dst_unused:UNUSED_PAD src0_sel:WORD_1
	v_cvt_f32_f16_e32 v122, v100
	v_cvt_f32_f16_sdwa v125, v101 dst_sel:DWORD dst_unused:UNUSED_PAD src0_sel:WORD_1
	v_cvt_f32_f16_e32 v124, v101
	s_mov_b64 s[36:37], 0

;     __device__ __forceinline__ void operator()(const f32x4 (&acc)[2][2][4][2], const Unit& u, int wr, int wc, int fr, int fq) const {
;     ...
;                     if (st) { const f16x8 h = hv[m][bj]; yp[0] = (f32x4){(float)h[0], (float)h[1], (float)h[2], (float)h[3]}; yp[1] = (f32x4){(float)h[4], (float)h[5], (float)h[6], (float)h[7]}; }
;                     else { yp[0] = *(const f32x4*)(x0 + off + bj * 32); yp[1] = *(const f32x4*)(x0 + off + bj * 32 + 4); }
;                     f32x4 y[2];
; #pragma unroll
;                     for (int n = 0; n < 2; ++n) { const f32x4 x = (yp[n] - rmu[m]) * ra[m] * gv[bj][n] + bv[bj][n];
;                         y[n] = x * alpha + acc[ai][bj][m][n] * s;
;                         s1 += (y[n][0] + y[n][1]) + (y[n][2] + y[n][3]); s2 += (y[n][0] * y[n][0] + y[n][1] * y[n][1]) + (y[n][2] * y[n][2] + y[n][3] * y[n][3]); }
;                     u32x4 w; w.x = cvtpk_h(y[0][0], y[0][1]); w.y = cvtpk_h(y[0][2], y[0][3]); w.z = cvtpk_h(y[1][0], y[1][1]); w.w = cvtpk_h(y[1][2], y[1][3]);
;                     *(u32x4*)(yh + off + bj * 32) = w;
;                 }
;                 s1 += __shfl_xor(s1, 16); s1 += __shfl_xor(s1, 32); s2 += __shfl_xor(s2, 16); s2 += __shfl_xor(s2, 32);
;                 if (fq == 0) { atomicAdd(st_new + 2 * (size_t)row, s1); atomicAdd(st_new + 2 * (size_t)row + 1, s2); }
.LBB0_917:
	v_add_f32_e32 v150, v144, v145
	v_add_f32_e32 v151, v142, v143
	v_mul_f32_e32 v145, v145, v145
	v_mul_f32_e32 v143, v143, v143
	v_fmac_f32_e32 v145, v144, v144
	v_fmac_f32_e32 v143, v142, v142
	v_add_f32_e32 v142, v145, v143
	v_add_f32_e32 v143, v152, v153
	v_add_f32_e32 v144, v136, v137
	v_add_f32_e32 v143, v143, v144
	v_mul_f32_e32 v144, v153, v153
	v_mul_f32_e32 v137, v137, v137
	v_fmac_f32_e32 v144, v152, v152
	v_fmac_f32_e32 v137, v136, v136
	v_add_f32_e32 v136, v144, v137
	v_mov_b32_e32 v233, v232
	v_add_f32_e32 v142, v142, v136
	s_nop 0
	v_sub_f32_e32 v127, v127, v181
	v_sub_f32_e32 v126, v126, v181
	v_sub_f32_e32 v129, v129, v181
	v_sub_f32_e32 v128, v128, v181
	v_mov_b32_e32 v136, v232
	v_mov_b32_e32 v137, v232
	v_pk_mul_f32 v[128:129], v[136:137], v[128:129]
	v_pk_mul_f32 v[126:127], v[232:233], v[126:127]
	s_nop 0
	v_sub_f32_e32 v123, v123, v181
	v_sub_f32_e32 v122, v122, v181
	v_sub_f32_e32 v125, v125, v181
	v_sub_f32_e32 v124, v124, v181
	v_pk_fma_f32 v[126:127], v[54:55], v[126:127], v[62:63]
	v_pk_fma_f32 v[128:129], v[56:57], v[128:129], v[64:65]
	v_pk_mul_f32 v[124:125], v[136:137], v[124:125]
	v_pk_mul_f32 v[122:123], v[232:233], v[122:123]
	v_pk_fma_f32 v[116:117], v[128:129], s[66:67], v[116:117] op_sel_hi:[1,0,1]
	v_pk_fma_f32 v[114:115], v[126:127], s[66:67], v[114:115] op_sel_hi:[1,0,1]
	v_pk_fma_f32 v[122:123], v[42:43], v[122:123], v[46:47]
	v_pk_fma_f32 v[124:125], v[44:45], v[124:125], v[48:49]
	v_add_f32_e32 v126, v114, v115
	v_add_f32_e32 v127, v116, v117
	v_pk_fma_f32 v[124:125], v[124:125], s[66:67], v[112:113] op_sel_hi:[1,0,1]
	v_pk_fma_f32 v[122:123], v[122:123], s[66:67], v[110:111] op_sel_hi:[1,0,1]
	v_add_f32_e32 v150, v150, v151
	v_add_f32_e32 v126, v126, v127
	v_mul_f32_e32 v127, v115, v115
	v_mul_f32_e32 v128, v117, v117
	v_add_f32_e32 v110, v122, v123
	v_add_f32_e32 v111, v124, v125
	v_add_f32_e32 v150, 0, v150
	v_fmac_f32_e32 v127, v114, v114
	v_fmac_f32_e32 v128, v116, v116
	v_add_f32_e32 v110, v110, v111
	v_mul_f32_e32 v111, v123, v123
	v_mul_f32_e32 v112, v125, v125
	v_add_f32_e32 v143, v143, v150
	v_add_f32_e32 v127, v127, v128
	v_fmac_f32_e32 v111, v122, v122
	v_fmac_f32_e32 v112, v124, v124
	v_add_f32_e32 v126, v143, v126
	v_add_f32_e32 v127, v142, v127
	v_add_f32_e32 v111, v111, v112
	v_add_f32_e32 v110, v110, v126
	v_add_f32_e32 v113, v111, v127
	ds_bpermute_b32 v112, v207, v110
	ds_bpermute_b32 v126, v207, v113
	v_cvt_pk_f16_f32 v114, v114, v115
	v_cvt_pk_f16_f32 v115, v116, v117
	v_cvt_pk_f16_f32 v116, v122, v123
	s_waitcnt lgkmcnt(1)
	v_add_f32_e32 v110, v110, v112
	s_waitcnt lgkmcnt(0)
	v_add_f32_e32 v112, v113, v126
	ds_bpermute_b32 v111, v208, v110
	ds_bpermute_b32 v113, v208, v112
	v_cvt_pk_f16_f32 v117, v124, v125
	global_store_dwordx4 v[134:135], v[114:117], off offset:64
	s_and_saveexec_b64 s[36:37], s[40:41]
	s_cbranch_execz .LBB0_919
	v_lshl_add_u64 v[114:115], v[230:231], 3, s[86:87]
	s_waitcnt lgkmcnt(1)
	v_add_f32_e32 v110, v110, v111
	s_waitcnt lgkmcnt(0)
	v_add_f32_e32 v111, v112, v113
	global_atomic_add_f32 v[114:115], v110, off
	global_atomic_add_f32 v[114:115], v111, off offset:4

;     __device__ __forceinline__ void operator()(const f32x4 (&acc)[2][2][4][2], const Unit& u, int wr, int wc, int fr, int fq) const {
;     ...
;                 if (st) {
;                     const f32x2v sv = *(const f32x2v*)(st + 2 * (size_t)row); rmu[m] = sv.x * (1.0f / 1024.0f); ra[m] = rsqrtf(sv.y * (1.0f / 1024.0f) - rmu[m] * rmu[m] + 1e-5f);
;                     hv[m][0] = *(const f16x8*)(yh + off); hv[m][1] = *(const f16x8*)(yh + off + 32);
.LBB0_928:
	v_lshl_add_u64 v[98:99], v[116:117], 3, s[80:81]
	s_waitcnt lgkmcnt(1)
	global_load_dwordx2 v[110:111], v[98:99], off
	v_lshlrev_b64 v[98:99], 11, v[116:117]
	v_lshl_add_u64 v[98:99], v[226:227], 0, v[98:99]
	global_load_dwordx4 v[102:105], v[98:99], off
	s_nop 0
	global_load_dwordx4 v[98:101], v[98:99], off offset:64
	s_waitcnt vmcnt(0)
	v_pk_mul_f32 v[110:111], v[110:111], s[64:65] op_sel_hi:[1,0]
	s_nop 0
	v_fma_f32 v111, -v110, v110, v111
	v_add_f32_e32 v111, 0x3727c5ac, v111
	v_mul_f32_e32 v112, 0x4b800000, v111
	v_cmp_gt_f32_e32 vcc, s29, v111
	s_nop 1
	v_cndmask_b32_e32 v111, v111, v112, vcc
	v_rsq_f32_e32 v111, v111
	s_nop 0
	v_mul_f32_e32 v112, 0x45800000, v111
	v_cndmask_b32_e32 v127, v111, v112, vcc

;     __device__ __forceinline__ void operator()(const f32x4 (&acc)[2][2][4][2], const Unit& u, int wr, int wc, int fr, int fq) const {
;     ...
;                     if (st) { const f16x8 h = hv[m][bj]; yp[0] = (f32x4){(float)h[0], (float)h[1], (float)h[2], (float)h[3]}; yp[1] = (f32x4){(float)h[4], (float)h[5], (float)h[6], (float)h[7]}; }
;                     else { yp[0] = *(const f32x4*)(x0 + off + bj * 32); yp[1] = *(const f32x4*)(x0 + off + bj * 32 + 4); }
;                     f32x4 y[2];
; #pragma unroll
;                     for (int n = 0; n < 2; ++n) { const f32x4 x = (yp[n] - rmu[m]) * ra[m] * gv[bj][n] + bv[bj][n];
;                         y[n] = x * alpha + acc[ai][bj][m][n] * s;
;                         s1 += (y[n][0] + y[n][1]) + (y[n][2] + y[n][3]); s2 += (y[n][0] * y[n][0] + y[n][1] * y[n][1]) + (y[n][2] * y[n][2] + y[n][3] * y[n][3]); }
;                     u32x4 w; w.x = cvtpk_h(y[0][0], y[0][1]); w.y = cvtpk_h(y[0][2], y[0][3]); w.z = cvtpk_h(y[1][0], y[1][1]); w.w = cvtpk_h(y[1][2], y[1][3]);
;                     *(u32x4*)(yh + off + bj * 32) = w;
.LBB0_933:
	s_nop 0
	v_sub_f32_e32 v123, v123, v152
	v_sub_f32_e32 v122, v122, v152
	v_sub_f32_e32 v125, v125, v152
	v_sub_f32_e32 v124, v124, v152
	v_pk_mul_f32 v[124:125], v[144:145], v[124:125] op_sel_hi:[0,1]
	v_pk_mul_f32 v[122:123], v[144:145], v[122:123] op_sel_hi:[0,1]
	v_pk_fma_f32 v[156:157], v[74:75], v[122:123], v[78:79]
	v_pk_fma_f32 v[122:123], v[76:77], v[124:125], v[80:81]
	v_pk_fma_f32 v[124:125], v[156:157], s[66:67], v[94:95] op_sel_hi:[1,0,1]
	v_pk_fma_f32 v[122:123], v[122:123], s[66:67], v[96:97] op_sel_hi:[1,0,1]
	s_waitcnt lgkmcnt(0)
	v_sub_f32_e32 v95, v113, v152
	v_sub_f32_e32 v94, v112, v152
	v_sub_f32_e32 v97, v115, v152
	v_sub_f32_e32 v96, v114, v152
	v_pk_mul_f32 v[96:97], v[144:145], v[96:97] op_sel_hi:[0,1]
	v_pk_mul_f32 v[94:95], v[144:145], v[94:95] op_sel_hi:[0,1]
	v_pk_fma_f32 v[94:95], v[66:67], v[94:95], v[70:71]
	v_pk_fma_f32 v[96:97], v[68:69], v[96:97], v[72:73]
	v_pk_fma_f32 v[156:157], v[94:95], s[66:67], v[90:91] op_sel_hi:[1,0,1]
	v_pk_fma_f32 v[114:115], v[96:97], s[66:67], v[92:93] op_sel_hi:[1,0,1]
	v_mov_b32_e32 v111, v142
	v_cvt_pk_f16_f32 v90, v124, v125
	v_cvt_pk_f16_f32 v91, v122, v123
	v_cvt_pk_f16_f32 v92, v156, v157
	v_cvt_pk_f16_f32 v93, v114, v115
	v_lshl_add_u64 v[112:113], v[158:159], 1, s[92:93]
	s_and_b64 vcc, exec, s[38:39]
	s_mov_b64 s[36:37], -1
	global_store_dwordx4 v[112:113], v[90:93], off
	s_cbranch_vccnz .LBB0_935
	v_cvt_f32_f16_sdwa v95, v146 dst_sel:DWORD dst_unused:UNUSED_PAD src0_sel:WORD_1
	v_cvt_f32_f16_e32 v94, v146
	v_cvt_f32_f16_sdwa v97, v147 dst_sel:DWORD dst_unused:UNUSED_PAD src0_sel:WORD_1
	v_cvt_f32_f16_e32 v96, v147
	v_cvt_f32_f16_sdwa v91, v148 dst_sel:DWORD dst_unused:UNUSED_PAD src0_sel:WORD_1
	v_cvt_f32_f16_e32 v90, v148
	v_cvt_f32_f16_sdwa v93, v149 dst_sel:DWORD dst_unused:UNUSED_PAD src0_sel:WORD_1
	v_cvt_f32_f16_e32 v92, v149
	s_mov_b64 s[36:37], 0

;     __device__ __forceinline__ void operator()(const f32x4 (&acc)[2][2][4][2], const Unit& u, int wr, int wc, int fr, int fq) const {
;     ...
;                     if (st) { const f16x8 h = hv[m][bj]; yp[0] = (f32x4){(float)h[0], (float)h[1], (float)h[2], (float)h[3]}; yp[1] = (f32x4){(float)h[4], (float)h[5], (float)h[6], (float)h[7]}; }
;                     else { yp[0] = *(const f32x4*)(x0 + off + bj * 32); yp[1] = *(const f32x4*)(x0 + off + bj * 32 + 4); }
;                     f32x4 y[2];
; #pragma unroll
;                     for (int n = 0; n < 2; ++n) { const f32x4 x = (yp[n] - rmu[m]) * ra[m] * gv[bj][n] + bv[bj][n];
;                         y[n] = x * alpha + acc[ai][bj][m][n] * s;
;                         s1 += (y[n][0] + y[n][1]) + (y[n][2] + y[n][3]); s2 += (y[n][0] * y[n][0] + y[n][1] * y[n][1]) + (y[n][2] * y[n][2] + y[n][3] * y[n][3]); }
;                     u32x4 w; w.x = cvtpk_h(y[0][0], y[0][1]); w.y = cvtpk_h(y[0][2], y[0][3]); w.z = cvtpk_h(y[1][0], y[1][1]); w.w = cvtpk_h(y[1][2], y[1][3]);
;                     *(u32x4*)(yh + off + bj * 32) = w;
;                 }
;                 s1 += __shfl_xor(s1, 16); s1 += __shfl_xor(s1, 32); s2 += __shfl_xor(s2, 16); s2 += __shfl_xor(s2, 32);
;                 if (fq == 0) { atomicAdd(st_new + 2 * (size_t)row, s1); atomicAdd(st_new + 2 * (size_t)row + 1, s2); }
.LBB0_937:
	v_add_f32_e32 v135, v124, v125
	v_add_f32_e32 v143, v122, v123
	v_mul_f32_e32 v125, v125, v125
	v_mul_f32_e32 v123, v123, v123
	v_fmac_f32_e32 v125, v124, v124
	v_fmac_f32_e32 v123, v122, v122
	v_add_f32_e32 v122, v125, v123
	v_add_f32_e32 v123, v156, v157
	v_add_f32_e32 v124, v114, v115
	v_add_f32_e32 v123, v123, v124
	v_mul_f32_e32 v124, v157, v157
	v_mul_f32_e32 v115, v115, v115
	v_fmac_f32_e32 v124, v156, v156
	v_fmac_f32_e32 v115, v114, v114
	v_add_f32_e32 v114, v124, v115
	v_mov_b32_e32 v146, v144
	v_mov_b32_e32 v147, v144
	v_add_f32_e32 v122, v122, v114
	s_nop 0
	v_sub_f32_e32 v95, v95, v152
	v_sub_f32_e32 v94, v94, v152
	v_sub_f32_e32 v97, v97, v152
	v_sub_f32_e32 v96, v96, v152
	v_mov_b32_e32 v114, v144
	v_mov_b32_e32 v115, v144
	v_pk_mul_f32 v[96:97], v[114:115], v[96:97]
	v_pk_mul_f32 v[94:95], v[146:147], v[94:95]
	s_nop 0
	v_sub_f32_e32 v91, v91, v152
	v_sub_f32_e32 v90, v90, v152
	v_sub_f32_e32 v93, v93, v152
	v_sub_f32_e32 v92, v92, v152
	v_pk_fma_f32 v[94:95], v[54:55], v[94:95], v[62:63]
	v_pk_fma_f32 v[96:97], v[56:57], v[96:97], v[64:65]
	v_pk_mul_f32 v[92:93], v[114:115], v[92:93]
	v_pk_mul_f32 v[90:91], v[146:147], v[90:91]
	v_pk_fma_f32 v[88:89], v[96:97], s[66:67], v[88:89] op_sel_hi:[1,0,1]
	v_pk_fma_f32 v[86:87], v[94:95], s[66:67], v[86:87] op_sel_hi:[1,0,1]
	v_pk_fma_f32 v[90:91], v[42:43], v[90:91], v[46:47]
	v_pk_fma_f32 v[92:93], v[44:45], v[92:93], v[48:49]
	v_add_f32_e32 v94, v86, v87
	v_add_f32_e32 v95, v88, v89
	v_pk_fma_f32 v[92:93], v[92:93], s[66:67], v[84:85] op_sel_hi:[1,0,1]
	v_pk_fma_f32 v[90:91], v[90:91], s[66:67], v[82:83] op_sel_hi:[1,0,1]
	v_add_f32_e32 v135, v135, v143
	v_add_f32_e32 v94, v94, v95
	v_mul_f32_e32 v95, v87, v87
	v_mul_f32_e32 v96, v89, v89
	v_add_f32_e32 v82, v90, v91
	v_add_f32_e32 v83, v92, v93
	v_add_f32_e32 v135, 0, v135
	v_fmac_f32_e32 v95, v86, v86
	v_fmac_f32_e32 v96, v88, v88
	v_add_f32_e32 v82, v82, v83
	v_mul_f32_e32 v83, v91, v91
	v_mul_f32_e32 v84, v93, v93
	v_add_f32_e32 v123, v123, v135
	v_add_f32_e32 v95, v95, v96
	v_fmac_f32_e32 v83, v90, v90
	v_fmac_f32_e32 v84, v92, v92
	v_add_f32_e32 v94, v123, v94
	v_add_f32_e32 v95, v122, v95
	v_add_f32_e32 v83, v83, v84
	v_add_f32_e32 v82, v82, v94
	v_add_f32_e32 v85, v83, v95
	ds_bpermute_b32 v84, v207, v82
	ds_bpermute_b32 v94, v207, v85
	v_cvt_pk_f16_f32 v86, v86, v87
	v_cvt_pk_f16_f32 v87, v88, v89
	v_cvt_pk_f16_f32 v88, v90, v91
	s_waitcnt lgkmcnt(1)
	v_add_f32_e32 v82, v82, v84
	s_waitcnt lgkmcnt(0)
	v_add_f32_e32 v84, v85, v94
	ds_bpermute_b32 v83, v208, v82
	ds_bpermute_b32 v85, v208, v84
	v_cvt_pk_f16_f32 v89, v92, v93
	global_store_dwordx4 v[112:113], v[86:89], off offset:64
	s_and_saveexec_b64 s[36:37], s[40:41]
	s_cbranch_execz .LBB0_939
	v_lshl_add_u64 v[86:87], v[150:151], 3, s[86:87]
	s_waitcnt lgkmcnt(1)
	v_add_f32_e32 v82, v82, v83
	s_waitcnt lgkmcnt(0)
	v_add_f32_e32 v83, v84, v85
	global_atomic_add_f32 v[86:87], v82, off
	global_atomic_add_f32 v[86:87], v83, off offset:4

;     __device__ __forceinline__ void operator()(const f32x4 (&acc)[2][2][4][2], const Unit& u, int wr, int wc, int fr, int fq) const {
;     ...
;                 for (int bj = 0; bj < 2; ++bj) {
;                     f32x4 yp[2];
;                     if (st) { const f16x8 h = hv[m][bj]; yp[0] = (f32x4){(float)h[0], (float)h[1], (float)h[2], (float)h[3]}; yp[1] = (f32x4){(float)h[4], (float)h[5], (float)h[6], (float)h[7]}; }
;                     else { yp[0] = *(const f32x4*)(x0 + off + bj * 32); yp[1] = *(const f32x4*)(x0 + off + bj * 32 + 4); }
;                     f32x4 y[2];
; #pragma unroll
;                     for (int n = 0; n < 2; ++n) { const f32x4 x = (yp[n] - rmu[m]) * ra[m] * gv[bj][n] + bv[bj][n];
;                         y[n] = x * alpha + acc[ai][bj][m][n] * s;
;                         s1 += (y[n][0] + y[n][1]) + (y[n][2] + y[n][3]); s2 += (y[n][0] * y[n][0] + y[n][1] * y[n][1]) + (y[n][2] * y[n][2] + y[n][3] * y[n][3]); }
;                     u32x4 w; w.x = cvtpk_h(y[0][0], y[0][1]); w.y = cvtpk_h(y[0][2], y[0][3]); w.z = cvtpk_h(y[1][0], y[1][1]); w.w = cvtpk_h(y[1][2], y[1][3]);
;                     *(u32x4*)(yh + off + bj * 32) = w;
;                 }
;                 s1 += __shfl_xor(s1, 16); s1 += __shfl_xor(s1, 32); s2 += __shfl_xor(s2, 16); s2 += __shfl_xor(s2, 32);
;                 if (fq == 0) { atomicAdd(st_new + 2 * (size_t)row, s1); atomicAdd(st_new + 2 * (size_t)row + 1, s2); }
.LBB0_943:
	s_nop 0
	v_sub_f32_e32 v87, v87, v111
	v_sub_f32_e32 v86, v86, v111
	v_sub_f32_e32 v89, v89, v111
	v_sub_f32_e32 v88, v88, v111
	v_pk_mul_f32 v[88:89], v[144:145], v[88:89] op_sel:[1,0]
	v_pk_mul_f32 v[86:87], v[144:145], v[86:87] op_sel:[1,0]
	s_and_b64 vcc, exec, s[38:39]
	v_pk_fma_f32 v[92:93], v[74:75], v[86:87], v[78:79]
	v_pk_fma_f32 v[86:87], v[76:77], v[88:89], v[80:81]
	v_pk_fma_f32 v[88:89], v[92:93], s[66:67], v[58:59] op_sel_hi:[1,0,1]
	v_pk_fma_f32 v[86:87], v[86:87], s[66:67], v[60:61] op_sel_hi:[1,0,1]
	s_waitcnt lgkmcnt(1)
	v_sub_f32_e32 v59, v83, v111
	v_sub_f32_e32 v58, v82, v111
	s_waitcnt lgkmcnt(0)
	v_sub_f32_e32 v61, v85, v111
	v_sub_f32_e32 v60, v84, v111
	v_pk_mul_f32 v[60:61], v[144:145], v[60:61] op_sel:[1,0]
	v_pk_mul_f32 v[58:59], v[144:145], v[58:59] op_sel:[1,0]
	v_pk_fma_f32 v[60:61], v[68:69], v[60:61], v[72:73]
	v_pk_fma_f32 v[58:59], v[66:67], v[58:59], v[70:71]
	v_pk_fma_f32 v[84:85], v[60:61], s[66:67], v[52:53] op_sel_hi:[1,0,1]
	v_pk_fma_f32 v[92:93], v[58:59], s[66:67], v[50:51] op_sel_hi:[1,0,1]
	v_cvt_pk_f16_f32 v50, v88, v89
	v_cvt_pk_f16_f32 v51, v86, v87
	v_cvt_pk_f16_f32 v52, v92, v93
	v_cvt_pk_f16_f32 v53, v84, v85
	v_lshl_add_u64 v[82:83], v[94:95], 1, s[92:93]
	s_mov_b64 s[36:37], -1
	global_store_dwordx4 v[82:83], v[50:53], off
	s_cbranch_vccnz .LBB0_945
	v_cvt_f32_f16_sdwa v59, v130 dst_sel:DWORD dst_unused:UNUSED_PAD src0_sel:WORD_1
	v_cvt_f32_f16_e32 v58, v130
	v_cvt_f32_f16_sdwa v61, v131 dst_sel:DWORD dst_unused:UNUSED_PAD src0_sel:WORD_1
	v_cvt_f32_f16_e32 v60, v131
	v_cvt_f32_f16_sdwa v51, v132 dst_sel:DWORD dst_unused:UNUSED_PAD src0_sel:WORD_1
	v_cvt_f32_f16_e32 v50, v132
	v_cvt_f32_f16_sdwa v53, v133 dst_sel:DWORD dst_unused:UNUSED_PAD src0_sel:WORD_1
	v_cvt_f32_f16_e32 v52, v133
	s_mov_b64 s[36:37], 0
.LBB0_945:
	s_andn2_b64 vcc, exec, s[36:37]
	s_cbranch_vccnz .LBB0_947
	global_load_dwordx4 v[58:61], v[90:91], off offset:128
	global_load_dwordx4 v[50:53], v[90:91], off offset:144
	s_waitcnt vmcnt(0)
.LBB0_947:
	v_add_f32_e32 v90, v88, v89
	v_add_f32_e32 v91, v86, v87
	v_mul_f32_e32 v89, v89, v89
	v_mul_f32_e32 v87, v87, v87
	v_fmac_f32_e32 v89, v88, v88
	v_fmac_f32_e32 v87, v86, v86
	v_add_f32_e32 v86, v89, v87
	v_add_f32_e32 v87, v92, v93
	v_add_f32_e32 v88, v84, v85
	v_add_f32_e32 v87, v87, v88
	v_mul_f32_e32 v88, v93, v93
	v_mul_f32_e32 v85, v85, v85
	v_fmac_f32_e32 v88, v92, v92
	v_fmac_f32_e32 v85, v84, v84
	v_add_f32_e32 v84, v88, v85
	v_mov_b32_e32 v144, v145
	v_add_f32_e32 v86, v86, v84
	s_nop 0
	v_sub_f32_e32 v59, v59, v111
	v_sub_f32_e32 v58, v58, v142
	v_sub_f32_e32 v61, v61, v111
	v_sub_f32_e32 v60, v60, v142
	v_mov_b32_e32 v84, v145
	v_mov_b32_e32 v85, v145
	v_pk_mul_f32 v[60:61], v[84:85], v[60:61]
	v_pk_mul_f32 v[58:59], v[144:145], v[58:59]
	s_nop 0
	v_sub_f32_e32 v51, v51, v111
	v_sub_f32_e32 v50, v50, v142
	v_sub_f32_e32 v53, v53, v111
	v_sub_f32_e32 v52, v52, v142
	v_pk_fma_f32 v[58:59], v[54:55], v[58:59], v[62:63]
	v_pk_fma_f32 v[60:61], v[56:57], v[60:61], v[64:65]
	v_pk_mul_f32 v[52:53], v[84:85], v[52:53]
	v_pk_mul_f32 v[50:51], v[144:145], v[50:51]
	v_pk_fma_f32 v[40:41], v[60:61], s[66:67], v[40:41] op_sel_hi:[1,0,1]
	v_pk_fma_f32 v[38:39], v[58:59], s[66:67], v[38:39] op_sel_hi:[1,0,1]
	v_pk_fma_f32 v[50:51], v[42:43], v[50:51], v[46:47]
	v_pk_fma_f32 v[52:53], v[44:45], v[52:53], v[48:49]
	v_add_f32_e32 v58, v38, v39
	v_add_f32_e32 v59, v40, v41
	v_pk_fma_f32 v[52:53], v[52:53], s[66:67], v[36:37] op_sel_hi:[1,0,1]
	v_pk_fma_f32 v[50:51], v[50:51], s[66:67], v[34:35] op_sel_hi:[1,0,1]
	v_add_f32_e32 v90, v90, v91
	v_add_f32_e32 v58, v58, v59
	v_mul_f32_e32 v59, v39, v39
	v_mul_f32_e32 v60, v41, v41
	v_add_f32_e32 v34, v50, v51
	v_add_f32_e32 v35, v52, v53
	v_add_f32_e32 v90, 0, v90
	v_fmac_f32_e32 v59, v38, v38
	v_fmac_f32_e32 v60, v40, v40
	v_add_f32_e32 v34, v34, v35
	v_mul_f32_e32 v35, v51, v51
	v_mul_f32_e32 v36, v53, v53
	v_add_f32_e32 v87, v87, v90
	v_add_f32_e32 v59, v59, v60
	v_fmac_f32_e32 v35, v50, v50
	v_fmac_f32_e32 v36, v52, v52
	v_add_f32_e32 v58, v87, v58
	v_add_f32_e32 v59, v86, v59
	v_add_f32_e32 v35, v35, v36
	v_add_f32_e32 v34, v34, v58
	v_add_f32_e32 v37, v35, v59
	ds_bpermute_b32 v36, v207, v34
	ds_bpermute_b32 v58, v207, v37
	v_cvt_pk_f16_f32 v38, v38, v39
	v_cvt_pk_f16_f32 v39, v40, v41
	v_cvt_pk_f16_f32 v40, v50, v51
	s_waitcnt lgkmcnt(1)
	v_add_f32_e32 v34, v34, v36
	s_waitcnt lgkmcnt(0)
	v_add_f32_e32 v36, v37, v58
	ds_bpermute_b32 v35, v208, v34
	ds_bpermute_b32 v37, v208, v36
	v_cvt_pk_f16_f32 v41, v52, v53
	global_store_dwordx4 v[82:83], v[38:41], off offset:64
	s_and_saveexec_b64 s[36:37], s[40:41]
	s_cbranch_execz .LBB0_949
	v_lshl_add_u64 v[38:39], v[136:137], 3, s[86:87]
	s_waitcnt lgkmcnt(1)
	v_add_f32_e32 v34, v34, v35
	s_waitcnt lgkmcnt(0)
	v_add_f32_e32 v35, v36, v37
	global_atomic_add_f32 v[38:39], v34, off
	global_atomic_add_f32 v[38:39], v35, off offset:4

;     __device__ __forceinline__ void operator()(const f32x4 (&acc)[2][2][4][2], const Unit& u, int wr, int wc, int fr, int fq) const {
;     ...
;                 for (int bj = 0; bj < 2; ++bj) {
;                     f32x4 yp[2];
;                     if (st) { const f16x8 h = hv[m][bj]; yp[0] = (f32x4){(float)h[0], (float)h[1], (float)h[2], (float)h[3]}; yp[1] = (f32x4){(float)h[4], (float)h[5], (float)h[6], (float)h[7]}; }
;                     else { yp[0] = *(const f32x4*)(x0 + off + bj * 32); yp[1] = *(const f32x4*)(x0 + off + bj * 32 + 4); }
;                     f32x4 y[2];
; #pragma unroll
;                     for (int n = 0; n < 2; ++n) { const f32x4 x = (yp[n] - rmu[m]) * ra[m] * gv[bj][n] + bv[bj][n];
;                         y[n] = x * alpha + acc[ai][bj][m][n] * s;
;                         s1 += (y[n][0] + y[n][1]) + (y[n][2] + y[n][3]); s2 += (y[n][0] * y[n][0] + y[n][1] * y[n][1]) + (y[n][2] * y[n][2] + y[n][3] * y[n][3]); }
;                     u32x4 w; w.x = cvtpk_h(y[0][0], y[0][1]); w.y = cvtpk_h(y[0][2], y[0][3]); w.z = cvtpk_h(y[1][0], y[1][1]); w.w = cvtpk_h(y[1][2], y[1][3]);
;                     *(u32x4*)(yh + off + bj * 32) = w;
.LBB0_951:
	v_lshlrev_b64 v[50:51], 10, v[128:129]
	v_lshl_add_u64 v[58:59], v[50:51], 0, v[224:225]
	s_andn2_b64 vcc, exec, s[36:37]
	v_lshl_add_u64 v[50:51], v[58:59], 2, s[68:69]
	s_cbranch_vccnz .LBB0_953
	global_load_dwordx4 v[38:41], v[50:51], off
	s_waitcnt lgkmcnt(0)
	global_load_dwordx4 v[34:37], v[50:51], off offset:16
	s_waitcnt vmcnt(0)
.LBB0_953:
	s_nop 0
	v_sub_f32_e32 v39, v39, v134
	v_sub_f32_e32 v38, v38, v134
	v_sub_f32_e32 v41, v41, v134
	v_sub_f32_e32 v40, v40, v134
	v_pk_mul_f32 v[40:41], v[126:127], v[40:41] op_sel_hi:[0,1]
	v_pk_mul_f32 v[38:39], v[126:127], v[38:39] op_sel_hi:[0,1]
	v_pk_fma_f32 v[52:53], v[74:75], v[38:39], v[78:79]
	v_pk_fma_f32 v[38:39], v[76:77], v[40:41], v[80:81]
	v_pk_fma_f32 v[40:41], v[52:53], s[66:67], v[30:31] op_sel_hi:[1,0,1]
	v_pk_fma_f32 v[38:39], v[38:39], s[66:67], v[32:33] op_sel_hi:[1,0,1]
	s_waitcnt lgkmcnt(1)
	v_sub_f32_e32 v31, v35, v134
	v_sub_f32_e32 v30, v34, v134
	s_waitcnt lgkmcnt(0)
	v_sub_f32_e32 v33, v37, v134
	v_sub_f32_e32 v32, v36, v134
	v_pk_mul_f32 v[32:33], v[126:127], v[32:33] op_sel_hi:[0,1]
	v_pk_mul_f32 v[30:31], v[126:127], v[30:31] op_sel_hi:[0,1]
	v_pk_fma_f32 v[30:31], v[66:67], v[30:31], v[70:71]
	v_pk_fma_f32 v[32:33], v[68:69], v[32:33], v[72:73]
	v_pk_fma_f32 v[52:53], v[30:31], s[66:67], v[26:27] op_sel_hi:[1,0,1]
	v_pk_fma_f32 v[36:37], v[32:33], s[66:67], v[28:29] op_sel_hi:[1,0,1]
	v_cvt_pk_f16_f32 v26, v40, v41
	v_cvt_pk_f16_f32 v27, v38, v39
	v_cvt_pk_f16_f32 v28, v52, v53
	v_cvt_pk_f16_f32 v29, v36, v37
	v_lshl_add_u64 v[34:35], v[58:59], 1, s[92:93]
	s_and_b64 vcc, exec, s[38:39]
	s_mov_b64 s[36:37], -1
	global_store_dwordx4 v[34:35], v[26:29], off
	s_cbranch_vccnz .LBB0_955
	v_cvt_f32_f16_sdwa v31, v106 dst_sel:DWORD dst_unused:UNUSED_PAD src0_sel:WORD_1
	v_cvt_f32_f16_e32 v30, v106
	v_cvt_f32_f16_sdwa v33, v107 dst_sel:DWORD dst_unused:UNUSED_PAD src0_sel:WORD_1
	v_cvt_f32_f16_e32 v32, v107
	v_cvt_f32_f16_sdwa v27, v108 dst_sel:DWORD dst_unused:UNUSED_PAD src0_sel:WORD_1
	v_cvt_f32_f16_e32 v26, v108
	v_cvt_f32_f16_sdwa v29, v109 dst_sel:DWORD dst_unused:UNUSED_PAD src0_sel:WORD_1
	v_cvt_f32_f16_e32 v28, v109
	s_mov_b64 s[36:37], 0

;     __device__ __forceinline__ void operator()(const f32x4 (&acc)[2][2][4][2], const Unit& u, int wr, int wc, int fr, int fq) const {
;     ...
;                     if (st) { const f16x8 h = hv[m][bj]; yp[0] = (f32x4){(float)h[0], (float)h[1], (float)h[2], (float)h[3]}; yp[1] = (f32x4){(float)h[4], (float)h[5], (float)h[6], (float)h[7]}; }
;                     else { yp[0] = *(const f32x4*)(x0 + off + bj * 32); yp[1] = *(const f32x4*)(x0 + off + bj * 32 + 4); }
;                     f32x4 y[2];
; #pragma unroll
;                     for (int n = 0; n < 2; ++n) { const f32x4 x = (yp[n] - rmu[m]) * ra[m] * gv[bj][n] + bv[bj][n];
;                         y[n] = x * alpha + acc[ai][bj][m][n] * s;
;                         s1 += (y[n][0] + y[n][1]) + (y[n][2] + y[n][3]); s2 += (y[n][0] * y[n][0] + y[n][1] * y[n][1]) + (y[n][2] * y[n][2] + y[n][3] * y[n][3]); }
;                     u32x4 w; w.x = cvtpk_h(y[0][0], y[0][1]); w.y = cvtpk_h(y[0][2], y[0][3]); w.z = cvtpk_h(y[1][0], y[1][1]); w.w = cvtpk_h(y[1][2], y[1][3]);
;                     *(u32x4*)(yh + off + bj * 32) = w;
;                 }
;                 s1 += __shfl_xor(s1, 16); s1 += __shfl_xor(s1, 32); s2 += __shfl_xor(s2, 16); s2 += __shfl_xor(s2, 32);
;                 if (fq == 0) { atomicAdd(st_new + 2 * (size_t)row, s1); atomicAdd(st_new + 2 * (size_t)row + 1, s2); }
.LBB0_957:
	v_add_f32_e32 v58, v40, v41
	v_add_f32_e32 v59, v38, v39
	v_mul_f32_e32 v41, v41, v41
	v_mul_f32_e32 v39, v39, v39
	v_fmac_f32_e32 v41, v40, v40
	v_fmac_f32_e32 v39, v38, v38
	v_add_f32_e32 v38, v41, v39
	v_add_f32_e32 v39, v52, v53
	v_add_f32_e32 v40, v36, v37
	v_add_f32_e32 v39, v39, v40
	v_mul_f32_e32 v40, v53, v53
	v_mul_f32_e32 v37, v37, v37
	v_fmac_f32_e32 v40, v52, v52
	v_fmac_f32_e32 v37, v36, v36
	v_add_f32_e32 v36, v40, v37
	v_mov_b32_e32 v50, v126
	v_mov_b32_e32 v51, v126
	v_add_f32_e32 v38, v38, v36
	s_nop 0
	v_sub_f32_e32 v31, v31, v134
	v_sub_f32_e32 v30, v30, v134
	v_sub_f32_e32 v33, v33, v134
	v_sub_f32_e32 v32, v32, v134
	v_mov_b32_e32 v36, v126
	v_mov_b32_e32 v37, v126
	v_pk_mul_f32 v[32:33], v[36:37], v[32:33]
	v_pk_mul_f32 v[30:31], v[50:51], v[30:31]
	s_nop 0
	v_sub_f32_e32 v27, v27, v134
	v_sub_f32_e32 v26, v26, v134
	v_sub_f32_e32 v29, v29, v134
	v_sub_f32_e32 v28, v28, v134
	v_pk_fma_f32 v[30:31], v[54:55], v[30:31], v[62:63]
	v_pk_fma_f32 v[32:33], v[56:57], v[32:33], v[64:65]
	v_pk_mul_f32 v[28:29], v[36:37], v[28:29]
	v_pk_mul_f32 v[26:27], v[50:51], v[26:27]
	v_pk_fma_f32 v[24:25], v[32:33], s[66:67], v[24:25] op_sel_hi:[1,0,1]
	v_pk_fma_f32 v[22:23], v[30:31], s[66:67], v[22:23] op_sel_hi:[1,0,1]
	v_pk_fma_f32 v[26:27], v[42:43], v[26:27], v[46:47]
	v_pk_fma_f32 v[28:29], v[44:45], v[28:29], v[48:49]
	v_add_f32_e32 v30, v22, v23
	v_add_f32_e32 v31, v24, v25
	v_pk_fma_f32 v[28:29], v[28:29], s[66:67], v[20:21] op_sel_hi:[1,0,1]
	v_pk_fma_f32 v[26:27], v[26:27], s[66:67], v[18:19] op_sel_hi:[1,0,1]
	v_add_f32_e32 v58, v58, v59
	v_add_f32_e32 v30, v30, v31
	v_mul_f32_e32 v31, v23, v23
	v_mul_f32_e32 v32, v25, v25
	v_add_f32_e32 v18, v26, v27
	v_add_f32_e32 v19, v28, v29
	v_add_f32_e32 v58, 0, v58
	v_fmac_f32_e32 v31, v22, v22
	v_fmac_f32_e32 v32, v24, v24
	v_add_f32_e32 v18, v18, v19
	v_mul_f32_e32 v19, v27, v27
	v_mul_f32_e32 v20, v29, v29
	v_add_f32_e32 v39, v39, v58
	v_add_f32_e32 v31, v31, v32
	v_fmac_f32_e32 v19, v26, v26
	v_fmac_f32_e32 v20, v28, v28
	v_add_f32_e32 v30, v39, v30
	v_add_f32_e32 v31, v38, v31
	v_add_f32_e32 v19, v19, v20
	v_add_f32_e32 v18, v18, v30
	v_add_f32_e32 v21, v19, v31
	ds_bpermute_b32 v20, v207, v18
	ds_bpermute_b32 v30, v207, v21
	v_cvt_pk_f16_f32 v22, v22, v23
	v_cvt_pk_f16_f32 v23, v24, v25
	v_cvt_pk_f16_f32 v24, v26, v27
	s_waitcnt lgkmcnt(1)
	v_add_f32_e32 v18, v18, v20
	s_waitcnt lgkmcnt(0)
	v_add_f32_e32 v20, v21, v30
	ds_bpermute_b32 v19, v208, v18
	ds_bpermute_b32 v21, v208, v20
	v_cvt_pk_f16_f32 v25, v28, v29
	global_store_dwordx4 v[34:35], v[22:25], off offset:64
	s_and_saveexec_b64 s[36:37], s[40:41]
	s_cbranch_execz .LBB0_959
	v_lshl_add_u64 v[22:23], v[128:129], 3, s[86:87]
	s_waitcnt lgkmcnt(1)
	v_add_f32_e32 v18, v18, v19
	s_waitcnt lgkmcnt(0)
	v_add_f32_e32 v19, v20, v21
	global_atomic_add_f32 v[22:23], v18, off
	global_atomic_add_f32 v[22:23], v19, off offset:4

;     __device__ __forceinline__ void operator()(const f32x4 (&acc)[2][2][4][2], const Unit& u, int wr, int wc, int fr, int fq) const {
;     ...
;                     if (st) { const f16x8 h = hv[m][bj]; yp[0] = (f32x4){(float)h[0], (float)h[1], (float)h[2], (float)h[3]}; yp[1] = (f32x4){(float)h[4], (float)h[5], (float)h[6], (float)h[7]}; }
;                     else { yp[0] = *(const f32x4*)(x0 + off + bj * 32); yp[1] = *(const f32x4*)(x0 + off + bj * 32 + 4); }
;                     f32x4 y[2];
; #pragma unroll
;                     for (int n = 0; n < 2; ++n) { const f32x4 x = (yp[n] - rmu[m]) * ra[m] * gv[bj][n] + bv[bj][n];
;                         y[n] = x * alpha + acc[ai][bj][m][n] * s;
;                         s1 += (y[n][0] + y[n][1]) + (y[n][2] + y[n][3]); s2 += (y[n][0] * y[n][0] + y[n][1] * y[n][1]) + (y[n][2] * y[n][2] + y[n][3] * y[n][3]); }
;                     u32x4 w; w.x = cvtpk_h(y[0][0], y[0][1]); w.y = cvtpk_h(y[0][2], y[0][3]); w.z = cvtpk_h(y[1][0], y[1][1]); w.w = cvtpk_h(y[1][2], y[1][3]);
;                     *(u32x4*)(yh + off + bj * 32) = w;
.LBB0_963:
	s_nop 0
	v_sub_f32_e32 v23, v23, v110
	v_sub_f32_e32 v22, v22, v110
	v_sub_f32_e32 v25, v25, v110
	v_sub_f32_e32 v24, v24, v110
	v_mov_b32_e32 v28, v127
	v_pk_mul_f32 v[24:25], v[28:29], v[24:25] op_sel_hi:[0,1]
	v_pk_mul_f32 v[22:23], v[28:29], v[22:23] op_sel_hi:[0,1]
	v_pk_fma_f32 v[32:33], v[74:75], v[22:23], v[78:79]
	v_pk_fma_f32 v[22:23], v[76:77], v[24:25], v[80:81]
	v_pk_fma_f32 v[24:25], v[32:33], s[66:67], v[14:15] op_sel_hi:[1,0,1]
	v_pk_fma_f32 v[22:23], v[22:23], s[66:67], v[16:17] op_sel_hi:[1,0,1]
	s_waitcnt lgkmcnt(1)
	v_sub_f32_e32 v15, v19, v110
	v_sub_f32_e32 v14, v18, v110
	s_waitcnt lgkmcnt(0)
	v_sub_f32_e32 v17, v21, v110
	v_sub_f32_e32 v16, v20, v110
	v_pk_mul_f32 v[16:17], v[28:29], v[16:17] op_sel_hi:[0,1]
	v_pk_mul_f32 v[14:15], v[28:29], v[14:15] op_sel_hi:[0,1]
	v_pk_fma_f32 v[14:15], v[66:67], v[14:15], v[70:71]
	v_pk_fma_f32 v[16:17], v[68:69], v[16:17], v[72:73]
	v_pk_fma_f32 v[28:29], v[14:15], s[66:67], v[10:11] op_sel_hi:[1,0,1]
	v_pk_fma_f32 v[20:21], v[16:17], s[66:67], v[12:13] op_sel_hi:[1,0,1]
	v_cvt_pk_f16_f32 v10, v24, v25
	v_cvt_pk_f16_f32 v11, v22, v23
	v_cvt_pk_f16_f32 v12, v28, v29
	v_cvt_pk_f16_f32 v13, v20, v21
	v_lshl_add_u64 v[18:19], v[30:31], 1, s[92:93]
	s_and_b64 vcc, exec, s[38:39]
	s_mov_b64 s[36:37], -1
	global_store_dwordx4 v[18:19], v[10:13], off
	s_cbranch_vccnz .LBB0_965
	v_cvt_f32_f16_sdwa v15, v98 dst_sel:DWORD dst_unused:UNUSED_PAD src0_sel:WORD_1
	v_cvt_f32_f16_e32 v14, v98
	v_cvt_f32_f16_sdwa v17, v99 dst_sel:DWORD dst_unused:UNUSED_PAD src0_sel:WORD_1
	v_cvt_f32_f16_e32 v16, v99
	v_cvt_f32_f16_sdwa v11, v100 dst_sel:DWORD dst_unused:UNUSED_PAD src0_sel:WORD_1
	v_cvt_f32_f16_e32 v10, v100
	v_cvt_f32_f16_sdwa v13, v101 dst_sel:DWORD dst_unused:UNUSED_PAD src0_sel:WORD_1
	v_cvt_f32_f16_e32 v12, v101
	s_mov_b64 s[36:37], 0

;     __device__ __forceinline__ void operator()(const f32x4 (&acc)[2][2][4][2], const Unit& u, int wr, int wc, int fr, int fq) const {
;     ...
;                     if (st) { const f16x8 h = hv[m][bj]; yp[0] = (f32x4){(float)h[0], (float)h[1], (float)h[2], (float)h[3]}; yp[1] = (f32x4){(float)h[4], (float)h[5], (float)h[6], (float)h[7]}; }
;                     else { yp[0] = *(const f32x4*)(x0 + off + bj * 32); yp[1] = *(const f32x4*)(x0 + off + bj * 32 + 4); }
;                     f32x4 y[2];
; #pragma unroll
;                     for (int n = 0; n < 2; ++n) { const f32x4 x = (yp[n] - rmu[m]) * ra[m] * gv[bj][n] + bv[bj][n];
;                         y[n] = x * alpha + acc[ai][bj][m][n] * s;
;                         s1 += (y[n][0] + y[n][1]) + (y[n][2] + y[n][3]); s2 += (y[n][0] * y[n][0] + y[n][1] * y[n][1]) + (y[n][2] * y[n][2] + y[n][3] * y[n][3]); }
;                     u32x4 w; w.x = cvtpk_h(y[0][0], y[0][1]); w.y = cvtpk_h(y[0][2], y[0][3]); w.z = cvtpk_h(y[1][0], y[1][1]); w.w = cvtpk_h(y[1][2], y[1][3]);
;                     *(u32x4*)(yh + off + bj * 32) = w;
;                 }
;                 s1 += __shfl_xor(s1, 16); s1 += __shfl_xor(s1, 32); s2 += __shfl_xor(s2, 16); s2 += __shfl_xor(s2, 32);
;                 if (fq == 0) { atomicAdd(st_new + 2 * (size_t)row, s1); atomicAdd(st_new + 2 * (size_t)row + 1, s2); }
.LBB0_967:
	v_mov_b32_e32 v26, v127
	v_mov_b32_e32 v27, v127
	s_nop 0
	v_sub_f32_e32 v15, v15, v110
	v_sub_f32_e32 v14, v14, v110
	v_sub_f32_e32 v17, v17, v110
	v_sub_f32_e32 v16, v16, v110
	v_mov_b32_e32 v126, v127
	v_add_f32_e32 v30, v24, v25
	v_add_f32_e32 v31, v22, v23
	v_mul_f32_e32 v25, v25, v25
	v_mul_f32_e32 v23, v23, v23
	v_pk_mul_f32 v[16:17], v[126:127], v[16:17]
	v_pk_mul_f32 v[14:15], v[26:27], v[14:15]
	s_nop 0
	v_sub_f32_e32 v11, v11, v110
	v_sub_f32_e32 v10, v10, v110
	v_sub_f32_e32 v13, v13, v110
	v_sub_f32_e32 v12, v12, v110
	v_fmac_f32_e32 v25, v24, v24
	v_fmac_f32_e32 v23, v22, v22
	v_pk_fma_f32 v[14:15], v[54:55], v[14:15], v[62:63]
	v_pk_fma_f32 v[16:17], v[56:57], v[16:17], v[64:65]
	v_pk_mul_f32 v[12:13], v[126:127], v[12:13]
	v_pk_mul_f32 v[10:11], v[26:27], v[10:11]
	v_add_f32_e32 v22, v25, v23
	v_add_f32_e32 v23, v28, v29
	v_add_f32_e32 v24, v20, v21
	v_pk_fma_f32 v[8:9], v[16:17], s[66:67], v[8:9] op_sel_hi:[1,0,1]
	v_pk_fma_f32 v[6:7], v[14:15], s[66:67], v[6:7] op_sel_hi:[1,0,1]
	v_pk_fma_f32 v[10:11], v[42:43], v[10:11], v[46:47]
	v_pk_fma_f32 v[12:13], v[44:45], v[12:13], v[48:49]
	v_add_f32_e32 v23, v23, v24
	v_mul_f32_e32 v24, v29, v29
	v_mul_f32_e32 v21, v21, v21
	v_add_f32_e32 v14, v6, v7
	v_add_f32_e32 v15, v8, v9
	v_pk_fma_f32 v[12:13], v[12:13], s[66:67], v[4:5] op_sel_hi:[1,0,1]
	v_pk_fma_f32 v[10:11], v[10:11], s[66:67], v[2:3] op_sel_hi:[1,0,1]
	v_add_f32_e32 v30, v30, v31
	v_fmac_f32_e32 v24, v28, v28
	v_fmac_f32_e32 v21, v20, v20
	v_add_f32_e32 v14, v14, v15
	v_mul_f32_e32 v15, v7, v7
	v_mul_f32_e32 v16, v9, v9
	v_add_f32_e32 v2, v10, v11
	v_add_f32_e32 v3, v12, v13
	v_add_f32_e32 v30, 0, v30
	v_add_f32_e32 v20, v24, v21
	v_fmac_f32_e32 v15, v6, v6
	v_fmac_f32_e32 v16, v8, v8
	v_add_f32_e32 v2, v2, v3
	v_mul_f32_e32 v3, v11, v11
	v_mul_f32_e32 v4, v13, v13
	v_add_f32_e32 v23, v23, v30
	v_add_f32_e32 v20, v22, v20
	v_add_f32_e32 v15, v15, v16
	v_fmac_f32_e32 v3, v10, v10
	v_fmac_f32_e32 v4, v12, v12
	v_add_f32_e32 v14, v23, v14
	v_add_f32_e32 v15, v20, v15
	v_add_f32_e32 v3, v3, v4
	v_add_f32_e32 v2, v2, v14
	v_add_f32_e32 v5, v3, v15
	ds_bpermute_b32 v4, v207, v2
	ds_bpermute_b32 v14, v207, v5
	v_cvt_pk_f16_f32 v6, v6, v7
	v_cvt_pk_f16_f32 v7, v8, v9
	v_cvt_pk_f16_f32 v8, v10, v11
	s_waitcnt lgkmcnt(1)
	v_add_f32_e32 v2, v2, v4
	s_waitcnt lgkmcnt(0)
	v_add_f32_e32 v4, v5, v14
	ds_bpermute_b32 v3, v208, v2
	ds_bpermute_b32 v5, v208, v4
	v_cvt_pk_f16_f32 v9, v12, v13
	global_store_dwordx4 v[18:19], v[6:9], off offset:64
	s_and_saveexec_b64 s[36:37], s[40:41]
	s_cbranch_execz .LBB0_969
	v_lshl_add_u64 v[6:7], v[116:117], 3, s[86:87]
	s_waitcnt lgkmcnt(1)
	v_add_f32_e32 v2, v2, v3
	s_waitcnt lgkmcnt(0)
	v_add_f32_e32 v3, v4, v5
	global_atomic_add_f32 v[6:7], v2, off
	global_atomic_add_f32 v[6:7], v3, off offset:4

;     __device__ __forceinline__ void operator()(const f32x4 (&acc)[2][2][4][2], const Unit& u, int wr, int wc, int fr, int fq) const {
;     ...
;                     if (st) { const f16x8 h = hv[m][bj]; yp[0] = (f32x4){(float)h[0], (float)h[1], (float)h[2], (float)h[3]}; yp[1] = (f32x4){(float)h[4], (float)h[5], (float)h[6], (float)h[7]}; }
;                     else { yp[0] = *(const f32x4*)(x0 + off + bj * 32); yp[1] = *(const f32x4*)(x0 + off + bj * 32 + 4); }
;                     f32x4 y[2];
; #pragma unroll
;                     for (int n = 0; n < 2; ++n) { const f32x4 x = (yp[n] - rmu[m]) * ra[m] * gv[bj][n] + bv[bj][n];
;                         y[n] = x * alpha + acc[ai][bj][m][n] * s;
;                         s1 += (y[n][0] + y[n][1]) + (y[n][2] + y[n][3]); s2 += (y[n][0] * y[n][0] + y[n][1] * y[n][1]) + (y[n][2] * y[n][2] + y[n][3] * y[n][3]); }
;                     u32x4 w; w.x = cvtpk_h(y[0][0], y[0][1]); w.y = cvtpk_h(y[0][2], y[0][3]); w.z = cvtpk_h(y[1][0], y[1][1]); w.w = cvtpk_h(y[1][2], y[1][3]);
;                     *(u32x4*)(yh + off + bj * 32) = w;
.LBB0_1157:
	v_mov_b32_e32 v243, v244
	s_nop 0
	v_sub_f32_e32 v205, v205, v178
	v_sub_f32_e32 v204, v204, v178
	v_sub_f32_e32 v203, v203, v178
	v_sub_f32_e32 v202, v202, v178
	v_pk_mul_f32 v[202:203], v[242:243], v[202:203] op_sel_hi:[0,1]
	v_pk_mul_f32 v[204:205], v[242:243], v[204:205] op_sel_hi:[0,1]
	v_pk_fma_f32 v[204:205], v[76:77], v[204:205], v[80:81]
	v_pk_fma_f32 v[202:203], v[74:75], v[202:203], v[78:79]
	v_mov_b32_e32 v238, v237
	v_pk_mul_f32 v[248:249], v[202:203], s[66:67] op_sel_hi:[1,0]
	v_pk_mul_f32 v[202:203], v[204:205], s[66:67] op_sel_hi:[1,0]
	v_pk_fma_f32 v[204:205], v[194:195], 0.5, v[248:249] op_sel_hi:[1,0,1]
	v_pk_fma_f32 v[202:203], v[196:197], 0.5, v[202:203] op_sel_hi:[1,0,1]
	v_sub_f32_e32 v195, v201, v178
	v_sub_f32_e32 v194, v200, v178
	v_sub_f32_e32 v197, v199, v178
	v_sub_f32_e32 v196, v198, v178
	v_pk_mul_f32 v[196:197], v[242:243], v[196:197] op_sel_hi:[0,1]
	v_pk_mul_f32 v[194:195], v[242:243], v[194:195] op_sel_hi:[0,1]
	v_pk_fma_f32 v[194:195], v[68:69], v[194:195], v[72:73]
	v_pk_fma_f32 v[196:197], v[66:67], v[196:197], v[70:71]
	v_pk_mul_f32 v[194:195], v[194:195], s[66:67] op_sel_hi:[1,0]
	v_pk_mul_f32 v[196:197], v[196:197], s[66:67] op_sel_hi:[1,0]
	v_pk_fma_f32 v[200:201], v[192:193], 0.5, v[194:195] op_sel_hi:[1,0,1]
	v_pk_fma_f32 v[248:249], v[190:191], 0.5, v[196:197] op_sel_hi:[1,0,1]
	v_cvt_pk_f16_f32 v190, v204, v205
	v_cvt_pk_f16_f32 v191, v202, v203
	v_cvt_pk_f16_f32 v192, v248, v249
	v_cvt_pk_f16_f32 v193, v200, v201
	v_lshl_add_u64 v[198:199], v[250:251], 1, s[92:93]
	s_and_b64 vcc, exec, s[38:39]
	s_mov_b64 s[36:37], -1
	global_store_dwordx4 v[198:199], v[190:193], off
	s_cbranch_vccnz .LBB0_1159
	v_cvt_f32_f16_sdwa v195, v146 dst_sel:DWORD dst_unused:UNUSED_PAD src0_sel:WORD_1
	v_cvt_f32_f16_e32 v194, v146
	v_cvt_f32_f16_sdwa v197, v147 dst_sel:DWORD dst_unused:UNUSED_PAD src0_sel:WORD_1
	v_cvt_f32_f16_e32 v196, v147
	v_cvt_f32_f16_sdwa v191, v148 dst_sel:DWORD dst_unused:UNUSED_PAD src0_sel:WORD_1
	v_cvt_f32_f16_e32 v190, v148
	v_cvt_f32_f16_sdwa v193, v149 dst_sel:DWORD dst_unused:UNUSED_PAD src0_sel:WORD_1
	v_cvt_f32_f16_e32 v192, v149
	s_mov_b64 s[36:37], 0

;     __device__ __forceinline__ void operator()(const f32x4 (&acc)[2][2][4][2], const Unit& u, int wr, int wc, int fr, int fq) const {
;     ...
;                     if (st) { const f16x8 h = hv[m][bj]; yp[0] = (f32x4){(float)h[0], (float)h[1], (float)h[2], (float)h[3]}; yp[1] = (f32x4){(float)h[4], (float)h[5], (float)h[6], (float)h[7]}; }
;                     else { yp[0] = *(const f32x4*)(x0 + off + bj * 32); yp[1] = *(const f32x4*)(x0 + off + bj * 32 + 4); }
;                     f32x4 y[2];
; #pragma unroll
;                     for (int n = 0; n < 2; ++n) { const f32x4 x = (yp[n] - rmu[m]) * ra[m] * gv[bj][n] + bv[bj][n];
;                         y[n] = x * alpha + acc[ai][bj][m][n] * s;
;                         s1 += (y[n][0] + y[n][1]) + (y[n][2] + y[n][3]); s2 += (y[n][0] * y[n][0] + y[n][1] * y[n][1]) + (y[n][2] * y[n][2] + y[n][3] * y[n][3]); }
;                     u32x4 w; w.x = cvtpk_h(y[0][0], y[0][1]); w.y = cvtpk_h(y[0][2], y[0][3]); w.z = cvtpk_h(y[1][0], y[1][1]); w.w = cvtpk_h(y[1][2], y[1][3]);
;                     *(u32x4*)(yh + off + bj * 32) = w;
;                 }
;                 s1 += __shfl_xor(s1, 16); s1 += __shfl_xor(s1, 32); s2 += __shfl_xor(s2, 16); s2 += __shfl_xor(s2, 32);
;                 if (fq == 0) { atomicAdd(st_new + 2 * (size_t)row, s1); atomicAdd(st_new + 2 * (size_t)row + 1, s2); }
.LBB0_1161:
	v_add_f32_e32 v233, v204, v205
	v_add_f32_e32 v236, v202, v203
	v_mul_f32_e32 v205, v205, v205
	v_mul_f32_e32 v203, v203, v203
	v_fmac_f32_e32 v205, v204, v204
	v_fmac_f32_e32 v203, v202, v202
	v_add_f32_e32 v202, v205, v203
	v_add_f32_e32 v203, v248, v249
	v_add_f32_e32 v204, v200, v201
	v_add_f32_e32 v203, v203, v204
	v_mul_f32_e32 v204, v249, v249
	v_mul_f32_e32 v201, v201, v201
	v_fmac_f32_e32 v204, v248, v248
	v_fmac_f32_e32 v201, v200, v200
	v_add_f32_e32 v200, v204, v201
	v_mov_b32_e32 v246, v242
	v_mov_b32_e32 v247, v242
	v_add_f32_e32 v202, v202, v200
	s_nop 0
	v_sub_f32_e32 v197, v197, v178
	v_sub_f32_e32 v196, v196, v178
	v_sub_f32_e32 v195, v195, v178
	v_sub_f32_e32 v194, v194, v178
	v_mov_b32_e32 v200, v242
	v_mov_b32_e32 v201, v242
	v_pk_mul_f32 v[194:195], v[246:247], v[194:195]
	v_pk_mul_f32 v[196:197], v[200:201], v[196:197]
	s_nop 0
	v_sub_f32_e32 v193, v193, v178
	v_sub_f32_e32 v192, v192, v178
	v_sub_f32_e32 v191, v191, v178
	v_sub_f32_e32 v190, v190, v178
	v_pk_fma_f32 v[196:197], v[56:57], v[196:197], v[60:61]
	v_pk_fma_f32 v[194:195], v[54:55], v[194:195], v[58:59]
	v_pk_mul_f32 v[190:191], v[246:247], v[190:191]
	v_pk_mul_f32 v[192:193], v[200:201], v[192:193]
	v_pk_mul_f32 v[194:195], v[194:195], s[66:67] op_sel_hi:[1,0]
	v_pk_mul_f32 v[196:197], v[196:197], s[66:67] op_sel_hi:[1,0]
	v_pk_fma_f32 v[192:193], v[44:45], v[192:193], v[48:49]
	v_pk_fma_f32 v[190:191], v[42:43], v[190:191], v[46:47]
	v_pk_fma_f32 v[188:189], v[188:189], 0.5, v[196:197] op_sel_hi:[1,0,1]
	v_pk_fma_f32 v[186:187], v[186:187], 0.5, v[194:195] op_sel_hi:[1,0,1]
	v_pk_mul_f32 v[190:191], v[190:191], s[66:67] op_sel_hi:[1,0]
	v_pk_mul_f32 v[192:193], v[192:193], s[66:67] op_sel_hi:[1,0]
	v_add_f32_e32 v194, v186, v187
	v_add_f32_e32 v195, v188, v189
	v_pk_fma_f32 v[192:193], v[184:185], 0.5, v[192:193] op_sel_hi:[1,0,1]
	v_pk_fma_f32 v[190:191], v[182:183], 0.5, v[190:191] op_sel_hi:[1,0,1]
	v_add_f32_e32 v233, v233, v236
	v_add_f32_e32 v194, v194, v195
	v_mul_f32_e32 v195, v187, v187
	v_mul_f32_e32 v196, v189, v189
	v_add_f32_e32 v178, v190, v191
	v_add_f32_e32 v182, v192, v193
	v_add_f32_e32 v233, 0, v233
	v_fmac_f32_e32 v195, v186, v186
	v_fmac_f32_e32 v196, v188, v188
	v_add_f32_e32 v178, v178, v182
	v_mul_f32_e32 v182, v191, v191
	v_mul_f32_e32 v183, v193, v193
	v_add_f32_e32 v203, v203, v233
	v_add_f32_e32 v195, v195, v196
	v_fmac_f32_e32 v182, v190, v190
	v_fmac_f32_e32 v183, v192, v192
	v_add_f32_e32 v194, v203, v194
	v_add_f32_e32 v195, v202, v195
	v_add_f32_e32 v182, v182, v183
	v_add_f32_e32 v178, v178, v194
	v_add_f32_e32 v184, v182, v195
	ds_bpermute_b32 v183, v207, v178
	ds_bpermute_b32 v185, v207, v184
	v_cvt_pk_f16_f32 v186, v186, v187
	v_cvt_pk_f16_f32 v187, v188, v189
	v_cvt_pk_f16_f32 v188, v190, v191
	s_waitcnt lgkmcnt(1)
	v_add_f32_e32 v178, v178, v183
	s_waitcnt lgkmcnt(0)
	v_add_f32_e32 v183, v184, v185
	ds_bpermute_b32 v182, v208, v178
	ds_bpermute_b32 v184, v208, v183
	v_cvt_pk_f16_f32 v189, v192, v193
	global_store_dwordx4 v[198:199], v[186:189], off offset:64
	s_and_saveexec_b64 s[36:37], s[40:41]
	s_cbranch_execz .LBB0_1163
	v_lshl_add_u64 v[186:187], v[228:229], 3, s[80:81]
	s_waitcnt lgkmcnt(1)
	v_add_f32_e32 v178, v178, v182
	s_waitcnt lgkmcnt(0)
	v_add_f32_e32 v182, v183, v184
	global_atomic_add_f32 v[186:187], v178, off
	global_atomic_add_f32 v[186:187], v182, off offset:4

;     __device__ __forceinline__ void operator()(const f32x4 (&acc)[2][2][4][2], const Unit& u, int wr, int wc, int fr, int fq) const {
;     ...
;                 if (st) {
;                     const f32x2v sv = *(const f32x2v*)(st + 2 * (size_t)row); rmu[m] = sv.x * (1.0f / 1024.0f); ra[m] = rsqrtf(sv.y * (1.0f / 1024.0f) - rmu[m] * rmu[m] + 1e-5f);
;                     hv[m][0] = *(const f16x8*)(yh + off); hv[m][1] = *(const f16x8*)(yh + off + 32);
.LBB0_1202:
	v_lshl_add_u64 v[98:99], v[116:117], 3, s[86:87]
	s_waitcnt lgkmcnt(1)
	global_load_dwordx2 v[110:111], v[98:99], off
	v_lshlrev_b64 v[98:99], 11, v[116:117]
	v_lshl_add_u64 v[98:99], v[226:227], 0, v[98:99]
	global_load_dwordx4 v[102:105], v[98:99], off
	s_nop 0
	global_load_dwordx4 v[98:101], v[98:99], off offset:64
	s_waitcnt vmcnt(0)
	v_pk_mul_f32 v[110:111], v[110:111], s[64:65] op_sel_hi:[1,0]
	s_nop 0
	v_fma_f32 v111, -v110, v110, v111
	v_add_f32_e32 v111, 0x3727c5ac, v111
	v_mul_f32_e32 v112, 0x4b800000, v111
	v_cmp_gt_f32_e32 vcc, s29, v111
	s_nop 1
	v_cndmask_b32_e32 v111, v111, v112, vcc
	v_rsq_f32_e32 v111, v111
	s_nop 0
	v_mul_f32_e32 v112, 0x45800000, v111
	v_cndmask_b32_e32 v127, v111, v112, vcc
